# kpair A-major boustrophedon with k order of every second pair swapped (fp32 accumulation order of those accumulators changes within a K-tile)
# baseline (speedup 1.0000x reference)
.LBB0_642:
	ds_read_b128 v[148:151], v139
	ds_read_b128 v[152:155], v139 offset:1024
	ds_read_b128 v[156:159], v139 offset:2048
	ds_read_b128 v[160:163], v139 offset:3072
	ds_read_b128 v[164:167], v140
	ds_read_b128 v[168:171], v140 offset:1024
	ds_read_b128 v[172:175], v140 offset:2048
	ds_read_b128 v[176:179], v140 offset:3072
	s_add_i32 s18, s71, 0xffe80080
	s_cmp_eq_u32 s58, s73
	s_cselect_b32 s74, s69, s18
	s_cselect_b32 s76, s70, s72
	s_or_b32 s75, s74, 0x80
	s_add_i32 s18, s71, 0xfff80000
	s_mov_b32 m0, s59
	ds_read_b128 v[180:183], v141
	ds_read_b128 v[184:187], v141 offset:1024
	ds_read_b128 v[188:191], v141 offset:2048
	ds_read_b128 v[192:195], v141 offset:3072
	ds_read_b128 v[196:199], v141 offset:4096
	ds_read_b128 v[200:203], v141 offset:5120
	ds_read_b128 v[204:207], v141 offset:6144
	ds_read_b128 v[208:211], v141 offset:7168
	buffer_load_dwordx4 v137, s[12:15], s18 offen lds
	s_mov_b32 m0, s60
	s_nop 0
	buffer_load_dwordx4 v137, s[12:15], s71 offen lds
	s_waitcnt vmcnt(8)
	s_waitcnt lgkmcnt(0)
	s_setprio 1
	v_mfma_f32_16x16x32_bf16 v[118:121], v[148:151], v[180:183], v[118:121]
	s_barrier
	v_mfma_f32_16x16x32_bf16 v[118:121], v[152:155], v[184:187], v[118:121]
	v_mfma_f32_16x16x32_bf16 v[114:117], v[160:163], v[184:187], v[114:117]
	v_mfma_f32_16x16x32_bf16 v[114:117], v[156:159], v[180:183], v[114:117]
	v_mfma_f32_16x16x32_bf16 v[126:129], v[164:167], v[180:183], v[126:129]
	v_mfma_f32_16x16x32_bf16 v[126:129], v[168:171], v[184:187], v[126:129]
	v_mfma_f32_16x16x32_bf16 v[122:125], v[176:179], v[184:187], v[122:125]
	v_mfma_f32_16x16x32_bf16 v[122:125], v[172:175], v[180:183], v[122:125]
	v_mfma_f32_16x16x32_bf16 v[98:101], v[172:175], v[188:191], v[98:101]
	v_mfma_f32_16x16x32_bf16 v[98:101], v[176:179], v[192:195], v[98:101]
	v_mfma_f32_16x16x32_bf16 v[106:109], v[168:171], v[192:195], v[106:109]
	v_mfma_f32_16x16x32_bf16 v[106:109], v[164:167], v[188:191], v[106:109]
	v_mfma_f32_16x16x32_bf16 v[102:105], v[156:159], v[188:191], v[102:105]
	v_mfma_f32_16x16x32_bf16 v[102:105], v[160:163], v[192:195], v[102:105]
	v_mfma_f32_16x16x32_bf16 v[110:113], v[152:155], v[192:195], v[110:113]
	v_mfma_f32_16x16x32_bf16 v[110:113], v[148:151], v[188:191], v[110:113]
	v_mfma_f32_16x16x32_bf16 v[94:97], v[148:151], v[196:199], v[94:97]
	v_mfma_f32_16x16x32_bf16 v[94:97], v[152:155], v[200:203], v[94:97]
	v_mfma_f32_16x16x32_bf16 v[86:89], v[160:163], v[200:203], v[86:89]
	v_mfma_f32_16x16x32_bf16 v[86:89], v[156:159], v[196:199], v[86:89]
	v_mfma_f32_16x16x32_bf16 v[90:93], v[164:167], v[196:199], v[90:93]
	v_mfma_f32_16x16x32_bf16 v[90:93], v[168:171], v[200:203], v[90:93]
	v_mfma_f32_16x16x32_bf16 v[82:85], v[176:179], v[200:203], v[82:85]
	v_mfma_f32_16x16x32_bf16 v[82:85], v[172:175], v[196:199], v[82:85]
	v_mfma_f32_16x16x32_bf16 v[70:73], v[172:175], v[204:207], v[70:73]
	v_mfma_f32_16x16x32_bf16 v[70:73], v[176:179], v[208:211], v[70:73]
	v_mfma_f32_16x16x32_bf16 v[74:77], v[168:171], v[208:211], v[74:77]
	v_mfma_f32_16x16x32_bf16 v[74:77], v[164:167], v[204:207], v[74:77]
	v_mfma_f32_16x16x32_bf16 v[66:69], v[156:159], v[204:207], v[66:69]
	v_mfma_f32_16x16x32_bf16 v[66:69], v[160:163], v[208:211], v[66:69]
	v_mfma_f32_16x16x32_bf16 v[78:81], v[152:155], v[208:211], v[78:81]
	v_mfma_f32_16x16x32_bf16 v[78:81], v[148:151], v[204:207], v[78:81]
	s_setprio 0
	s_barrier
	s_mov_b32 m0, s30
	s_mov_b32 s18, s14
	s_mov_b32 s19, s15
	ds_read_b128 v[180:183], v141 offset:16384
	ds_read_b128 v[184:187], v141 offset:17408
	ds_read_b128 v[188:191], v141 offset:18432
	ds_read_b128 v[192:195], v141 offset:19456
	ds_read_b128 v[196:199], v141 offset:20480
	ds_read_b128 v[200:203], v141 offset:21504
	ds_read_b128 v[204:207], v141 offset:22528
	ds_read_b128 v[208:211], v141 offset:23552
	buffer_load_dwordx4 v138, s[16:19], s76 offen lds
	s_add_i32 s77, s76, 0x80000
	s_mov_b32 m0, s31
	s_nop 0
	buffer_load_dwordx4 v138, s[16:19], s77 offen lds
	s_add_i32 s77, s76, 0x100000
	s_mov_b32 m0, s44
	s_nop 0
	buffer_load_dwordx4 v138, s[16:19], s77 offen lds
	s_add_i32 s77, s76, 0x180000
	s_mov_b32 m0, s45
	s_nop 0
	buffer_load_dwordx4 v138, s[16:19], s77 offen lds
	s_mov_b32 m0, s27
	s_add_i32 s77, s74, 0x80000
	buffer_load_dwordx4 v137, s[12:15], s74 offen lds
	s_mov_b32 m0, s46
	s_nop 0
	buffer_load_dwordx4 v137, s[12:15], s77 offen lds
	s_waitcnt vmcnt(8)
	s_waitcnt lgkmcnt(0)
	s_setprio 1
	v_mfma_f32_16x16x32_bf16 v[62:65], v[148:151], v[180:183], v[62:65]
	s_barrier
	v_mfma_f32_16x16x32_bf16 v[62:65], v[152:155], v[184:187], v[62:65]
	v_mfma_f32_16x16x32_bf16 v[54:57], v[160:163], v[184:187], v[54:57]
	v_mfma_f32_16x16x32_bf16 v[54:57], v[156:159], v[180:183], v[54:57]
	v_mfma_f32_16x16x32_bf16 v[58:61], v[164:167], v[180:183], v[58:61]
	v_mfma_f32_16x16x32_bf16 v[58:61], v[168:171], v[184:187], v[58:61]
	v_mfma_f32_16x16x32_bf16 v[50:53], v[176:179], v[184:187], v[50:53]
	v_mfma_f32_16x16x32_bf16 v[50:53], v[172:175], v[180:183], v[50:53]
	v_mfma_f32_16x16x32_bf16 v[34:37], v[172:175], v[188:191], v[34:37]
	v_mfma_f32_16x16x32_bf16 v[34:37], v[176:179], v[192:195], v[34:37]
	v_mfma_f32_16x16x32_bf16 v[42:45], v[168:171], v[192:195], v[42:45]
	v_mfma_f32_16x16x32_bf16 v[42:45], v[164:167], v[188:191], v[42:45]
	v_mfma_f32_16x16x32_bf16 v[38:41], v[156:159], v[188:191], v[38:41]
	v_mfma_f32_16x16x32_bf16 v[38:41], v[160:163], v[192:195], v[38:41]
	v_mfma_f32_16x16x32_bf16 v[46:49], v[152:155], v[192:195], v[46:49]
	v_mfma_f32_16x16x32_bf16 v[46:49], v[148:151], v[188:191], v[46:49]
	v_mfma_f32_16x16x32_bf16 v[30:33], v[148:151], v[196:199], v[30:33]
	v_mfma_f32_16x16x32_bf16 v[30:33], v[152:155], v[200:203], v[30:33]
	v_mfma_f32_16x16x32_bf16 v[22:25], v[160:163], v[200:203], v[22:25]
	v_mfma_f32_16x16x32_bf16 v[22:25], v[156:159], v[196:199], v[22:25]
	v_mfma_f32_16x16x32_bf16 v[26:29], v[164:167], v[196:199], v[26:29]
	v_mfma_f32_16x16x32_bf16 v[26:29], v[168:171], v[200:203], v[26:29]
	v_mfma_f32_16x16x32_bf16 v[18:21], v[176:179], v[200:203], v[18:21]
	v_mfma_f32_16x16x32_bf16 v[18:21], v[172:175], v[196:199], v[18:21]
	v_mfma_f32_16x16x32_bf16 v[2:5], v[172:175], v[204:207], v[2:5]
	v_mfma_f32_16x16x32_bf16 v[2:5], v[176:179], v[208:211], v[2:5]
	v_mfma_f32_16x16x32_bf16 v[10:13], v[168:171], v[208:211], v[10:13]
	v_mfma_f32_16x16x32_bf16 v[10:13], v[164:167], v[204:207], v[10:13]
	v_mfma_f32_16x16x32_bf16 v[6:9], v[156:159], v[204:207], v[6:9]
	v_mfma_f32_16x16x32_bf16 v[6:9], v[160:163], v[208:211], v[6:9]
	v_mfma_f32_16x16x32_bf16 v[14:17], v[152:155], v[208:211], v[14:17]
	v_mfma_f32_16x16x32_bf16 v[14:17], v[148:151], v[204:207], v[14:17]
	s_setprio 0
	s_barrier
	ds_read_b128 v[148:151], v142
	ds_read_b128 v[152:155], v142 offset:1024
	ds_read_b128 v[156:159], v142 offset:2048
	ds_read_b128 v[160:163], v142 offset:3072
	ds_read_b128 v[164:167], v143
	ds_read_b128 v[168:171], v143 offset:1024
	ds_read_b128 v[172:175], v143 offset:2048
	ds_read_b128 v[176:179], v143 offset:3072
	s_mov_b32 m0, s47
	s_add_i32 s77, s74, 0x100000
	ds_read_b128 v[180:183], v141 offset:32768
	ds_read_b128 v[184:187], v141 offset:33792
	ds_read_b128 v[188:191], v141 offset:34816
	ds_read_b128 v[192:195], v141 offset:35840
	ds_read_b128 v[196:199], v141 offset:36864
	ds_read_b128 v[200:203], v141 offset:37888
	ds_read_b128 v[204:207], v141 offset:38912
	ds_read_b128 v[208:211], v141 offset:39936
	buffer_load_dwordx4 v137, s[12:15], s77 offen lds
	s_add_i32 s77, s74, 0x180000
	s_mov_b32 m0, s48
	s_nop 0
	buffer_load_dwordx4 v137, s[12:15], s77 offen lds
	s_waitcnt vmcnt(8)
	s_waitcnt lgkmcnt(0)
	s_setprio 1
	v_mfma_f32_16x16x32_bf16 v[118:121], v[148:151], v[180:183], v[118:121]
	s_barrier
	v_mfma_f32_16x16x32_bf16 v[118:121], v[152:155], v[184:187], v[118:121]
	v_mfma_f32_16x16x32_bf16 v[114:117], v[160:163], v[184:187], v[114:117]
	v_mfma_f32_16x16x32_bf16 v[114:117], v[156:159], v[180:183], v[114:117]
	v_mfma_f32_16x16x32_bf16 v[126:129], v[164:167], v[180:183], v[126:129]
	v_mfma_f32_16x16x32_bf16 v[126:129], v[168:171], v[184:187], v[126:129]
	v_mfma_f32_16x16x32_bf16 v[122:125], v[176:179], v[184:187], v[122:125]
	v_mfma_f32_16x16x32_bf16 v[122:125], v[172:175], v[180:183], v[122:125]
	v_mfma_f32_16x16x32_bf16 v[98:101], v[172:175], v[188:191], v[98:101]
	v_mfma_f32_16x16x32_bf16 v[98:101], v[176:179], v[192:195], v[98:101]
	v_mfma_f32_16x16x32_bf16 v[106:109], v[168:171], v[192:195], v[106:109]
	v_mfma_f32_16x16x32_bf16 v[106:109], v[164:167], v[188:191], v[106:109]
	v_mfma_f32_16x16x32_bf16 v[102:105], v[156:159], v[188:191], v[102:105]
	v_mfma_f32_16x16x32_bf16 v[102:105], v[160:163], v[192:195], v[102:105]
	v_mfma_f32_16x16x32_bf16 v[110:113], v[152:155], v[192:195], v[110:113]
	v_mfma_f32_16x16x32_bf16 v[110:113], v[148:151], v[188:191], v[110:113]
	v_mfma_f32_16x16x32_bf16 v[94:97], v[148:151], v[196:199], v[94:97]
	v_mfma_f32_16x16x32_bf16 v[94:97], v[152:155], v[200:203], v[94:97]
	v_mfma_f32_16x16x32_bf16 v[86:89], v[160:163], v[200:203], v[86:89]
	v_mfma_f32_16x16x32_bf16 v[86:89], v[156:159], v[196:199], v[86:89]
	v_mfma_f32_16x16x32_bf16 v[90:93], v[164:167], v[196:199], v[90:93]
	v_mfma_f32_16x16x32_bf16 v[90:93], v[168:171], v[200:203], v[90:93]
	v_mfma_f32_16x16x32_bf16 v[82:85], v[176:179], v[200:203], v[82:85]
	v_mfma_f32_16x16x32_bf16 v[82:85], v[172:175], v[196:199], v[82:85]
	v_mfma_f32_16x16x32_bf16 v[70:73], v[172:175], v[204:207], v[70:73]
	v_mfma_f32_16x16x32_bf16 v[70:73], v[176:179], v[208:211], v[70:73]
	v_mfma_f32_16x16x32_bf16 v[74:77], v[168:171], v[208:211], v[74:77]
	v_mfma_f32_16x16x32_bf16 v[74:77], v[164:167], v[204:207], v[74:77]
	v_mfma_f32_16x16x32_bf16 v[66:69], v[156:159], v[204:207], v[66:69]
	v_mfma_f32_16x16x32_bf16 v[66:69], v[160:163], v[208:211], v[66:69]
	v_mfma_f32_16x16x32_bf16 v[78:81], v[152:155], v[208:211], v[78:81]
	v_mfma_f32_16x16x32_bf16 v[78:81], v[148:151], v[204:207], v[78:81]
	s_setprio 0
	s_barrier
	s_mov_b32 m0, s50
	s_or_b32 s77, s76, 0x80
	ds_read_b128 v[180:183], v141 offset:49152
	ds_read_b128 v[184:187], v141 offset:50176
	ds_read_b128 v[188:191], v141 offset:51200
	ds_read_b128 v[192:195], v141 offset:52224
	ds_read_b128 v[196:199], v141 offset:53248
	ds_read_b128 v[200:203], v141 offset:54272
	ds_read_b128 v[204:207], v141 offset:55296
	ds_read_b128 v[208:211], v141 offset:56320
	buffer_load_dwordx4 v138, s[16:19], s77 offen lds
	s_add_i32 s77, s76, 0x80080
	s_mov_b32 m0, s51
	s_add_i32 s74, s74, 0x80080
	buffer_load_dwordx4 v138, s[16:19], s77 offen lds
	s_add_i32 s77, s76, 0x100080
	s_mov_b32 m0, s54
	s_add_i32 s76, s76, 0x180080
	buffer_load_dwordx4 v138, s[16:19], s77 offen lds
	s_mov_b32 m0, s55
	s_nop 0
	buffer_load_dwordx4 v138, s[16:19], s76 offen lds
	s_mov_b32 m0, s52
	s_nop 0
	buffer_load_dwordx4 v137, s[12:15], s75 offen lds
	s_mov_b32 m0, s53
	s_nop 0
	buffer_load_dwordx4 v137, s[12:15], s74 offen lds
	s_waitcnt vmcnt(8)
	s_waitcnt lgkmcnt(0)
	s_setprio 1
	v_mfma_f32_16x16x32_bf16 v[62:65], v[148:151], v[180:183], v[62:65]
	s_barrier
	v_mfma_f32_16x16x32_bf16 v[62:65], v[152:155], v[184:187], v[62:65]
	v_mfma_f32_16x16x32_bf16 v[54:57], v[160:163], v[184:187], v[54:57]
	v_mfma_f32_16x16x32_bf16 v[54:57], v[156:159], v[180:183], v[54:57]
	v_mfma_f32_16x16x32_bf16 v[58:61], v[164:167], v[180:183], v[58:61]
	v_mfma_f32_16x16x32_bf16 v[58:61], v[168:171], v[184:187], v[58:61]
	v_mfma_f32_16x16x32_bf16 v[50:53], v[176:179], v[184:187], v[50:53]
	v_mfma_f32_16x16x32_bf16 v[50:53], v[172:175], v[180:183], v[50:53]
	v_mfma_f32_16x16x32_bf16 v[34:37], v[172:175], v[188:191], v[34:37]
	v_mfma_f32_16x16x32_bf16 v[34:37], v[176:179], v[192:195], v[34:37]
	v_mfma_f32_16x16x32_bf16 v[42:45], v[168:171], v[192:195], v[42:45]
	v_mfma_f32_16x16x32_bf16 v[42:45], v[164:167], v[188:191], v[42:45]
	v_mfma_f32_16x16x32_bf16 v[38:41], v[156:159], v[188:191], v[38:41]
	v_mfma_f32_16x16x32_bf16 v[38:41], v[160:163], v[192:195], v[38:41]
	v_mfma_f32_16x16x32_bf16 v[46:49], v[152:155], v[192:195], v[46:49]
	v_mfma_f32_16x16x32_bf16 v[46:49], v[148:151], v[188:191], v[46:49]
	v_mfma_f32_16x16x32_bf16 v[30:33], v[148:151], v[196:199], v[30:33]
	v_mfma_f32_16x16x32_bf16 v[30:33], v[152:155], v[200:203], v[30:33]
	v_mfma_f32_16x16x32_bf16 v[22:25], v[160:163], v[200:203], v[22:25]
	v_mfma_f32_16x16x32_bf16 v[22:25], v[156:159], v[196:199], v[22:25]
	v_mfma_f32_16x16x32_bf16 v[26:29], v[164:167], v[196:199], v[26:29]
	v_mfma_f32_16x16x32_bf16 v[26:29], v[168:171], v[200:203], v[26:29]
	v_mfma_f32_16x16x32_bf16 v[18:21], v[176:179], v[200:203], v[18:21]
	v_mfma_f32_16x16x32_bf16 v[18:21], v[172:175], v[196:199], v[18:21]
	v_mfma_f32_16x16x32_bf16 v[2:5], v[172:175], v[204:207], v[2:5]
	v_mfma_f32_16x16x32_bf16 v[2:5], v[176:179], v[208:211], v[2:5]
	v_mfma_f32_16x16x32_bf16 v[10:13], v[168:171], v[208:211], v[10:13]
	v_mfma_f32_16x16x32_bf16 v[10:13], v[164:167], v[204:207], v[10:13]
	v_mfma_f32_16x16x32_bf16 v[6:9], v[156:159], v[204:207], v[6:9]
	v_mfma_f32_16x16x32_bf16 v[6:9], v[160:163], v[208:211], v[6:9]
	v_mfma_f32_16x16x32_bf16 v[14:17], v[152:155], v[208:211], v[14:17]
	v_mfma_f32_16x16x32_bf16 v[14:17], v[148:151], v[204:207], v[14:17]
	s_setprio 0
	s_barrier
	s_add_i32 s73, s73, 2
	s_addk_i32 s71, 0x100
	s_addk_i32 s72, 0x100
	s_cmp_ge_i32 s73, s3
	s_cbranch_scc0 .LBB0_642
	s_and_b64 vcc, exec, s[42:43]
	s_cbranch_vccz .LBB0_645

.LBB0_799:
	ds_read_b128 v[134:137], v210
	ds_read_b128 v[138:141], v210 offset:1024
	ds_read_b128 v[142:145], v210 offset:2048
	ds_read_b128 v[148:151], v210 offset:3072
	ds_read_b128 v[152:155], v211
	ds_read_b128 v[156:159], v211 offset:1024
	ds_read_b128 v[160:163], v211 offset:2048
	ds_read_b128 v[164:167], v211 offset:3072
	s_add_i32 s18, s77, 0xffbf8080
	s_cmp_eq_u32 s62, s79
	s_cselect_b32 s80, s6, s18
	s_cselect_b32 s82, s7, s78
	s_or_b32 s81, s80, 0x80
	s_add_i32 s18, s77, 0xffea8000
	s_mov_b32 m0, s63
	ds_read_b128 v[168:171], v212
	ds_read_b128 v[172:175], v212 offset:1024
	ds_read_b128 v[176:179], v212 offset:2048
	ds_read_b128 v[180:183], v212 offset:3072
	ds_read_b128 v[184:187], v212 offset:4096
	ds_read_b128 v[188:191], v212 offset:5120
	ds_read_b128 v[192:195], v212 offset:6144
	ds_read_b128 v[196:199], v212 offset:7168
	buffer_load_dwordx4 v208, s[12:15], s18 offen lds
	s_mov_b32 m0, s66
	s_nop 0
	buffer_load_dwordx4 v208, s[12:15], s77 offen lds
	s_waitcnt vmcnt(8)
	s_waitcnt lgkmcnt(0)
	s_setprio 1
	v_mfma_f32_16x16x32_bf16 v[126:129], v[134:137], v[168:171], v[126:129]
	s_barrier
	v_mfma_f32_16x16x32_bf16 v[126:129], v[138:141], v[172:175], v[126:129]
	v_mfma_f32_16x16x32_bf16 v[122:125], v[148:151], v[172:175], v[122:125]
	v_mfma_f32_16x16x32_bf16 v[122:125], v[142:145], v[168:171], v[122:125]
	v_mfma_f32_16x16x32_bf16 v[110:113], v[152:155], v[168:171], v[110:113]
	v_mfma_f32_16x16x32_bf16 v[110:113], v[156:159], v[172:175], v[110:113]
	v_mfma_f32_16x16x32_bf16 v[102:105], v[164:167], v[172:175], v[102:105]
	v_mfma_f32_16x16x32_bf16 v[102:105], v[160:163], v[168:171], v[102:105]
	v_mfma_f32_16x16x32_bf16 v[86:89], v[160:163], v[176:179], v[86:89]
	v_mfma_f32_16x16x32_bf16 v[86:89], v[164:167], v[180:183], v[86:89]
	v_mfma_f32_16x16x32_bf16 v[94:97], v[156:159], v[180:183], v[94:97]
	v_mfma_f32_16x16x32_bf16 v[94:97], v[152:155], v[176:179], v[94:97]
	v_mfma_f32_16x16x32_bf16 v[114:117], v[142:145], v[176:179], v[114:117]
	v_mfma_f32_16x16x32_bf16 v[114:117], v[148:151], v[180:183], v[114:117]
	v_mfma_f32_16x16x32_bf16 v[118:121], v[138:141], v[180:183], v[118:121]
	v_mfma_f32_16x16x32_bf16 v[118:121], v[134:137], v[176:179], v[118:121]
	v_mfma_f32_16x16x32_bf16 v[106:109], v[134:137], v[184:187], v[106:109]
	v_mfma_f32_16x16x32_bf16 v[106:109], v[138:141], v[188:191], v[106:109]
	v_mfma_f32_16x16x32_bf16 v[98:101], v[148:151], v[188:191], v[98:101]
	v_mfma_f32_16x16x32_bf16 v[98:101], v[142:145], v[184:187], v[98:101]
	v_mfma_f32_16x16x32_bf16 v[78:81], v[152:155], v[184:187], v[78:81]
	v_mfma_f32_16x16x32_bf16 v[78:81], v[156:159], v[188:191], v[78:81]
	v_mfma_f32_16x16x32_bf16 v[74:77], v[164:167], v[188:191], v[74:77]
	v_mfma_f32_16x16x32_bf16 v[74:77], v[160:163], v[184:187], v[74:77]
	v_mfma_f32_16x16x32_bf16 v[66:69], v[160:163], v[192:195], v[66:69]
	v_mfma_f32_16x16x32_bf16 v[66:69], v[164:167], v[196:199], v[66:69]
	v_mfma_f32_16x16x32_bf16 v[70:73], v[156:159], v[196:199], v[70:73]
	v_mfma_f32_16x16x32_bf16 v[70:73], v[152:155], v[192:195], v[70:73]
	v_mfma_f32_16x16x32_bf16 v[82:85], v[142:145], v[192:195], v[82:85]
	v_mfma_f32_16x16x32_bf16 v[82:85], v[148:151], v[196:199], v[82:85]
	v_mfma_f32_16x16x32_bf16 v[90:93], v[138:141], v[196:199], v[90:93]
	v_mfma_f32_16x16x32_bf16 v[90:93], v[134:137], v[192:195], v[90:93]
	s_setprio 0
	s_barrier
	s_mov_b32 m0, s25
	s_mov_b32 s18, s14
	s_mov_b32 s19, s15
	ds_read_b128 v[168:171], v212 offset:16384
	ds_read_b128 v[172:175], v212 offset:17408
	ds_read_b128 v[176:179], v212 offset:18432
	ds_read_b128 v[180:183], v212 offset:19456
	ds_read_b128 v[184:187], v212 offset:20480
	ds_read_b128 v[188:191], v212 offset:21504
	ds_read_b128 v[192:195], v212 offset:22528
	ds_read_b128 v[196:199], v212 offset:23552
	buffer_load_dwordx4 v209, s[16:19], s82 offen lds
	s_add_i32 s83, s82, 0x158000
	s_mov_b32 m0, s27
	s_nop 0
	buffer_load_dwordx4 v209, s[16:19], s83 offen lds
	s_add_i32 s83, s82, 0x2b0000
	s_mov_b32 m0, s30
	s_nop 0
	buffer_load_dwordx4 v209, s[16:19], s83 offen lds
	s_add_i32 s83, s82, 0x408000
	s_mov_b32 m0, s31
	s_nop 0
	buffer_load_dwordx4 v209, s[16:19], s83 offen lds
	s_mov_b32 m0, s21
	s_add_i32 s83, s80, 0x158000
	buffer_load_dwordx4 v208, s[12:15], s80 offen lds
	s_mov_b32 m0, s48
	s_nop 0
	buffer_load_dwordx4 v208, s[12:15], s83 offen lds
	s_waitcnt vmcnt(8)
	s_waitcnt lgkmcnt(0)
	s_setprio 1
	v_mfma_f32_16x16x32_bf16 v[62:65], v[134:137], v[168:171], v[62:65]
	s_barrier
	v_mfma_f32_16x16x32_bf16 v[62:65], v[138:141], v[172:175], v[62:65]
	v_mfma_f32_16x16x32_bf16 v[58:61], v[148:151], v[172:175], v[58:61]
	v_mfma_f32_16x16x32_bf16 v[58:61], v[142:145], v[168:171], v[58:61]
	v_mfma_f32_16x16x32_bf16 v[46:49], v[152:155], v[168:171], v[46:49]
	v_mfma_f32_16x16x32_bf16 v[46:49], v[156:159], v[172:175], v[46:49]
	v_mfma_f32_16x16x32_bf16 v[38:41], v[164:167], v[172:175], v[38:41]
	v_mfma_f32_16x16x32_bf16 v[38:41], v[160:163], v[168:171], v[38:41]
	v_mfma_f32_16x16x32_bf16 v[22:25], v[160:163], v[176:179], v[22:25]
	v_mfma_f32_16x16x32_bf16 v[22:25], v[164:167], v[180:183], v[22:25]
	v_mfma_f32_16x16x32_bf16 v[30:33], v[156:159], v[180:183], v[30:33]
	v_mfma_f32_16x16x32_bf16 v[30:33], v[152:155], v[176:179], v[30:33]
	v_mfma_f32_16x16x32_bf16 v[50:53], v[142:145], v[176:179], v[50:53]
	v_mfma_f32_16x16x32_bf16 v[50:53], v[148:151], v[180:183], v[50:53]
	v_mfma_f32_16x16x32_bf16 v[54:57], v[138:141], v[180:183], v[54:57]
	v_mfma_f32_16x16x32_bf16 v[54:57], v[134:137], v[176:179], v[54:57]
	v_mfma_f32_16x16x32_bf16 v[42:45], v[134:137], v[184:187], v[42:45]
	v_mfma_f32_16x16x32_bf16 v[42:45], v[138:141], v[188:191], v[42:45]
	v_mfma_f32_16x16x32_bf16 v[34:37], v[148:151], v[188:191], v[34:37]
	v_mfma_f32_16x16x32_bf16 v[34:37], v[142:145], v[184:187], v[34:37]
	v_mfma_f32_16x16x32_bf16 v[14:17], v[152:155], v[184:187], v[14:17]
	v_mfma_f32_16x16x32_bf16 v[14:17], v[156:159], v[188:191], v[14:17]
	v_mfma_f32_16x16x32_bf16 v[10:13], v[164:167], v[188:191], v[10:13]
	v_mfma_f32_16x16x32_bf16 v[10:13], v[160:163], v[184:187], v[10:13]
	v_mfma_f32_16x16x32_bf16 v[2:5], v[160:163], v[192:195], v[2:5]
	v_mfma_f32_16x16x32_bf16 v[2:5], v[164:167], v[196:199], v[2:5]
	v_mfma_f32_16x16x32_bf16 v[6:9], v[156:159], v[196:199], v[6:9]
	v_mfma_f32_16x16x32_bf16 v[6:9], v[152:155], v[192:195], v[6:9]
	v_mfma_f32_16x16x32_bf16 v[18:21], v[142:145], v[192:195], v[18:21]
	v_mfma_f32_16x16x32_bf16 v[18:21], v[148:151], v[196:199], v[18:21]
	v_mfma_f32_16x16x32_bf16 v[26:29], v[138:141], v[196:199], v[26:29]
	v_mfma_f32_16x16x32_bf16 v[26:29], v[134:137], v[192:195], v[26:29]
	s_setprio 0
	s_barrier
	ds_read_b128 v[134:137], v213
	ds_read_b128 v[138:141], v213 offset:1024
	ds_read_b128 v[142:145], v213 offset:2048
	ds_read_b128 v[148:151], v213 offset:3072
	ds_read_b128 v[152:155], v214
	ds_read_b128 v[156:159], v214 offset:1024
	ds_read_b128 v[160:163], v214 offset:2048
	ds_read_b128 v[164:167], v214 offset:3072
	s_mov_b32 m0, s49
	s_add_i32 s83, s80, 0x2b0000
	ds_read_b128 v[168:171], v212 offset:32768
	ds_read_b128 v[172:175], v212 offset:33792
	ds_read_b128 v[176:179], v212 offset:34816
	ds_read_b128 v[180:183], v212 offset:35840
	ds_read_b128 v[184:187], v212 offset:36864
	ds_read_b128 v[188:191], v212 offset:37888
	ds_read_b128 v[192:195], v212 offset:38912
	ds_read_b128 v[196:199], v212 offset:39936
	buffer_load_dwordx4 v208, s[12:15], s83 offen lds
	s_add_i32 s83, s80, 0x408000
	s_mov_b32 m0, s50
	s_nop 0
	buffer_load_dwordx4 v208, s[12:15], s83 offen lds
	s_waitcnt vmcnt(8)
	s_waitcnt lgkmcnt(0)
	s_setprio 1
	v_mfma_f32_16x16x32_bf16 v[126:129], v[134:137], v[168:171], v[126:129]
	s_barrier
	v_mfma_f32_16x16x32_bf16 v[126:129], v[138:141], v[172:175], v[126:129]
	v_mfma_f32_16x16x32_bf16 v[122:125], v[148:151], v[172:175], v[122:125]
	v_mfma_f32_16x16x32_bf16 v[122:125], v[142:145], v[168:171], v[122:125]
	v_mfma_f32_16x16x32_bf16 v[110:113], v[152:155], v[168:171], v[110:113]
	v_mfma_f32_16x16x32_bf16 v[110:113], v[156:159], v[172:175], v[110:113]
	v_mfma_f32_16x16x32_bf16 v[102:105], v[164:167], v[172:175], v[102:105]
	v_mfma_f32_16x16x32_bf16 v[102:105], v[160:163], v[168:171], v[102:105]
	v_mfma_f32_16x16x32_bf16 v[86:89], v[160:163], v[176:179], v[86:89]
	v_mfma_f32_16x16x32_bf16 v[86:89], v[164:167], v[180:183], v[86:89]
	v_mfma_f32_16x16x32_bf16 v[94:97], v[156:159], v[180:183], v[94:97]
	v_mfma_f32_16x16x32_bf16 v[94:97], v[152:155], v[176:179], v[94:97]
	v_mfma_f32_16x16x32_bf16 v[114:117], v[142:145], v[176:179], v[114:117]
	v_mfma_f32_16x16x32_bf16 v[114:117], v[148:151], v[180:183], v[114:117]
	v_mfma_f32_16x16x32_bf16 v[118:121], v[138:141], v[180:183], v[118:121]
	v_mfma_f32_16x16x32_bf16 v[118:121], v[134:137], v[176:179], v[118:121]
	v_mfma_f32_16x16x32_bf16 v[106:109], v[134:137], v[184:187], v[106:109]
	v_mfma_f32_16x16x32_bf16 v[106:109], v[138:141], v[188:191], v[106:109]
	v_mfma_f32_16x16x32_bf16 v[98:101], v[148:151], v[188:191], v[98:101]
	v_mfma_f32_16x16x32_bf16 v[98:101], v[142:145], v[184:187], v[98:101]
	v_mfma_f32_16x16x32_bf16 v[78:81], v[152:155], v[184:187], v[78:81]
	v_mfma_f32_16x16x32_bf16 v[78:81], v[156:159], v[188:191], v[78:81]
	v_mfma_f32_16x16x32_bf16 v[74:77], v[164:167], v[188:191], v[74:77]
	v_mfma_f32_16x16x32_bf16 v[74:77], v[160:163], v[184:187], v[74:77]
	v_mfma_f32_16x16x32_bf16 v[66:69], v[160:163], v[192:195], v[66:69]
	v_mfma_f32_16x16x32_bf16 v[66:69], v[164:167], v[196:199], v[66:69]
	v_mfma_f32_16x16x32_bf16 v[70:73], v[156:159], v[196:199], v[70:73]
	v_mfma_f32_16x16x32_bf16 v[70:73], v[152:155], v[192:195], v[70:73]
	v_mfma_f32_16x16x32_bf16 v[82:85], v[142:145], v[192:195], v[82:85]
	v_mfma_f32_16x16x32_bf16 v[82:85], v[148:151], v[196:199], v[82:85]
	v_mfma_f32_16x16x32_bf16 v[90:93], v[138:141], v[196:199], v[90:93]
	v_mfma_f32_16x16x32_bf16 v[90:93], v[134:137], v[192:195], v[90:93]
	s_setprio 0
	s_barrier
	s_mov_b32 m0, s54
	s_or_b32 s83, s82, 0x80
	ds_read_b128 v[168:171], v212 offset:49152
	ds_read_b128 v[172:175], v212 offset:50176
	ds_read_b128 v[176:179], v212 offset:51200
	ds_read_b128 v[180:183], v212 offset:52224
	ds_read_b128 v[184:187], v212 offset:53248
	ds_read_b128 v[188:191], v212 offset:54272
	ds_read_b128 v[192:195], v212 offset:55296
	ds_read_b128 v[196:199], v212 offset:56320
	buffer_load_dwordx4 v209, s[16:19], s83 offen lds
	s_add_i32 s83, s82, 0x158080
	s_mov_b32 m0, s55
	s_add_i32 s80, s80, 0x158080
	buffer_load_dwordx4 v209, s[16:19], s83 offen lds
	s_add_i32 s83, s82, 0x2b0080
	s_mov_b32 m0, s58
	s_add_i32 s82, s82, 0x408080
	buffer_load_dwordx4 v209, s[16:19], s83 offen lds
	s_mov_b32 m0, s59
	s_nop 0
	buffer_load_dwordx4 v209, s[16:19], s82 offen lds
	s_mov_b32 m0, s56
	s_nop 0
	buffer_load_dwordx4 v208, s[12:15], s81 offen lds
	s_mov_b32 m0, s57
	s_nop 0
	buffer_load_dwordx4 v208, s[12:15], s80 offen lds
	s_waitcnt vmcnt(8)
	s_waitcnt lgkmcnt(0)
	s_setprio 1
	v_mfma_f32_16x16x32_bf16 v[62:65], v[134:137], v[168:171], v[62:65]
	s_barrier
	v_mfma_f32_16x16x32_bf16 v[62:65], v[138:141], v[172:175], v[62:65]
	v_mfma_f32_16x16x32_bf16 v[58:61], v[148:151], v[172:175], v[58:61]
	v_mfma_f32_16x16x32_bf16 v[58:61], v[142:145], v[168:171], v[58:61]
	v_mfma_f32_16x16x32_bf16 v[46:49], v[152:155], v[168:171], v[46:49]
	v_mfma_f32_16x16x32_bf16 v[46:49], v[156:159], v[172:175], v[46:49]
	v_mfma_f32_16x16x32_bf16 v[38:41], v[164:167], v[172:175], v[38:41]
	v_mfma_f32_16x16x32_bf16 v[38:41], v[160:163], v[168:171], v[38:41]
	v_mfma_f32_16x16x32_bf16 v[22:25], v[160:163], v[176:179], v[22:25]
	v_mfma_f32_16x16x32_bf16 v[22:25], v[164:167], v[180:183], v[22:25]
	v_mfma_f32_16x16x32_bf16 v[30:33], v[156:159], v[180:183], v[30:33]
	v_mfma_f32_16x16x32_bf16 v[30:33], v[152:155], v[176:179], v[30:33]
	v_mfma_f32_16x16x32_bf16 v[50:53], v[142:145], v[176:179], v[50:53]
	v_mfma_f32_16x16x32_bf16 v[50:53], v[148:151], v[180:183], v[50:53]
	v_mfma_f32_16x16x32_bf16 v[54:57], v[138:141], v[180:183], v[54:57]
	v_mfma_f32_16x16x32_bf16 v[54:57], v[134:137], v[176:179], v[54:57]
	v_mfma_f32_16x16x32_bf16 v[42:45], v[134:137], v[184:187], v[42:45]
	v_mfma_f32_16x16x32_bf16 v[42:45], v[138:141], v[188:191], v[42:45]
	v_mfma_f32_16x16x32_bf16 v[34:37], v[148:151], v[188:191], v[34:37]
	v_mfma_f32_16x16x32_bf16 v[34:37], v[142:145], v[184:187], v[34:37]
	v_mfma_f32_16x16x32_bf16 v[14:17], v[152:155], v[184:187], v[14:17]
	v_mfma_f32_16x16x32_bf16 v[14:17], v[156:159], v[188:191], v[14:17]
	v_mfma_f32_16x16x32_bf16 v[10:13], v[164:167], v[188:191], v[10:13]
	v_mfma_f32_16x16x32_bf16 v[10:13], v[160:163], v[184:187], v[10:13]
	v_mfma_f32_16x16x32_bf16 v[2:5], v[160:163], v[192:195], v[2:5]
	v_mfma_f32_16x16x32_bf16 v[2:5], v[164:167], v[196:199], v[2:5]
	v_mfma_f32_16x16x32_bf16 v[6:9], v[156:159], v[196:199], v[6:9]
	v_mfma_f32_16x16x32_bf16 v[6:9], v[152:155], v[192:195], v[6:9]
	v_mfma_f32_16x16x32_bf16 v[18:21], v[142:145], v[192:195], v[18:21]
	v_mfma_f32_16x16x32_bf16 v[18:21], v[148:151], v[196:199], v[18:21]
	v_mfma_f32_16x16x32_bf16 v[26:29], v[138:141], v[196:199], v[26:29]
	v_mfma_f32_16x16x32_bf16 v[26:29], v[134:137], v[192:195], v[26:29]
	s_setprio 0
	s_barrier
	s_add_i32 s79, s79, 2
	s_addk_i32 s77, 0x100
	s_addk_i32 s78, 0x100
	s_cmp_ge_i32 s79, s3
	s_cbranch_scc0 .LBB0_799
	v_pk_mul_f32 v[184:185], v[128:129], 0.5 op_sel_hi:[1,0]
	v_pk_mul_f32 v[186:187], v[126:127], 0.5 op_sel_hi:[1,0]
	v_pk_mul_f32 v[188:189], v[124:125], 0.5 op_sel_hi:[1,0]
	v_pk_mul_f32 v[190:191], v[122:123], 0.5 op_sel_hi:[1,0]
	v_pk_mul_f32 v[198:199], v[112:113], 0.5 op_sel_hi:[1,0]
	v_pk_mul_f32 v[196:197], v[110:111], 0.5 op_sel_hi:[1,0]
	v_pk_mul_f32 v[194:195], v[104:105], 0.5 op_sel_hi:[1,0]
	v_pk_mul_f32 v[192:193], v[102:103], 0.5 op_sel_hi:[1,0]
	v_pk_mul_f32 v[182:183], v[120:121], 0.5 op_sel_hi:[1,0]
	v_pk_mul_f32 v[180:181], v[118:119], 0.5 op_sel_hi:[1,0]
	v_pk_mul_f32 v[178:179], v[116:117], 0.5 op_sel_hi:[1,0]
	v_pk_mul_f32 v[176:177], v[114:115], 0.5 op_sel_hi:[1,0]
	v_pk_mul_f32 v[172:173], v[96:97], 0.5 op_sel_hi:[1,0]
	v_pk_mul_f32 v[170:171], v[94:95], 0.5 op_sel_hi:[1,0]
	v_pk_mul_f32 v[168:169], v[88:89], 0.5 op_sel_hi:[1,0]
	v_pk_mul_f32 v[166:167], v[86:87], 0.5 op_sel_hi:[1,0]
	v_pk_mul_f32 v[164:165], v[108:109], 0.5 op_sel_hi:[1,0]
	v_pk_mul_f32 v[162:163], v[106:107], 0.5 op_sel_hi:[1,0]
	v_pk_mul_f32 v[160:161], v[100:101], 0.5 op_sel_hi:[1,0]
	v_pk_mul_f32 v[158:159], v[98:99], 0.5 op_sel_hi:[1,0]
	v_pk_mul_f32 v[156:157], v[80:81], 0.5 op_sel_hi:[1,0]
	v_pk_mul_f32 v[154:155], v[78:79], 0.5 op_sel_hi:[1,0]
	v_pk_mul_f32 v[152:153], v[76:77], 0.5 op_sel_hi:[1,0]
	v_pk_mul_f32 v[150:151], v[74:75], 0.5 op_sel_hi:[1,0]
	v_pk_mul_f32 v[144:145], v[92:93], 0.5 op_sel_hi:[1,0]
	v_pk_mul_f32 v[142:143], v[90:91], 0.5 op_sel_hi:[1,0]
	v_pk_mul_f32 v[140:141], v[84:85], 0.5 op_sel_hi:[1,0]
	v_pk_mul_f32 v[138:139], v[82:83], 0.5 op_sel_hi:[1,0]
	v_pk_mul_f32 v[136:137], v[72:73], 0.5 op_sel_hi:[1,0]
	v_pk_mul_f32 v[134:135], v[70:71], 0.5 op_sel_hi:[1,0]
	v_pk_mul_f32 v[128:129], v[68:69], 0.5 op_sel_hi:[1,0]
	v_pk_mul_f32 v[126:127], v[66:67], 0.5 op_sel_hi:[1,0]
	v_pk_mul_f32 v[122:123], v[64:65], 0.5 op_sel_hi:[1,0]
	v_pk_mul_f32 v[120:121], v[62:63], 0.5 op_sel_hi:[1,0]
	v_pk_mul_f32 v[118:119], v[60:61], 0.5 op_sel_hi:[1,0]
	v_pk_mul_f32 v[116:117], v[58:59], 0.5 op_sel_hi:[1,0]
	v_pk_mul_f32 v[112:113], v[48:49], 0.5 op_sel_hi:[1,0]
	v_pk_mul_f32 v[110:111], v[46:47], 0.5 op_sel_hi:[1,0]
	v_pk_mul_f32 v[108:109], v[40:41], 0.5 op_sel_hi:[1,0]
	v_pk_mul_f32 v[106:107], v[38:39], 0.5 op_sel_hi:[1,0]
	v_pk_mul_f32 v[104:105], v[56:57], 0.5 op_sel_hi:[1,0]
	v_pk_mul_f32 v[102:103], v[54:55], 0.5 op_sel_hi:[1,0]
	v_pk_mul_f32 v[100:101], v[52:53], 0.5 op_sel_hi:[1,0]
	v_pk_mul_f32 v[98:99], v[50:51], 0.5 op_sel_hi:[1,0]
	v_pk_mul_f32 v[96:97], v[32:33], 0.5 op_sel_hi:[1,0]
	v_pk_mul_f32 v[94:95], v[30:31], 0.5 op_sel_hi:[1,0]
	v_pk_mul_f32 v[92:93], v[24:25], 0.5 op_sel_hi:[1,0]
	v_pk_mul_f32 v[90:91], v[22:23], 0.5 op_sel_hi:[1,0]
	v_pk_mul_f32 v[88:89], v[44:45], 0.5 op_sel_hi:[1,0]
	v_pk_mul_f32 v[86:87], v[42:43], 0.5 op_sel_hi:[1,0]
	v_pk_mul_f32 v[84:85], v[36:37], 0.5 op_sel_hi:[1,0]
	v_pk_mul_f32 v[82:83], v[34:35], 0.5 op_sel_hi:[1,0]
	v_pk_mul_f32 v[80:81], v[16:17], 0.5 op_sel_hi:[1,0]
	v_pk_mul_f32 v[78:79], v[14:15], 0.5 op_sel_hi:[1,0]
	v_pk_mul_f32 v[76:77], v[12:13], 0.5 op_sel_hi:[1,0]
	v_pk_mul_f32 v[74:75], v[10:11], 0.5 op_sel_hi:[1,0]
	v_pk_mul_f32 v[72:73], v[28:29], 0.5 op_sel_hi:[1,0]
	v_pk_mul_f32 v[70:71], v[26:27], 0.5 op_sel_hi:[1,0]
	v_pk_mul_f32 v[68:69], v[20:21], 0.5 op_sel_hi:[1,0]
	v_pk_mul_f32 v[66:67], v[18:19], 0.5 op_sel_hi:[1,0]
	v_pk_mul_f32 v[64:65], v[8:9], 0.5 op_sel_hi:[1,0]
	v_pk_mul_f32 v[62:63], v[6:7], 0.5 op_sel_hi:[1,0]
	v_pk_mul_f32 v[60:61], v[4:5], 0.5 op_sel_hi:[1,0]
	v_pk_mul_f32 v[58:59], v[2:3], 0.5 op_sel_hi:[1,0]
	s_and_b64 vcc, exec, s[38:39]
	s_cbranch_vccz .LBB0_802

.LBB0_892:
	ds_read_b128 v[130:133], v172
	ds_read_b128 v[134:137], v172 offset:1024
	ds_read_b128 v[148:151], v172 offset:2048
	ds_read_b128 v[152:155], v172 offset:3072
	ds_read_b128 v[156:159], v173
	ds_read_b128 v[160:163], v173 offset:1024
	ds_read_b128 v[164:167], v173 offset:2048
	ds_read_b128 v[180:183], v173 offset:3072
	s_add_i32 s18, s8, 0xffe80080
	s_cmp_eq_u32 s77, s52
	s_cselect_b32 s53, s6, s18
	s_cselect_b32 s58, s7, s9
	s_or_b32 s57, s53, 0x80
	s_add_i32 s18, s8, 0xfff80000
	s_mov_b32 m0, s78
	ds_read_b128 v[184:187], v174
	ds_read_b128 v[188:191], v174 offset:1024
	ds_read_b128 v[192:195], v174 offset:2048
	ds_read_b128 v[196:199], v174 offset:3072
	ds_read_b128 v[200:203], v174 offset:4096
	ds_read_b128 v[204:207], v174 offset:5120
	ds_read_b128 v[208:211], v174 offset:6144
	ds_read_b128 v[212:215], v174 offset:7168
	buffer_load_dwordx4 v170, s[12:15], s18 offen lds
	s_mov_b32 m0, s79
	s_nop 0
	buffer_load_dwordx4 v170, s[12:15], s8 offen lds
	s_waitcnt vmcnt(8)
	s_waitcnt lgkmcnt(0)
	s_setprio 1
	v_mfma_f32_16x16x32_bf16 v[126:129], v[130:133], v[184:187], v[126:129]
	s_barrier
	v_mfma_f32_16x16x32_bf16 v[126:129], v[134:137], v[188:191], v[126:129]
	v_mfma_f32_16x16x32_bf16 v[118:121], v[152:155], v[188:191], v[118:121]
	v_mfma_f32_16x16x32_bf16 v[118:121], v[148:151], v[184:187], v[118:121]
	v_mfma_f32_16x16x32_bf16 v[122:125], v[156:159], v[184:187], v[122:125]
	v_mfma_f32_16x16x32_bf16 v[122:125], v[160:163], v[188:191], v[122:125]
	v_mfma_f32_16x16x32_bf16 v[114:117], v[180:183], v[188:191], v[114:117]
	v_mfma_f32_16x16x32_bf16 v[114:117], v[164:167], v[184:187], v[114:117]
	v_mfma_f32_16x16x32_bf16 v[98:101], v[164:167], v[192:195], v[98:101]
	v_mfma_f32_16x16x32_bf16 v[98:101], v[180:183], v[196:199], v[98:101]
	v_mfma_f32_16x16x32_bf16 v[106:109], v[160:163], v[196:199], v[106:109]
	v_mfma_f32_16x16x32_bf16 v[106:109], v[156:159], v[192:195], v[106:109]
	v_mfma_f32_16x16x32_bf16 v[102:105], v[148:151], v[192:195], v[102:105]
	v_mfma_f32_16x16x32_bf16 v[102:105], v[152:155], v[196:199], v[102:105]
	v_mfma_f32_16x16x32_bf16 v[110:113], v[134:137], v[196:199], v[110:113]
	v_mfma_f32_16x16x32_bf16 v[110:113], v[130:133], v[192:195], v[110:113]
	v_mfma_f32_16x16x32_bf16 v[94:97], v[130:133], v[200:203], v[94:97]
	v_mfma_f32_16x16x32_bf16 v[94:97], v[134:137], v[204:207], v[94:97]
	v_mfma_f32_16x16x32_bf16 v[90:93], v[152:155], v[204:207], v[90:93]
	v_mfma_f32_16x16x32_bf16 v[90:93], v[148:151], v[200:203], v[90:93]
	v_mfma_f32_16x16x32_bf16 v[86:89], v[156:159], v[200:203], v[86:89]
	v_mfma_f32_16x16x32_bf16 v[86:89], v[160:163], v[204:207], v[86:89]
	v_mfma_f32_16x16x32_bf16 v[82:85], v[180:183], v[204:207], v[82:85]
	v_mfma_f32_16x16x32_bf16 v[82:85], v[164:167], v[200:203], v[82:85]
	v_mfma_f32_16x16x32_bf16 v[66:69], v[164:167], v[208:211], v[66:69]
	v_mfma_f32_16x16x32_bf16 v[66:69], v[180:183], v[212:215], v[66:69]
	v_mfma_f32_16x16x32_bf16 v[74:77], v[160:163], v[212:215], v[74:77]
	v_mfma_f32_16x16x32_bf16 v[74:77], v[156:159], v[208:211], v[74:77]
	v_mfma_f32_16x16x32_bf16 v[70:73], v[148:151], v[208:211], v[70:73]
	v_mfma_f32_16x16x32_bf16 v[70:73], v[152:155], v[212:215], v[70:73]
	v_mfma_f32_16x16x32_bf16 v[78:81], v[134:137], v[212:215], v[78:81]
	v_mfma_f32_16x16x32_bf16 v[78:81], v[130:133], v[208:211], v[78:81]
	s_setprio 0
	s_barrier
	s_mov_b32 m0, s27
	s_mov_b32 s18, s14
	s_mov_b32 s19, s15
	ds_read_b128 v[184:187], v174 offset:16384
	ds_read_b128 v[188:191], v174 offset:17408
	ds_read_b128 v[192:195], v174 offset:18432
	ds_read_b128 v[196:199], v174 offset:19456
	ds_read_b128 v[200:203], v174 offset:20480
	ds_read_b128 v[204:207], v174 offset:21504
	ds_read_b128 v[208:211], v174 offset:22528
	ds_read_b128 v[212:215], v174 offset:23552
	buffer_load_dwordx4 v171, s[16:19], s58 offen lds
	s_add_i32 s59, s58, 0x80000
	s_mov_b32 m0, s60
	s_nop 0
	buffer_load_dwordx4 v171, s[16:19], s59 offen lds
	s_add_i32 s59, s58, 0x100000
	s_mov_b32 m0, s61
	s_nop 0
	buffer_load_dwordx4 v171, s[16:19], s59 offen lds
	s_add_i32 s59, s58, 0x180000
	s_mov_b32 m0, s62
	s_nop 0
	buffer_load_dwordx4 v171, s[16:19], s59 offen lds
	s_mov_b32 m0, s25
	s_add_i32 s59, s53, 0x80000
	buffer_load_dwordx4 v170, s[12:15], s53 offen lds
	s_mov_b32 m0, s63
	s_nop 0
	buffer_load_dwordx4 v170, s[12:15], s59 offen lds
	s_waitcnt vmcnt(8)
	s_waitcnt lgkmcnt(0)
	s_setprio 1
	v_mfma_f32_16x16x32_bf16 v[62:65], v[130:133], v[184:187], v[62:65]
	s_barrier
	v_mfma_f32_16x16x32_bf16 v[62:65], v[134:137], v[188:191], v[62:65]
	v_mfma_f32_16x16x32_bf16 v[54:57], v[152:155], v[188:191], v[54:57]
	v_mfma_f32_16x16x32_bf16 v[54:57], v[148:151], v[184:187], v[54:57]
	v_mfma_f32_16x16x32_bf16 v[58:61], v[156:159], v[184:187], v[58:61]
	v_mfma_f32_16x16x32_bf16 v[58:61], v[160:163], v[188:191], v[58:61]
	v_mfma_f32_16x16x32_bf16 v[50:53], v[180:183], v[188:191], v[50:53]
	v_mfma_f32_16x16x32_bf16 v[50:53], v[164:167], v[184:187], v[50:53]
	v_mfma_f32_16x16x32_bf16 v[34:37], v[164:167], v[192:195], v[34:37]
	v_mfma_f32_16x16x32_bf16 v[34:37], v[180:183], v[196:199], v[34:37]
	v_mfma_f32_16x16x32_bf16 v[42:45], v[160:163], v[196:199], v[42:45]
	v_mfma_f32_16x16x32_bf16 v[42:45], v[156:159], v[192:195], v[42:45]
	v_mfma_f32_16x16x32_bf16 v[38:41], v[148:151], v[192:195], v[38:41]
	v_mfma_f32_16x16x32_bf16 v[38:41], v[152:155], v[196:199], v[38:41]
	v_mfma_f32_16x16x32_bf16 v[46:49], v[134:137], v[196:199], v[46:49]
	v_mfma_f32_16x16x32_bf16 v[46:49], v[130:133], v[192:195], v[46:49]
	v_mfma_f32_16x16x32_bf16 v[30:33], v[130:133], v[200:203], v[30:33]
	v_mfma_f32_16x16x32_bf16 v[30:33], v[134:137], v[204:207], v[30:33]
	v_mfma_f32_16x16x32_bf16 v[22:25], v[152:155], v[204:207], v[22:25]
	v_mfma_f32_16x16x32_bf16 v[22:25], v[148:151], v[200:203], v[22:25]
	v_mfma_f32_16x16x32_bf16 v[26:29], v[156:159], v[200:203], v[26:29]
	v_mfma_f32_16x16x32_bf16 v[26:29], v[160:163], v[204:207], v[26:29]
	v_mfma_f32_16x16x32_bf16 v[18:21], v[180:183], v[204:207], v[18:21]
	v_mfma_f32_16x16x32_bf16 v[18:21], v[164:167], v[200:203], v[18:21]
	v_mfma_f32_16x16x32_bf16 v[2:5], v[164:167], v[208:211], v[2:5]
	v_mfma_f32_16x16x32_bf16 v[2:5], v[180:183], v[212:215], v[2:5]
	v_mfma_f32_16x16x32_bf16 v[10:13], v[160:163], v[212:215], v[10:13]
	v_mfma_f32_16x16x32_bf16 v[10:13], v[156:159], v[208:211], v[10:13]
	v_mfma_f32_16x16x32_bf16 v[6:9], v[148:151], v[208:211], v[6:9]
	v_mfma_f32_16x16x32_bf16 v[6:9], v[152:155], v[212:215], v[6:9]
	v_mfma_f32_16x16x32_bf16 v[14:17], v[134:137], v[212:215], v[14:17]
	v_mfma_f32_16x16x32_bf16 v[14:17], v[130:133], v[208:211], v[14:17]
	s_setprio 0
	s_barrier
	ds_read_b128 v[130:133], v175
	ds_read_b128 v[134:137], v175 offset:1024
	ds_read_b128 v[148:151], v175 offset:2048
	ds_read_b128 v[152:155], v175 offset:3072
	ds_read_b128 v[156:159], v176
	ds_read_b128 v[160:163], v176 offset:1024
	ds_read_b128 v[164:167], v176 offset:2048
	ds_read_b128 v[180:183], v176 offset:3072
	s_mov_b32 m0, s64
	s_add_i32 s59, s53, 0x100000
	ds_read_b128 v[184:187], v174 offset:32768
	ds_read_b128 v[188:191], v174 offset:33792
	ds_read_b128 v[192:195], v174 offset:34816
	ds_read_b128 v[196:199], v174 offset:35840
	ds_read_b128 v[200:203], v174 offset:36864
	ds_read_b128 v[204:207], v174 offset:37888
	ds_read_b128 v[208:211], v174 offset:38912
	ds_read_b128 v[212:215], v174 offset:39936
	buffer_load_dwordx4 v170, s[12:15], s59 offen lds
	s_add_i32 s59, s53, 0x180000
	s_mov_b32 m0, s65
	s_nop 0
	buffer_load_dwordx4 v170, s[12:15], s59 offen lds
	s_waitcnt vmcnt(8)
	s_waitcnt lgkmcnt(0)
	s_setprio 1
	v_mfma_f32_16x16x32_bf16 v[126:129], v[130:133], v[184:187], v[126:129]
	s_barrier
	v_mfma_f32_16x16x32_bf16 v[126:129], v[134:137], v[188:191], v[126:129]
	v_mfma_f32_16x16x32_bf16 v[118:121], v[152:155], v[188:191], v[118:121]
	v_mfma_f32_16x16x32_bf16 v[118:121], v[148:151], v[184:187], v[118:121]
	v_mfma_f32_16x16x32_bf16 v[122:125], v[156:159], v[184:187], v[122:125]
	v_mfma_f32_16x16x32_bf16 v[122:125], v[160:163], v[188:191], v[122:125]
	v_mfma_f32_16x16x32_bf16 v[114:117], v[180:183], v[188:191], v[114:117]
	v_mfma_f32_16x16x32_bf16 v[114:117], v[164:167], v[184:187], v[114:117]
	v_mfma_f32_16x16x32_bf16 v[98:101], v[164:167], v[192:195], v[98:101]
	v_mfma_f32_16x16x32_bf16 v[98:101], v[180:183], v[196:199], v[98:101]
	v_mfma_f32_16x16x32_bf16 v[106:109], v[160:163], v[196:199], v[106:109]
	v_mfma_f32_16x16x32_bf16 v[106:109], v[156:159], v[192:195], v[106:109]
	v_mfma_f32_16x16x32_bf16 v[102:105], v[148:151], v[192:195], v[102:105]
	v_mfma_f32_16x16x32_bf16 v[102:105], v[152:155], v[196:199], v[102:105]
	v_mfma_f32_16x16x32_bf16 v[110:113], v[134:137], v[196:199], v[110:113]
	v_mfma_f32_16x16x32_bf16 v[110:113], v[130:133], v[192:195], v[110:113]
	v_mfma_f32_16x16x32_bf16 v[94:97], v[130:133], v[200:203], v[94:97]
	v_mfma_f32_16x16x32_bf16 v[94:97], v[134:137], v[204:207], v[94:97]
	v_mfma_f32_16x16x32_bf16 v[90:93], v[152:155], v[204:207], v[90:93]
	v_mfma_f32_16x16x32_bf16 v[90:93], v[148:151], v[200:203], v[90:93]
	v_mfma_f32_16x16x32_bf16 v[86:89], v[156:159], v[200:203], v[86:89]
	v_mfma_f32_16x16x32_bf16 v[86:89], v[160:163], v[204:207], v[86:89]
	v_mfma_f32_16x16x32_bf16 v[82:85], v[180:183], v[204:207], v[82:85]
	v_mfma_f32_16x16x32_bf16 v[82:85], v[164:167], v[200:203], v[82:85]
	v_mfma_f32_16x16x32_bf16 v[66:69], v[164:167], v[208:211], v[66:69]
	v_mfma_f32_16x16x32_bf16 v[66:69], v[180:183], v[212:215], v[66:69]
	v_mfma_f32_16x16x32_bf16 v[74:77], v[160:163], v[212:215], v[74:77]
	v_mfma_f32_16x16x32_bf16 v[74:77], v[156:159], v[208:211], v[74:77]
	v_mfma_f32_16x16x32_bf16 v[70:73], v[148:151], v[208:211], v[70:73]
	v_mfma_f32_16x16x32_bf16 v[70:73], v[152:155], v[212:215], v[70:73]
	v_mfma_f32_16x16x32_bf16 v[78:81], v[134:137], v[212:215], v[78:81]
	v_mfma_f32_16x16x32_bf16 v[78:81], v[130:133], v[208:211], v[78:81]
	s_setprio 0
	s_barrier
	s_mov_b32 m0, s70
	s_or_b32 s59, s58, 0x80
	ds_read_b128 v[184:187], v174 offset:49152
	ds_read_b128 v[188:191], v174 offset:50176
	ds_read_b128 v[192:195], v174 offset:51200
	ds_read_b128 v[196:199], v174 offset:52224
	ds_read_b128 v[200:203], v174 offset:53248
	ds_read_b128 v[204:207], v174 offset:54272
	ds_read_b128 v[208:211], v174 offset:55296
	ds_read_b128 v[212:215], v174 offset:56320
	buffer_load_dwordx4 v171, s[16:19], s59 offen lds
	s_add_i32 s59, s58, 0x80080
	s_mov_b32 m0, s71
	s_add_i32 s53, s53, 0x80080
	buffer_load_dwordx4 v171, s[16:19], s59 offen lds
	s_add_i32 s59, s58, 0x100080
	s_mov_b32 m0, s74
	s_add_i32 s58, s58, 0x180080
	buffer_load_dwordx4 v171, s[16:19], s59 offen lds
	s_mov_b32 m0, s75
	s_nop 0
	buffer_load_dwordx4 v171, s[16:19], s58 offen lds
	s_mov_b32 m0, s72
	s_nop 0
	buffer_load_dwordx4 v170, s[12:15], s57 offen lds
	s_mov_b32 m0, s73
	s_nop 0
	buffer_load_dwordx4 v170, s[12:15], s53 offen lds
	s_waitcnt vmcnt(8)
	s_waitcnt lgkmcnt(0)
	s_setprio 1
	v_mfma_f32_16x16x32_bf16 v[62:65], v[130:133], v[184:187], v[62:65]
	s_barrier
	v_mfma_f32_16x16x32_bf16 v[62:65], v[134:137], v[188:191], v[62:65]
	v_mfma_f32_16x16x32_bf16 v[54:57], v[152:155], v[188:191], v[54:57]
	v_mfma_f32_16x16x32_bf16 v[54:57], v[148:151], v[184:187], v[54:57]
	v_mfma_f32_16x16x32_bf16 v[58:61], v[156:159], v[184:187], v[58:61]
	v_mfma_f32_16x16x32_bf16 v[58:61], v[160:163], v[188:191], v[58:61]
	v_mfma_f32_16x16x32_bf16 v[50:53], v[180:183], v[188:191], v[50:53]
	v_mfma_f32_16x16x32_bf16 v[50:53], v[164:167], v[184:187], v[50:53]
	v_mfma_f32_16x16x32_bf16 v[34:37], v[164:167], v[192:195], v[34:37]
	v_mfma_f32_16x16x32_bf16 v[34:37], v[180:183], v[196:199], v[34:37]
	v_mfma_f32_16x16x32_bf16 v[42:45], v[160:163], v[196:199], v[42:45]
	v_mfma_f32_16x16x32_bf16 v[42:45], v[156:159], v[192:195], v[42:45]
	v_mfma_f32_16x16x32_bf16 v[38:41], v[148:151], v[192:195], v[38:41]
	v_mfma_f32_16x16x32_bf16 v[38:41], v[152:155], v[196:199], v[38:41]
	v_mfma_f32_16x16x32_bf16 v[46:49], v[134:137], v[196:199], v[46:49]
	v_mfma_f32_16x16x32_bf16 v[46:49], v[130:133], v[192:195], v[46:49]
	v_mfma_f32_16x16x32_bf16 v[30:33], v[130:133], v[200:203], v[30:33]
	v_mfma_f32_16x16x32_bf16 v[30:33], v[134:137], v[204:207], v[30:33]
	v_mfma_f32_16x16x32_bf16 v[22:25], v[152:155], v[204:207], v[22:25]
	v_mfma_f32_16x16x32_bf16 v[22:25], v[148:151], v[200:203], v[22:25]
	v_mfma_f32_16x16x32_bf16 v[26:29], v[156:159], v[200:203], v[26:29]
	v_mfma_f32_16x16x32_bf16 v[26:29], v[160:163], v[204:207], v[26:29]
	v_mfma_f32_16x16x32_bf16 v[18:21], v[180:183], v[204:207], v[18:21]
	v_mfma_f32_16x16x32_bf16 v[18:21], v[164:167], v[200:203], v[18:21]
	v_mfma_f32_16x16x32_bf16 v[2:5], v[164:167], v[208:211], v[2:5]
	v_mfma_f32_16x16x32_bf16 v[2:5], v[180:183], v[212:215], v[2:5]
	v_mfma_f32_16x16x32_bf16 v[10:13], v[160:163], v[212:215], v[10:13]
	v_mfma_f32_16x16x32_bf16 v[10:13], v[156:159], v[208:211], v[10:13]
	v_mfma_f32_16x16x32_bf16 v[6:9], v[148:151], v[208:211], v[6:9]
	v_mfma_f32_16x16x32_bf16 v[6:9], v[152:155], v[212:215], v[6:9]
	v_mfma_f32_16x16x32_bf16 v[14:17], v[134:137], v[212:215], v[14:17]
	v_mfma_f32_16x16x32_bf16 v[14:17], v[130:133], v[208:211], v[14:17]
	s_setprio 0
	s_barrier
	s_add_i32 s52, s52, 2
	s_addk_i32 s8, 0x100
	s_addk_i32 s9, 0x100
	s_cmp_ge_i32 s52, s21
	s_cbranch_scc0 .LBB0_892
	s_and_b64 vcc, exec, s[48:49]
	s_cbranch_vccz .LBB0_895

.LBB0_1020:
	v_add_u32_e32 v142, 0x10000, v162
	v_add_u32_e32 v150, 0x14000, v162
	ds_read_b128 v[130:133], v142
	ds_read_b128 v[134:137], v142 offset:1024
	ds_read_b128 v[138:141], v142 offset:2048
	ds_read_b128 v[142:145], v142 offset:3072
	ds_read_b128 v[154:157], v150
	ds_read_b128 v[164:167], v150 offset:1024
	ds_read_b128 v[168:171], v150 offset:2048
	ds_read_b128 v[172:175], v150 offset:3072
	s_add_i32 s90, s6, 0x100
	s_add_i32 s7, s88, s6
	s_cmp_eq_u32 s81, s89
	s_cselect_b32 s91, 0, s90
	s_cselect_b32 s93, s87, s7
	s_add_i32 s91, s91, s70
	s_or_b32 s92, s91, 0x80
	s_add_i32 s6, s3, s6
	s_mov_b32 m0, s82
	s_add_i32 s7, s6, 0x20080
	ds_read_b128 v[176:179], v163
	ds_read_b128 v[180:183], v163 offset:1024
	ds_read_b128 v[184:187], v163 offset:2048
	ds_read_b128 v[188:191], v163 offset:3072
	ds_read_b128 v[192:195], v163 offset:4096
	ds_read_b128 v[196:199], v163 offset:5120
	ds_read_b128 v[200:203], v163 offset:6144
	ds_read_b128 v[204:207], v163 offset:7168
	buffer_load_dwordx4 v161, s[12:15], s7 offen lds
	s_add_i32 s6, s6, 0x30080
	s_mov_b32 m0, s83
	s_nop 0
	buffer_load_dwordx4 v161, s[12:15], s6 offen lds
	s_waitcnt vmcnt(8)
	s_waitcnt lgkmcnt(0)
	s_setprio 1
	v_mfma_f32_16x16x32_bf16 v[126:129], v[130:133], v[176:179], v[126:129]
	s_barrier
	v_mfma_f32_16x16x32_bf16 v[126:129], v[134:137], v[180:183], v[126:129]
	v_mfma_f32_16x16x32_bf16 v[122:125], v[142:145], v[180:183], v[122:125]
	v_mfma_f32_16x16x32_bf16 v[122:125], v[138:141], v[176:179], v[122:125]
	v_mfma_f32_16x16x32_bf16 v[118:121], v[154:157], v[176:179], v[118:121]
	v_mfma_f32_16x16x32_bf16 v[118:121], v[164:167], v[180:183], v[118:121]
	v_mfma_f32_16x16x32_bf16 v[114:117], v[172:175], v[180:183], v[114:117]
	v_mfma_f32_16x16x32_bf16 v[114:117], v[168:171], v[176:179], v[114:117]
	v_mfma_f32_16x16x32_bf16 v[98:101], v[168:171], v[184:187], v[98:101]
	v_mfma_f32_16x16x32_bf16 v[98:101], v[172:175], v[188:191], v[98:101]
	v_mfma_f32_16x16x32_bf16 v[102:105], v[164:167], v[188:191], v[102:105]
	v_mfma_f32_16x16x32_bf16 v[102:105], v[154:157], v[184:187], v[102:105]
	v_mfma_f32_16x16x32_bf16 v[106:109], v[138:141], v[184:187], v[106:109]
	v_mfma_f32_16x16x32_bf16 v[106:109], v[142:145], v[188:191], v[106:109]
	v_mfma_f32_16x16x32_bf16 v[110:113], v[134:137], v[188:191], v[110:113]
	v_mfma_f32_16x16x32_bf16 v[110:113], v[130:133], v[184:187], v[110:113]
	v_mfma_f32_16x16x32_bf16 v[94:97], v[130:133], v[192:195], v[94:97]
	v_mfma_f32_16x16x32_bf16 v[94:97], v[134:137], v[196:199], v[94:97]
	v_mfma_f32_16x16x32_bf16 v[90:93], v[142:145], v[196:199], v[90:93]
	v_mfma_f32_16x16x32_bf16 v[90:93], v[138:141], v[192:195], v[90:93]
	v_mfma_f32_16x16x32_bf16 v[86:89], v[154:157], v[192:195], v[86:89]
	v_mfma_f32_16x16x32_bf16 v[86:89], v[164:167], v[196:199], v[86:89]
	v_mfma_f32_16x16x32_bf16 v[82:85], v[172:175], v[196:199], v[82:85]
	v_mfma_f32_16x16x32_bf16 v[82:85], v[168:171], v[192:195], v[82:85]
	v_mfma_f32_16x16x32_bf16 v[66:69], v[168:171], v[200:203], v[66:69]
	v_mfma_f32_16x16x32_bf16 v[66:69], v[172:175], v[204:207], v[66:69]
	v_mfma_f32_16x16x32_bf16 v[70:73], v[164:167], v[204:207], v[70:73]
	v_mfma_f32_16x16x32_bf16 v[70:73], v[154:157], v[200:203], v[70:73]
	v_mfma_f32_16x16x32_bf16 v[74:77], v[138:141], v[200:203], v[74:77]
	v_mfma_f32_16x16x32_bf16 v[74:77], v[142:145], v[204:207], v[74:77]
	v_mfma_f32_16x16x32_bf16 v[78:81], v[134:137], v[204:207], v[78:81]
	v_mfma_f32_16x16x32_bf16 v[78:81], v[130:133], v[200:203], v[78:81]
	s_setprio 0
	s_barrier
	s_mov_b32 m0, s66
	s_mov_b32 s6, s14
	s_mov_b32 s7, s15
	ds_read_b128 v[176:179], v163 offset:16384
	ds_read_b128 v[180:183], v163 offset:17408
	ds_read_b128 v[184:187], v163 offset:18432
	ds_read_b128 v[188:191], v163 offset:19456
	ds_read_b128 v[192:195], v163 offset:20480
	ds_read_b128 v[196:199], v163 offset:21504
	ds_read_b128 v[200:203], v163 offset:22528
	ds_read_b128 v[204:207], v163 offset:23552
	buffer_load_dwordx4 v160, s[4:7], s93 offen lds
	s_add_i32 s94, s93, 0x10000
	s_mov_b32 m0, s67
	s_nop 0
	buffer_load_dwordx4 v160, s[4:7], s94 offen lds
	s_add_i32 s94, s93, 0x20000
	s_mov_b32 m0, s68
	s_nop 0
	buffer_load_dwordx4 v160, s[4:7], s94 offen lds
	s_add_i32 s94, s93, 0x30000
	s_mov_b32 m0, s69
	s_nop 0
	buffer_load_dwordx4 v160, s[4:7], s94 offen lds
	s_mov_b32 m0, s65
	s_add_i32 s94, s91, 0x10000
	buffer_load_dwordx4 v161, s[12:15], s91 offen lds
	s_mov_b32 m0, s71
	s_nop 0
	buffer_load_dwordx4 v161, s[12:15], s94 offen lds
	s_waitcnt vmcnt(8)
	s_waitcnt lgkmcnt(0)
	s_setprio 1
	v_mfma_f32_16x16x32_bf16 v[62:65], v[130:133], v[176:179], v[62:65]
	s_barrier
	v_mfma_f32_16x16x32_bf16 v[62:65], v[134:137], v[180:183], v[62:65]
	v_mfma_f32_16x16x32_bf16 v[58:61], v[142:145], v[180:183], v[58:61]
	v_mfma_f32_16x16x32_bf16 v[58:61], v[138:141], v[176:179], v[58:61]
	v_mfma_f32_16x16x32_bf16 v[54:57], v[154:157], v[176:179], v[54:57]
	v_mfma_f32_16x16x32_bf16 v[54:57], v[164:167], v[180:183], v[54:57]
	v_mfma_f32_16x16x32_bf16 v[50:53], v[172:175], v[180:183], v[50:53]
	v_mfma_f32_16x16x32_bf16 v[50:53], v[168:171], v[176:179], v[50:53]
	v_mfma_f32_16x16x32_bf16 v[34:37], v[168:171], v[184:187], v[34:37]
	v_mfma_f32_16x16x32_bf16 v[34:37], v[172:175], v[188:191], v[34:37]
	v_mfma_f32_16x16x32_bf16 v[38:41], v[164:167], v[188:191], v[38:41]
	v_mfma_f32_16x16x32_bf16 v[38:41], v[154:157], v[184:187], v[38:41]
	v_mfma_f32_16x16x32_bf16 v[42:45], v[138:141], v[184:187], v[42:45]
	v_mfma_f32_16x16x32_bf16 v[42:45], v[142:145], v[188:191], v[42:45]
	v_mfma_f32_16x16x32_bf16 v[46:49], v[134:137], v[188:191], v[46:49]
	v_mfma_f32_16x16x32_bf16 v[46:49], v[130:133], v[184:187], v[46:49]
	v_mfma_f32_16x16x32_bf16 v[30:33], v[130:133], v[192:195], v[30:33]
	v_mfma_f32_16x16x32_bf16 v[30:33], v[134:137], v[196:199], v[30:33]
	v_mfma_f32_16x16x32_bf16 v[26:29], v[142:145], v[196:199], v[26:29]
	v_mfma_f32_16x16x32_bf16 v[26:29], v[138:141], v[192:195], v[26:29]
	v_mfma_f32_16x16x32_bf16 v[22:25], v[154:157], v[192:195], v[22:25]
	v_mfma_f32_16x16x32_bf16 v[22:25], v[164:167], v[196:199], v[22:25]
	v_mfma_f32_16x16x32_bf16 v[18:21], v[172:175], v[196:199], v[18:21]
	v_mfma_f32_16x16x32_bf16 v[18:21], v[168:171], v[192:195], v[18:21]
	v_mfma_f32_16x16x32_bf16 v[2:5], v[168:171], v[200:203], v[2:5]
	v_mfma_f32_16x16x32_bf16 v[2:5], v[172:175], v[204:207], v[2:5]
	v_mfma_f32_16x16x32_bf16 v[6:9], v[164:167], v[204:207], v[6:9]
	v_mfma_f32_16x16x32_bf16 v[6:9], v[154:157], v[200:203], v[6:9]
	v_mfma_f32_16x16x32_bf16 v[10:13], v[138:141], v[200:203], v[10:13]
	v_mfma_f32_16x16x32_bf16 v[10:13], v[142:145], v[204:207], v[10:13]
	v_mfma_f32_16x16x32_bf16 v[14:17], v[134:137], v[204:207], v[14:17]
	v_mfma_f32_16x16x32_bf16 v[14:17], v[130:133], v[200:203], v[14:17]
	s_setprio 0
	s_barrier
	v_add_u32_e32 v142, 0x18000, v162
	v_add_u32_e32 v150, 0x1c000, v162
	ds_read_b128 v[130:133], v142
	ds_read_b128 v[134:137], v142 offset:1024
	ds_read_b128 v[138:141], v142 offset:2048
	ds_read_b128 v[142:145], v142 offset:3072
	ds_read_b128 v[154:157], v150
	ds_read_b128 v[164:167], v150 offset:1024
	ds_read_b128 v[168:171], v150 offset:2048
	ds_read_b128 v[172:175], v150 offset:3072
	s_mov_b32 m0, s72
	s_add_i32 s94, s91, 0x20000
	ds_read_b128 v[176:179], v163 offset:32768
	ds_read_b128 v[180:183], v163 offset:33792
	ds_read_b128 v[184:187], v163 offset:34816
	ds_read_b128 v[188:191], v163 offset:35840
	ds_read_b128 v[192:195], v163 offset:36864
	ds_read_b128 v[196:199], v163 offset:37888
	ds_read_b128 v[200:203], v163 offset:38912
	ds_read_b128 v[204:207], v163 offset:39936
	buffer_load_dwordx4 v161, s[12:15], s94 offen lds
	s_add_i32 s94, s91, 0x30000
	s_mov_b32 m0, s73
	s_nop 0
	buffer_load_dwordx4 v161, s[12:15], s94 offen lds
	s_waitcnt vmcnt(8)
	s_waitcnt lgkmcnt(0)
	s_setprio 1
	v_mfma_f32_16x16x32_bf16 v[126:129], v[130:133], v[176:179], v[126:129]
	s_barrier
	v_mfma_f32_16x16x32_bf16 v[126:129], v[134:137], v[180:183], v[126:129]
	v_mfma_f32_16x16x32_bf16 v[122:125], v[142:145], v[180:183], v[122:125]
	v_mfma_f32_16x16x32_bf16 v[122:125], v[138:141], v[176:179], v[122:125]
	v_mfma_f32_16x16x32_bf16 v[118:121], v[154:157], v[176:179], v[118:121]
	v_mfma_f32_16x16x32_bf16 v[118:121], v[164:167], v[180:183], v[118:121]
	v_mfma_f32_16x16x32_bf16 v[114:117], v[172:175], v[180:183], v[114:117]
	v_mfma_f32_16x16x32_bf16 v[114:117], v[168:171], v[176:179], v[114:117]
	v_mfma_f32_16x16x32_bf16 v[98:101], v[168:171], v[184:187], v[98:101]
	v_mfma_f32_16x16x32_bf16 v[98:101], v[172:175], v[188:191], v[98:101]
	v_mfma_f32_16x16x32_bf16 v[102:105], v[164:167], v[188:191], v[102:105]
	v_mfma_f32_16x16x32_bf16 v[102:105], v[154:157], v[184:187], v[102:105]
	v_mfma_f32_16x16x32_bf16 v[106:109], v[138:141], v[184:187], v[106:109]
	v_mfma_f32_16x16x32_bf16 v[106:109], v[142:145], v[188:191], v[106:109]
	v_mfma_f32_16x16x32_bf16 v[110:113], v[134:137], v[188:191], v[110:113]
	v_mfma_f32_16x16x32_bf16 v[110:113], v[130:133], v[184:187], v[110:113]
	v_mfma_f32_16x16x32_bf16 v[94:97], v[130:133], v[192:195], v[94:97]
	v_mfma_f32_16x16x32_bf16 v[94:97], v[134:137], v[196:199], v[94:97]
	v_mfma_f32_16x16x32_bf16 v[90:93], v[142:145], v[196:199], v[90:93]
	v_mfma_f32_16x16x32_bf16 v[90:93], v[138:141], v[192:195], v[90:93]
	v_mfma_f32_16x16x32_bf16 v[86:89], v[154:157], v[192:195], v[86:89]
	v_mfma_f32_16x16x32_bf16 v[86:89], v[164:167], v[196:199], v[86:89]
	v_mfma_f32_16x16x32_bf16 v[82:85], v[172:175], v[196:199], v[82:85]
	v_mfma_f32_16x16x32_bf16 v[82:85], v[168:171], v[192:195], v[82:85]
	v_mfma_f32_16x16x32_bf16 v[66:69], v[168:171], v[200:203], v[66:69]
	v_mfma_f32_16x16x32_bf16 v[66:69], v[172:175], v[204:207], v[66:69]
	v_mfma_f32_16x16x32_bf16 v[70:73], v[164:167], v[204:207], v[70:73]
	v_mfma_f32_16x16x32_bf16 v[70:73], v[154:157], v[200:203], v[70:73]
	v_mfma_f32_16x16x32_bf16 v[74:77], v[138:141], v[200:203], v[74:77]
	v_mfma_f32_16x16x32_bf16 v[74:77], v[142:145], v[204:207], v[74:77]
	v_mfma_f32_16x16x32_bf16 v[78:81], v[134:137], v[204:207], v[78:81]
	v_mfma_f32_16x16x32_bf16 v[78:81], v[130:133], v[200:203], v[78:81]
	s_setprio 0
	s_barrier
	s_mov_b32 m0, s74
	s_or_b32 s94, s93, 0x80
	ds_read_b128 v[176:179], v163 offset:49152
	ds_read_b128 v[180:183], v163 offset:50176
	ds_read_b128 v[184:187], v163 offset:51200
	ds_read_b128 v[188:191], v163 offset:52224
	ds_read_b128 v[192:195], v163 offset:53248
	ds_read_b128 v[196:199], v163 offset:54272
	ds_read_b128 v[200:203], v163 offset:55296
	ds_read_b128 v[204:207], v163 offset:56320
	buffer_load_dwordx4 v160, s[4:7], s94 offen lds
	s_add_i32 s94, s93, 0x10080
	s_mov_b32 m0, s75
	s_add_i32 s91, s91, 0x10080
	buffer_load_dwordx4 v160, s[4:7], s94 offen lds
	s_add_i32 s94, s93, 0x20080
	s_mov_b32 m0, s78
	s_add_i32 s93, s93, 0x30080
	buffer_load_dwordx4 v160, s[4:7], s94 offen lds
	s_mov_b32 m0, s79
	s_nop 0
	buffer_load_dwordx4 v160, s[4:7], s93 offen lds
	s_mov_b32 m0, s76
	s_nop 0
	buffer_load_dwordx4 v161, s[12:15], s92 offen lds
	s_mov_b32 m0, s77
	s_nop 0
	buffer_load_dwordx4 v161, s[12:15], s91 offen lds
	s_waitcnt vmcnt(8)
	s_waitcnt lgkmcnt(0)
	s_setprio 1
	v_mfma_f32_16x16x32_bf16 v[62:65], v[130:133], v[176:179], v[62:65]
	s_barrier
	v_mfma_f32_16x16x32_bf16 v[62:65], v[134:137], v[180:183], v[62:65]
	v_mfma_f32_16x16x32_bf16 v[58:61], v[142:145], v[180:183], v[58:61]
	v_mfma_f32_16x16x32_bf16 v[58:61], v[138:141], v[176:179], v[58:61]
	v_mfma_f32_16x16x32_bf16 v[54:57], v[154:157], v[176:179], v[54:57]
	v_mfma_f32_16x16x32_bf16 v[54:57], v[164:167], v[180:183], v[54:57]
	v_mfma_f32_16x16x32_bf16 v[50:53], v[172:175], v[180:183], v[50:53]
	v_mfma_f32_16x16x32_bf16 v[50:53], v[168:171], v[176:179], v[50:53]
	v_mfma_f32_16x16x32_bf16 v[34:37], v[168:171], v[184:187], v[34:37]
	v_mfma_f32_16x16x32_bf16 v[34:37], v[172:175], v[188:191], v[34:37]
	v_mfma_f32_16x16x32_bf16 v[38:41], v[164:167], v[188:191], v[38:41]
	v_mfma_f32_16x16x32_bf16 v[38:41], v[154:157], v[184:187], v[38:41]
	v_mfma_f32_16x16x32_bf16 v[42:45], v[138:141], v[184:187], v[42:45]
	v_mfma_f32_16x16x32_bf16 v[42:45], v[142:145], v[188:191], v[42:45]
	v_mfma_f32_16x16x32_bf16 v[46:49], v[134:137], v[188:191], v[46:49]
	v_mfma_f32_16x16x32_bf16 v[46:49], v[130:133], v[184:187], v[46:49]
	v_mfma_f32_16x16x32_bf16 v[30:33], v[130:133], v[192:195], v[30:33]
	v_mfma_f32_16x16x32_bf16 v[30:33], v[134:137], v[196:199], v[30:33]
	v_mfma_f32_16x16x32_bf16 v[26:29], v[142:145], v[196:199], v[26:29]
	v_mfma_f32_16x16x32_bf16 v[26:29], v[138:141], v[192:195], v[26:29]
	v_mfma_f32_16x16x32_bf16 v[22:25], v[154:157], v[192:195], v[22:25]
	v_mfma_f32_16x16x32_bf16 v[22:25], v[164:167], v[196:199], v[22:25]
	v_mfma_f32_16x16x32_bf16 v[18:21], v[172:175], v[196:199], v[18:21]
	v_mfma_f32_16x16x32_bf16 v[18:21], v[168:171], v[192:195], v[18:21]
	v_mfma_f32_16x16x32_bf16 v[2:5], v[168:171], v[200:203], v[2:5]
	v_mfma_f32_16x16x32_bf16 v[2:5], v[172:175], v[204:207], v[2:5]
	v_mfma_f32_16x16x32_bf16 v[6:9], v[164:167], v[204:207], v[6:9]
	v_mfma_f32_16x16x32_bf16 v[6:9], v[154:157], v[200:203], v[6:9]
	v_mfma_f32_16x16x32_bf16 v[10:13], v[138:141], v[200:203], v[10:13]
	v_mfma_f32_16x16x32_bf16 v[10:13], v[142:145], v[204:207], v[10:13]
	v_mfma_f32_16x16x32_bf16 v[14:17], v[134:137], v[204:207], v[14:17]
	v_mfma_f32_16x16x32_bf16 v[14:17], v[130:133], v[200:203], v[14:17]
	s_setprio 0
	s_barrier
	s_add_i32 s89, s89, 2
	s_cmp_ge_i32 s89, s63
	s_mov_b32 s6, s90
	s_cbranch_scc0 .LBB0_1020
	s_and_b64 vcc, exec, s[54:55]
	s_cbranch_vccz .LBB0_1023

.LBB0_1035:
	ds_read_b128 v[140:143], v134
	ds_read_b128 v[148:151], v134 offset:1024
	ds_read_b128 v[152:155], v134 offset:2048
	ds_read_b128 v[156:159], v134 offset:3072
	ds_read_b128 v[160:163], v135
	ds_read_b128 v[164:167], v135 offset:1024
	ds_read_b128 v[168:171], v135 offset:2048
	ds_read_b128 v[172:175], v135 offset:3072
	s_add_i32 s73, s70, 0xfffb8080
	s_cmp_eq_u32 s53, s72
	s_cselect_b32 s73, s68, s73
	s_cselect_b32 s75, s69, s71
	s_add_i32 s74, s73, 0x80
	s_add_i32 s76, s70, 0xfffe8000
	s_mov_b32 m0, s54
	ds_read_b128 v[176:179], v136
	ds_read_b128 v[180:183], v136 offset:1024
	ds_read_b128 v[184:187], v136 offset:2048
	ds_read_b128 v[188:191], v136 offset:3072
	ds_read_b128 v[192:195], v136 offset:4096
	ds_read_b128 v[196:199], v136 offset:5120
	ds_read_b128 v[200:203], v136 offset:6144
	ds_read_b128 v[204:207], v136 offset:7168
	buffer_load_dwordx4 v132, s[12:15], s76 offen lds
	s_mov_b32 m0, s55
	s_nop 0
	buffer_load_dwordx4 v132, s[12:15], s70 offen lds
	s_waitcnt vmcnt(8)
	s_waitcnt lgkmcnt(0)
	s_setprio 1
	v_mfma_f32_16x16x32_bf16 v[126:129], v[140:143], v[176:179], v[126:129]
	s_barrier
	v_mfma_f32_16x16x32_bf16 v[126:129], v[148:151], v[180:183], v[126:129]
	v_mfma_f32_16x16x32_bf16 v[122:125], v[156:159], v[180:183], v[122:125]
	v_mfma_f32_16x16x32_bf16 v[122:125], v[152:155], v[176:179], v[122:125]
	v_mfma_f32_16x16x32_bf16 v[118:121], v[160:163], v[176:179], v[118:121]
	v_mfma_f32_16x16x32_bf16 v[118:121], v[164:167], v[180:183], v[118:121]
	v_mfma_f32_16x16x32_bf16 v[114:117], v[172:175], v[180:183], v[114:117]
	v_mfma_f32_16x16x32_bf16 v[114:117], v[168:171], v[176:179], v[114:117]
	v_mfma_f32_16x16x32_bf16 v[98:101], v[168:171], v[184:187], v[98:101]
	v_mfma_f32_16x16x32_bf16 v[98:101], v[172:175], v[188:191], v[98:101]
	v_mfma_f32_16x16x32_bf16 v[102:105], v[164:167], v[188:191], v[102:105]
	v_mfma_f32_16x16x32_bf16 v[102:105], v[160:163], v[184:187], v[102:105]
	v_mfma_f32_16x16x32_bf16 v[106:109], v[152:155], v[184:187], v[106:109]
	v_mfma_f32_16x16x32_bf16 v[106:109], v[156:159], v[188:191], v[106:109]
	v_mfma_f32_16x16x32_bf16 v[110:113], v[148:151], v[188:191], v[110:113]
	v_mfma_f32_16x16x32_bf16 v[110:113], v[140:143], v[184:187], v[110:113]
	v_mfma_f32_16x16x32_bf16 v[94:97], v[140:143], v[192:195], v[94:97]
	v_mfma_f32_16x16x32_bf16 v[94:97], v[148:151], v[196:199], v[94:97]
	v_mfma_f32_16x16x32_bf16 v[90:93], v[156:159], v[196:199], v[90:93]
	v_mfma_f32_16x16x32_bf16 v[90:93], v[152:155], v[192:195], v[90:93]
	v_mfma_f32_16x16x32_bf16 v[86:89], v[160:163], v[192:195], v[86:89]
	v_mfma_f32_16x16x32_bf16 v[86:89], v[164:167], v[196:199], v[86:89]
	v_mfma_f32_16x16x32_bf16 v[82:85], v[172:175], v[196:199], v[82:85]
	v_mfma_f32_16x16x32_bf16 v[82:85], v[168:171], v[192:195], v[82:85]
	v_mfma_f32_16x16x32_bf16 v[66:69], v[168:171], v[200:203], v[66:69]
	v_mfma_f32_16x16x32_bf16 v[66:69], v[172:175], v[204:207], v[66:69]
	v_mfma_f32_16x16x32_bf16 v[70:73], v[164:167], v[204:207], v[70:73]
	v_mfma_f32_16x16x32_bf16 v[70:73], v[160:163], v[200:203], v[70:73]
	v_mfma_f32_16x16x32_bf16 v[74:77], v[152:155], v[200:203], v[74:77]
	v_mfma_f32_16x16x32_bf16 v[74:77], v[156:159], v[204:207], v[74:77]
	v_mfma_f32_16x16x32_bf16 v[78:81], v[148:151], v[204:207], v[78:81]
	v_mfma_f32_16x16x32_bf16 v[78:81], v[140:143], v[200:203], v[78:81]
	s_setprio 0
	s_barrier
	s_mov_b32 m0, s30
	ds_read_b128 v[176:179], v136 offset:16384
	ds_read_b128 v[180:183], v136 offset:17408
	ds_read_b128 v[184:187], v136 offset:18432
	ds_read_b128 v[188:191], v136 offset:19456
	ds_read_b128 v[192:195], v136 offset:20480
	ds_read_b128 v[196:199], v136 offset:21504
	ds_read_b128 v[200:203], v136 offset:22528
	ds_read_b128 v[204:207], v136 offset:23552
	buffer_load_dwordx4 v133, s[16:19], s75 offen lds
	s_add_i32 s76, s75, 0x200000
	s_mov_b32 m0, s31
	s_nop 0
	buffer_load_dwordx4 v133, s[16:19], s76 offen lds
	s_add_i32 s76, s75, 0x400000
	s_mov_b32 m0, s35
	s_nop 0
	buffer_load_dwordx4 v133, s[16:19], s76 offen lds
	s_add_i32 s76, s75, 0x600000
	s_mov_b32 m0, s42
	s_nop 0
	buffer_load_dwordx4 v133, s[16:19], s76 offen lds
	s_mov_b32 m0, s27
	s_add_i32 s76, s73, 0x18000
	buffer_load_dwordx4 v132, s[12:15], s73 offen lds
	s_mov_b32 m0, s43
	s_nop 0
	buffer_load_dwordx4 v132, s[12:15], s76 offen lds
	s_waitcnt vmcnt(8)
	s_waitcnt lgkmcnt(0)
	s_setprio 1
	v_mfma_f32_16x16x32_bf16 v[62:65], v[140:143], v[176:179], v[62:65]
	s_barrier
	v_mfma_f32_16x16x32_bf16 v[62:65], v[148:151], v[180:183], v[62:65]
	v_mfma_f32_16x16x32_bf16 v[58:61], v[156:159], v[180:183], v[58:61]
	v_mfma_f32_16x16x32_bf16 v[58:61], v[152:155], v[176:179], v[58:61]
	v_mfma_f32_16x16x32_bf16 v[54:57], v[160:163], v[176:179], v[54:57]
	v_mfma_f32_16x16x32_bf16 v[54:57], v[164:167], v[180:183], v[54:57]
	v_mfma_f32_16x16x32_bf16 v[50:53], v[172:175], v[180:183], v[50:53]
	v_mfma_f32_16x16x32_bf16 v[50:53], v[168:171], v[176:179], v[50:53]
	v_mfma_f32_16x16x32_bf16 v[34:37], v[168:171], v[184:187], v[34:37]
	v_mfma_f32_16x16x32_bf16 v[34:37], v[172:175], v[188:191], v[34:37]
	v_mfma_f32_16x16x32_bf16 v[38:41], v[164:167], v[188:191], v[38:41]
	v_mfma_f32_16x16x32_bf16 v[38:41], v[160:163], v[184:187], v[38:41]
	v_mfma_f32_16x16x32_bf16 v[42:45], v[152:155], v[184:187], v[42:45]
	v_mfma_f32_16x16x32_bf16 v[42:45], v[156:159], v[188:191], v[42:45]
	v_mfma_f32_16x16x32_bf16 v[46:49], v[148:151], v[188:191], v[46:49]
	v_mfma_f32_16x16x32_bf16 v[46:49], v[140:143], v[184:187], v[46:49]
	v_mfma_f32_16x16x32_bf16 v[30:33], v[140:143], v[192:195], v[30:33]
	v_mfma_f32_16x16x32_bf16 v[30:33], v[148:151], v[196:199], v[30:33]
	v_mfma_f32_16x16x32_bf16 v[26:29], v[156:159], v[196:199], v[26:29]
	v_mfma_f32_16x16x32_bf16 v[26:29], v[152:155], v[192:195], v[26:29]
	v_mfma_f32_16x16x32_bf16 v[22:25], v[160:163], v[192:195], v[22:25]
	v_mfma_f32_16x16x32_bf16 v[22:25], v[164:167], v[196:199], v[22:25]
	v_mfma_f32_16x16x32_bf16 v[18:21], v[172:175], v[196:199], v[18:21]
	v_mfma_f32_16x16x32_bf16 v[18:21], v[168:171], v[192:195], v[18:21]
	v_mfma_f32_16x16x32_bf16 v[2:5], v[168:171], v[200:203], v[2:5]
	v_mfma_f32_16x16x32_bf16 v[2:5], v[172:175], v[204:207], v[2:5]
	v_mfma_f32_16x16x32_bf16 v[6:9], v[164:167], v[204:207], v[6:9]
	v_mfma_f32_16x16x32_bf16 v[6:9], v[160:163], v[200:203], v[6:9]
	v_mfma_f32_16x16x32_bf16 v[10:13], v[152:155], v[200:203], v[10:13]
	v_mfma_f32_16x16x32_bf16 v[10:13], v[156:159], v[204:207], v[10:13]
	v_mfma_f32_16x16x32_bf16 v[14:17], v[148:151], v[204:207], v[14:17]
	v_mfma_f32_16x16x32_bf16 v[14:17], v[140:143], v[200:203], v[14:17]
	s_setprio 0
	s_barrier
	ds_read_b128 v[140:143], v137
	ds_read_b128 v[148:151], v137 offset:1024
	ds_read_b128 v[152:155], v137 offset:2048
	ds_read_b128 v[156:159], v137 offset:3072
	ds_read_b128 v[160:163], v138
	ds_read_b128 v[164:167], v138 offset:1024
	ds_read_b128 v[168:171], v138 offset:2048
	ds_read_b128 v[172:175], v138 offset:3072
	s_mov_b32 m0, s44
	s_add_i32 s76, s73, 0x30000
	ds_read_b128 v[176:179], v136 offset:32768
	ds_read_b128 v[180:183], v136 offset:33792
	ds_read_b128 v[184:187], v136 offset:34816
	ds_read_b128 v[188:191], v136 offset:35840
	ds_read_b128 v[192:195], v136 offset:36864
	ds_read_b128 v[196:199], v136 offset:37888
	ds_read_b128 v[200:203], v136 offset:38912
	ds_read_b128 v[204:207], v136 offset:39936
	buffer_load_dwordx4 v132, s[12:15], s76 offen lds
	s_add_i32 s76, s73, 0x48000
	s_mov_b32 m0, s45
	s_nop 0
	buffer_load_dwordx4 v132, s[12:15], s76 offen lds
	s_waitcnt vmcnt(8)
	s_waitcnt lgkmcnt(0)
	s_setprio 1
	v_mfma_f32_16x16x32_bf16 v[126:129], v[140:143], v[176:179], v[126:129]
	s_barrier
	v_mfma_f32_16x16x32_bf16 v[126:129], v[148:151], v[180:183], v[126:129]
	v_mfma_f32_16x16x32_bf16 v[122:125], v[156:159], v[180:183], v[122:125]
	v_mfma_f32_16x16x32_bf16 v[122:125], v[152:155], v[176:179], v[122:125]
	v_mfma_f32_16x16x32_bf16 v[118:121], v[160:163], v[176:179], v[118:121]
	v_mfma_f32_16x16x32_bf16 v[118:121], v[164:167], v[180:183], v[118:121]
	v_mfma_f32_16x16x32_bf16 v[114:117], v[172:175], v[180:183], v[114:117]
	v_mfma_f32_16x16x32_bf16 v[114:117], v[168:171], v[176:179], v[114:117]
	v_mfma_f32_16x16x32_bf16 v[98:101], v[168:171], v[184:187], v[98:101]
	v_mfma_f32_16x16x32_bf16 v[98:101], v[172:175], v[188:191], v[98:101]
	v_mfma_f32_16x16x32_bf16 v[102:105], v[164:167], v[188:191], v[102:105]
	v_mfma_f32_16x16x32_bf16 v[102:105], v[160:163], v[184:187], v[102:105]
	v_mfma_f32_16x16x32_bf16 v[106:109], v[152:155], v[184:187], v[106:109]
	v_mfma_f32_16x16x32_bf16 v[106:109], v[156:159], v[188:191], v[106:109]
	v_mfma_f32_16x16x32_bf16 v[110:113], v[148:151], v[188:191], v[110:113]
	v_mfma_f32_16x16x32_bf16 v[110:113], v[140:143], v[184:187], v[110:113]
	v_mfma_f32_16x16x32_bf16 v[94:97], v[140:143], v[192:195], v[94:97]
	v_mfma_f32_16x16x32_bf16 v[94:97], v[148:151], v[196:199], v[94:97]
	v_mfma_f32_16x16x32_bf16 v[90:93], v[156:159], v[196:199], v[90:93]
	v_mfma_f32_16x16x32_bf16 v[90:93], v[152:155], v[192:195], v[90:93]
	v_mfma_f32_16x16x32_bf16 v[86:89], v[160:163], v[192:195], v[86:89]
	v_mfma_f32_16x16x32_bf16 v[86:89], v[164:167], v[196:199], v[86:89]
	v_mfma_f32_16x16x32_bf16 v[82:85], v[172:175], v[196:199], v[82:85]
	v_mfma_f32_16x16x32_bf16 v[82:85], v[168:171], v[192:195], v[82:85]
	v_mfma_f32_16x16x32_bf16 v[66:69], v[168:171], v[200:203], v[66:69]
	v_mfma_f32_16x16x32_bf16 v[66:69], v[172:175], v[204:207], v[66:69]
	v_mfma_f32_16x16x32_bf16 v[70:73], v[164:167], v[204:207], v[70:73]
	v_mfma_f32_16x16x32_bf16 v[70:73], v[160:163], v[200:203], v[70:73]
	v_mfma_f32_16x16x32_bf16 v[74:77], v[152:155], v[200:203], v[74:77]
	v_mfma_f32_16x16x32_bf16 v[74:77], v[156:159], v[204:207], v[74:77]
	v_mfma_f32_16x16x32_bf16 v[78:81], v[148:151], v[204:207], v[78:81]
	v_mfma_f32_16x16x32_bf16 v[78:81], v[140:143], v[200:203], v[78:81]
	s_setprio 0
	s_barrier
	s_mov_b32 m0, s46
	s_add_i32 s76, s75, 0x80
	ds_read_b128 v[176:179], v136 offset:49152
	ds_read_b128 v[180:183], v136 offset:50176
	ds_read_b128 v[184:187], v136 offset:51200
	ds_read_b128 v[188:191], v136 offset:52224
	ds_read_b128 v[192:195], v136 offset:53248
	ds_read_b128 v[196:199], v136 offset:54272
	ds_read_b128 v[200:203], v136 offset:55296
	ds_read_b128 v[204:207], v136 offset:56320
	buffer_load_dwordx4 v133, s[16:19], s76 offen lds
	s_add_i32 s76, s75, 0x200080
	s_mov_b32 m0, s47
	s_add_i32 s73, s73, 0x18080
	buffer_load_dwordx4 v133, s[16:19], s76 offen lds
	s_add_i32 s76, s75, 0x400080
	s_mov_b32 m0, s50
	s_add_i32 s75, s75, 0x600080
	buffer_load_dwordx4 v133, s[16:19], s76 offen lds
	s_mov_b32 m0, s51
	s_nop 0
	buffer_load_dwordx4 v133, s[16:19], s75 offen lds
	s_mov_b32 m0, s48
	s_nop 0
	buffer_load_dwordx4 v132, s[12:15], s74 offen lds
	s_mov_b32 m0, s49
	s_nop 0
	buffer_load_dwordx4 v132, s[12:15], s73 offen lds
	s_waitcnt vmcnt(8)
	s_waitcnt lgkmcnt(0)
	s_setprio 1
	v_mfma_f32_16x16x32_bf16 v[62:65], v[140:143], v[176:179], v[62:65]
	s_barrier
	v_mfma_f32_16x16x32_bf16 v[62:65], v[148:151], v[180:183], v[62:65]
	v_mfma_f32_16x16x32_bf16 v[58:61], v[156:159], v[180:183], v[58:61]
	v_mfma_f32_16x16x32_bf16 v[58:61], v[152:155], v[176:179], v[58:61]
	v_mfma_f32_16x16x32_bf16 v[54:57], v[160:163], v[176:179], v[54:57]
	v_mfma_f32_16x16x32_bf16 v[54:57], v[164:167], v[180:183], v[54:57]
	v_mfma_f32_16x16x32_bf16 v[50:53], v[172:175], v[180:183], v[50:53]
	v_mfma_f32_16x16x32_bf16 v[50:53], v[168:171], v[176:179], v[50:53]
	v_mfma_f32_16x16x32_bf16 v[34:37], v[168:171], v[184:187], v[34:37]
	v_mfma_f32_16x16x32_bf16 v[34:37], v[172:175], v[188:191], v[34:37]
	v_mfma_f32_16x16x32_bf16 v[38:41], v[164:167], v[188:191], v[38:41]
	v_mfma_f32_16x16x32_bf16 v[38:41], v[160:163], v[184:187], v[38:41]
	v_mfma_f32_16x16x32_bf16 v[42:45], v[152:155], v[184:187], v[42:45]
	v_mfma_f32_16x16x32_bf16 v[42:45], v[156:159], v[188:191], v[42:45]
	v_mfma_f32_16x16x32_bf16 v[46:49], v[148:151], v[188:191], v[46:49]
	v_mfma_f32_16x16x32_bf16 v[46:49], v[140:143], v[184:187], v[46:49]
	v_mfma_f32_16x16x32_bf16 v[30:33], v[140:143], v[192:195], v[30:33]
	v_mfma_f32_16x16x32_bf16 v[30:33], v[148:151], v[196:199], v[30:33]
	v_mfma_f32_16x16x32_bf16 v[26:29], v[156:159], v[196:199], v[26:29]
	v_mfma_f32_16x16x32_bf16 v[26:29], v[152:155], v[192:195], v[26:29]
	v_mfma_f32_16x16x32_bf16 v[22:25], v[160:163], v[192:195], v[22:25]
	v_mfma_f32_16x16x32_bf16 v[22:25], v[164:167], v[196:199], v[22:25]
	v_mfma_f32_16x16x32_bf16 v[18:21], v[172:175], v[196:199], v[18:21]
	v_mfma_f32_16x16x32_bf16 v[18:21], v[168:171], v[192:195], v[18:21]
	v_mfma_f32_16x16x32_bf16 v[2:5], v[168:171], v[200:203], v[2:5]
	v_mfma_f32_16x16x32_bf16 v[2:5], v[172:175], v[204:207], v[2:5]
	v_mfma_f32_16x16x32_bf16 v[6:9], v[164:167], v[204:207], v[6:9]
	v_mfma_f32_16x16x32_bf16 v[6:9], v[160:163], v[200:203], v[6:9]
	v_mfma_f32_16x16x32_bf16 v[10:13], v[152:155], v[200:203], v[10:13]
	v_mfma_f32_16x16x32_bf16 v[10:13], v[156:159], v[204:207], v[10:13]
	v_mfma_f32_16x16x32_bf16 v[14:17], v[148:151], v[204:207], v[14:17]
	v_mfma_f32_16x16x32_bf16 v[14:17], v[140:143], v[200:203], v[14:17]
	s_setprio 0
	s_barrier
	s_add_i32 s72, s72, 2
	s_addk_i32 s70, 0x100
	s_addk_i32 s71, 0x100
	s_cmp_ge_i32 s72, s21
	s_cbranch_scc0 .LBB0_1035

.LBB0_1050:
	ds_read_b128 v[132:135], v142
	ds_read_b128 v[136:139], v142 offset:1024
	ds_read_b128 v[148:151], v142 offset:2048
	ds_read_b128 v[152:155], v142 offset:3072
	ds_read_b128 v[156:159], v143
	ds_read_b128 v[160:163], v143 offset:1024
	ds_read_b128 v[164:167], v143 offset:2048
	ds_read_b128 v[168:171], v143 offset:3072
	s_add_i32 s18, s61, 0xfff40080
	s_cmp_eq_u32 s54, s62
	s_cselect_b32 s64, s35, s18
	s_add_i32 s63, s64, 0x80
	s_add_i32 s18, s61, 0xfffc0000
	s_mov_b32 m0, s55
	ds_read_b128 v[172:175], v144
	ds_read_b128 v[176:179], v144 offset:1024
	ds_read_b128 v[180:183], v144 offset:2048
	ds_read_b128 v[184:187], v144 offset:3072
	ds_read_b128 v[188:191], v144 offset:4096
	ds_read_b128 v[192:195], v144 offset:5120
	ds_read_b128 v[196:199], v144 offset:6144
	ds_read_b128 v[200:203], v144 offset:7168
	buffer_load_dwordx4 v140, s[12:15], s18 offen lds
	s_mov_b32 m0, s56
	s_nop 0
	buffer_load_dwordx4 v140, s[12:15], s61 offen lds
	s_waitcnt vmcnt(8)
	s_waitcnt lgkmcnt(0)
	s_setprio 1
	v_mfma_f32_16x16x32_bf16 v[126:129], v[132:135], v[172:175], v[126:129]
	s_barrier
	v_mfma_f32_16x16x32_bf16 v[126:129], v[136:139], v[176:179], v[126:129]
	v_mfma_f32_16x16x32_bf16 v[122:125], v[152:155], v[176:179], v[122:125]
	v_mfma_f32_16x16x32_bf16 v[122:125], v[148:151], v[172:175], v[122:125]
	v_mfma_f32_16x16x32_bf16 v[118:121], v[156:159], v[172:175], v[118:121]
	v_mfma_f32_16x16x32_bf16 v[118:121], v[160:163], v[176:179], v[118:121]
	v_mfma_f32_16x16x32_bf16 v[114:117], v[168:171], v[176:179], v[114:117]
	v_mfma_f32_16x16x32_bf16 v[114:117], v[164:167], v[172:175], v[114:117]
	v_mfma_f32_16x16x32_bf16 v[98:101], v[164:167], v[180:183], v[98:101]
	v_mfma_f32_16x16x32_bf16 v[98:101], v[168:171], v[184:187], v[98:101]
	v_mfma_f32_16x16x32_bf16 v[102:105], v[160:163], v[184:187], v[102:105]
	v_mfma_f32_16x16x32_bf16 v[102:105], v[156:159], v[180:183], v[102:105]
	v_mfma_f32_16x16x32_bf16 v[106:109], v[148:151], v[180:183], v[106:109]
	v_mfma_f32_16x16x32_bf16 v[106:109], v[152:155], v[184:187], v[106:109]
	v_mfma_f32_16x16x32_bf16 v[110:113], v[136:139], v[184:187], v[110:113]
	v_mfma_f32_16x16x32_bf16 v[110:113], v[132:135], v[180:183], v[110:113]
	v_mfma_f32_16x16x32_bf16 v[94:97], v[132:135], v[188:191], v[94:97]
	v_mfma_f32_16x16x32_bf16 v[94:97], v[136:139], v[192:195], v[94:97]
	v_mfma_f32_16x16x32_bf16 v[90:93], v[152:155], v[192:195], v[90:93]
	v_mfma_f32_16x16x32_bf16 v[90:93], v[148:151], v[188:191], v[90:93]
	v_mfma_f32_16x16x32_bf16 v[86:89], v[156:159], v[188:191], v[86:89]
	v_mfma_f32_16x16x32_bf16 v[86:89], v[160:163], v[192:195], v[86:89]
	v_mfma_f32_16x16x32_bf16 v[82:85], v[168:171], v[192:195], v[82:85]
	v_mfma_f32_16x16x32_bf16 v[82:85], v[164:167], v[188:191], v[82:85]
	v_mfma_f32_16x16x32_bf16 v[66:69], v[164:167], v[196:199], v[66:69]
	v_mfma_f32_16x16x32_bf16 v[66:69], v[168:171], v[200:203], v[66:69]
	v_mfma_f32_16x16x32_bf16 v[70:73], v[160:163], v[200:203], v[70:73]
	v_mfma_f32_16x16x32_bf16 v[70:73], v[156:159], v[196:199], v[70:73]
	v_mfma_f32_16x16x32_bf16 v[74:77], v[148:151], v[196:199], v[74:77]
	v_mfma_f32_16x16x32_bf16 v[74:77], v[152:155], v[200:203], v[74:77]
	v_mfma_f32_16x16x32_bf16 v[78:81], v[136:139], v[200:203], v[78:81]
	v_mfma_f32_16x16x32_bf16 v[78:81], v[132:135], v[196:199], v[78:81]
	s_setprio 0
	s_barrier
	s_mov_b32 m0, s25
	s_mov_b32 s18, s14
	s_mov_b32 s19, s15
	ds_read_b128 v[172:175], v144 offset:16384
	ds_read_b128 v[176:179], v144 offset:17408
	ds_read_b128 v[180:183], v144 offset:18432
	ds_read_b128 v[184:187], v144 offset:19456
	ds_read_b128 v[188:191], v144 offset:20480
	ds_read_b128 v[192:195], v144 offset:21504
	ds_read_b128 v[196:199], v144 offset:22528
	ds_read_b128 v[200:203], v144 offset:23552
	buffer_load_dwordx4 v141, s[16:19], s64 offen lds
	s_add_i32 s65, s64, 0x40000
	s_mov_b32 m0, s27
	s_add_i32 s66, s64, 0x80000
	buffer_load_dwordx4 v141, s[16:19], s65 offen lds
	s_mov_b32 m0, s30
	s_add_i32 s67, s64, 0xc0000
	buffer_load_dwordx4 v141, s[16:19], s66 offen lds
	s_mov_b32 m0, s31
	s_nop 0
	buffer_load_dwordx4 v141, s[16:19], s67 offen lds
	s_mov_b32 m0, s21
	s_nop 0
	buffer_load_dwordx4 v140, s[12:15], s64 offen lds
	s_mov_b32 m0, s38
	s_nop 0
	buffer_load_dwordx4 v140, s[12:15], s65 offen lds
	s_waitcnt vmcnt(8)
	s_waitcnt lgkmcnt(0)
	s_setprio 1
	v_mfma_f32_16x16x32_bf16 v[62:65], v[132:135], v[172:175], v[62:65]
	s_barrier
	v_mfma_f32_16x16x32_bf16 v[62:65], v[136:139], v[176:179], v[62:65]
	v_mfma_f32_16x16x32_bf16 v[58:61], v[152:155], v[176:179], v[58:61]
	v_mfma_f32_16x16x32_bf16 v[58:61], v[148:151], v[172:175], v[58:61]
	v_mfma_f32_16x16x32_bf16 v[54:57], v[156:159], v[172:175], v[54:57]
	v_mfma_f32_16x16x32_bf16 v[54:57], v[160:163], v[176:179], v[54:57]
	v_mfma_f32_16x16x32_bf16 v[50:53], v[168:171], v[176:179], v[50:53]
	v_mfma_f32_16x16x32_bf16 v[50:53], v[164:167], v[172:175], v[50:53]
	v_mfma_f32_16x16x32_bf16 v[34:37], v[164:167], v[180:183], v[34:37]
	v_mfma_f32_16x16x32_bf16 v[34:37], v[168:171], v[184:187], v[34:37]
	v_mfma_f32_16x16x32_bf16 v[38:41], v[160:163], v[184:187], v[38:41]
	v_mfma_f32_16x16x32_bf16 v[38:41], v[156:159], v[180:183], v[38:41]
	v_mfma_f32_16x16x32_bf16 v[42:45], v[148:151], v[180:183], v[42:45]
	v_mfma_f32_16x16x32_bf16 v[42:45], v[152:155], v[184:187], v[42:45]
	v_mfma_f32_16x16x32_bf16 v[46:49], v[136:139], v[184:187], v[46:49]
	v_mfma_f32_16x16x32_bf16 v[46:49], v[132:135], v[180:183], v[46:49]
	v_mfma_f32_16x16x32_bf16 v[30:33], v[132:135], v[188:191], v[30:33]
	v_mfma_f32_16x16x32_bf16 v[30:33], v[136:139], v[192:195], v[30:33]
	v_mfma_f32_16x16x32_bf16 v[26:29], v[152:155], v[192:195], v[26:29]
	v_mfma_f32_16x16x32_bf16 v[26:29], v[148:151], v[188:191], v[26:29]
	v_mfma_f32_16x16x32_bf16 v[22:25], v[156:159], v[188:191], v[22:25]
	v_mfma_f32_16x16x32_bf16 v[22:25], v[160:163], v[192:195], v[22:25]
	v_mfma_f32_16x16x32_bf16 v[18:21], v[168:171], v[192:195], v[18:21]
	v_mfma_f32_16x16x32_bf16 v[18:21], v[164:167], v[188:191], v[18:21]
	v_mfma_f32_16x16x32_bf16 v[2:5], v[164:167], v[196:199], v[2:5]
	v_mfma_f32_16x16x32_bf16 v[2:5], v[168:171], v[200:203], v[2:5]
	v_mfma_f32_16x16x32_bf16 v[6:9], v[160:163], v[200:203], v[6:9]
	v_mfma_f32_16x16x32_bf16 v[6:9], v[156:159], v[196:199], v[6:9]
	v_mfma_f32_16x16x32_bf16 v[10:13], v[148:151], v[196:199], v[10:13]
	v_mfma_f32_16x16x32_bf16 v[10:13], v[152:155], v[200:203], v[10:13]
	v_mfma_f32_16x16x32_bf16 v[14:17], v[136:139], v[200:203], v[14:17]
	v_mfma_f32_16x16x32_bf16 v[14:17], v[132:135], v[196:199], v[14:17]
	s_setprio 0
	s_barrier
	ds_read_b128 v[132:135], v145
	ds_read_b128 v[136:139], v145 offset:1024
	ds_read_b128 v[148:151], v145 offset:2048
	ds_read_b128 v[152:155], v145 offset:3072
	ds_read_b128 v[156:159], v147
	ds_read_b128 v[160:163], v147 offset:1024
	ds_read_b128 v[164:167], v147 offset:2048
	ds_read_b128 v[168:171], v147 offset:3072
	s_mov_b32 m0, s39
	ds_read_b128 v[172:175], v144 offset:32768
	ds_read_b128 v[176:179], v144 offset:33792
	ds_read_b128 v[180:183], v144 offset:34816
	ds_read_b128 v[184:187], v144 offset:35840
	ds_read_b128 v[188:191], v144 offset:36864
	ds_read_b128 v[192:195], v144 offset:37888
	ds_read_b128 v[196:199], v144 offset:38912
	ds_read_b128 v[200:203], v144 offset:39936
	buffer_load_dwordx4 v140, s[12:15], s66 offen lds
	s_mov_b32 m0, s40
	s_nop 0
	buffer_load_dwordx4 v140, s[12:15], s67 offen lds
	s_waitcnt vmcnt(8)
	s_waitcnt lgkmcnt(0)
	s_setprio 1
	v_mfma_f32_16x16x32_bf16 v[126:129], v[132:135], v[172:175], v[126:129]
	s_barrier
	v_mfma_f32_16x16x32_bf16 v[126:129], v[136:139], v[176:179], v[126:129]
	v_mfma_f32_16x16x32_bf16 v[122:125], v[152:155], v[176:179], v[122:125]
	v_mfma_f32_16x16x32_bf16 v[122:125], v[148:151], v[172:175], v[122:125]
	v_mfma_f32_16x16x32_bf16 v[118:121], v[156:159], v[172:175], v[118:121]
	v_mfma_f32_16x16x32_bf16 v[118:121], v[160:163], v[176:179], v[118:121]
	v_mfma_f32_16x16x32_bf16 v[114:117], v[168:171], v[176:179], v[114:117]
	v_mfma_f32_16x16x32_bf16 v[114:117], v[164:167], v[172:175], v[114:117]
	v_mfma_f32_16x16x32_bf16 v[98:101], v[164:167], v[180:183], v[98:101]
	v_mfma_f32_16x16x32_bf16 v[98:101], v[168:171], v[184:187], v[98:101]
	v_mfma_f32_16x16x32_bf16 v[102:105], v[160:163], v[184:187], v[102:105]
	v_mfma_f32_16x16x32_bf16 v[102:105], v[156:159], v[180:183], v[102:105]
	v_mfma_f32_16x16x32_bf16 v[106:109], v[148:151], v[180:183], v[106:109]
	v_mfma_f32_16x16x32_bf16 v[106:109], v[152:155], v[184:187], v[106:109]
	v_mfma_f32_16x16x32_bf16 v[110:113], v[136:139], v[184:187], v[110:113]
	v_mfma_f32_16x16x32_bf16 v[110:113], v[132:135], v[180:183], v[110:113]
	v_mfma_f32_16x16x32_bf16 v[94:97], v[132:135], v[188:191], v[94:97]
	v_mfma_f32_16x16x32_bf16 v[94:97], v[136:139], v[192:195], v[94:97]
	v_mfma_f32_16x16x32_bf16 v[90:93], v[152:155], v[192:195], v[90:93]
	v_mfma_f32_16x16x32_bf16 v[90:93], v[148:151], v[188:191], v[90:93]
	v_mfma_f32_16x16x32_bf16 v[86:89], v[156:159], v[188:191], v[86:89]
	v_mfma_f32_16x16x32_bf16 v[86:89], v[160:163], v[192:195], v[86:89]
	v_mfma_f32_16x16x32_bf16 v[82:85], v[168:171], v[192:195], v[82:85]
	v_mfma_f32_16x16x32_bf16 v[82:85], v[164:167], v[188:191], v[82:85]
	v_mfma_f32_16x16x32_bf16 v[66:69], v[164:167], v[196:199], v[66:69]
	v_mfma_f32_16x16x32_bf16 v[66:69], v[168:171], v[200:203], v[66:69]
	v_mfma_f32_16x16x32_bf16 v[70:73], v[160:163], v[200:203], v[70:73]
	v_mfma_f32_16x16x32_bf16 v[70:73], v[156:159], v[196:199], v[70:73]
	v_mfma_f32_16x16x32_bf16 v[74:77], v[148:151], v[196:199], v[74:77]
	v_mfma_f32_16x16x32_bf16 v[74:77], v[152:155], v[200:203], v[74:77]
	v_mfma_f32_16x16x32_bf16 v[78:81], v[136:139], v[200:203], v[78:81]
	v_mfma_f32_16x16x32_bf16 v[78:81], v[132:135], v[196:199], v[78:81]
	s_setprio 0
	s_barrier
	s_mov_b32 m0, s48
	ds_read_b128 v[172:175], v144 offset:49152
	ds_read_b128 v[176:179], v144 offset:50176
	ds_read_b128 v[180:183], v144 offset:51200
	ds_read_b128 v[184:187], v144 offset:52224
	ds_read_b128 v[188:191], v144 offset:53248
	ds_read_b128 v[192:195], v144 offset:54272
	ds_read_b128 v[196:199], v144 offset:55296
	ds_read_b128 v[200:203], v144 offset:56320
	buffer_load_dwordx4 v141, s[16:19], s63 offen lds
	s_add_i32 s65, s64, 0x40080
	s_mov_b32 m0, s49
	s_add_i32 s66, s64, 0x80080
	buffer_load_dwordx4 v141, s[16:19], s65 offen lds
	s_mov_b32 m0, s52
	s_add_i32 s64, s64, 0xc0080
	buffer_load_dwordx4 v141, s[16:19], s66 offen lds
	s_mov_b32 m0, s53
	s_nop 0
	buffer_load_dwordx4 v141, s[16:19], s64 offen lds
	s_mov_b32 m0, s50
	s_nop 0
	buffer_load_dwordx4 v140, s[12:15], s63 offen lds
	s_mov_b32 m0, s51
	s_nop 0
	buffer_load_dwordx4 v140, s[12:15], s65 offen lds
	s_waitcnt vmcnt(8)
	s_waitcnt lgkmcnt(0)
	s_setprio 1
	v_mfma_f32_16x16x32_bf16 v[62:65], v[132:135], v[172:175], v[62:65]
	s_barrier
	v_mfma_f32_16x16x32_bf16 v[62:65], v[136:139], v[176:179], v[62:65]
	v_mfma_f32_16x16x32_bf16 v[58:61], v[152:155], v[176:179], v[58:61]
	v_mfma_f32_16x16x32_bf16 v[58:61], v[148:151], v[172:175], v[58:61]
	v_mfma_f32_16x16x32_bf16 v[54:57], v[156:159], v[172:175], v[54:57]
	v_mfma_f32_16x16x32_bf16 v[54:57], v[160:163], v[176:179], v[54:57]
	v_mfma_f32_16x16x32_bf16 v[50:53], v[168:171], v[176:179], v[50:53]
	v_mfma_f32_16x16x32_bf16 v[50:53], v[164:167], v[172:175], v[50:53]
	v_mfma_f32_16x16x32_bf16 v[34:37], v[164:167], v[180:183], v[34:37]
	v_mfma_f32_16x16x32_bf16 v[34:37], v[168:171], v[184:187], v[34:37]
	v_mfma_f32_16x16x32_bf16 v[38:41], v[160:163], v[184:187], v[38:41]
	v_mfma_f32_16x16x32_bf16 v[38:41], v[156:159], v[180:183], v[38:41]
	v_mfma_f32_16x16x32_bf16 v[42:45], v[148:151], v[180:183], v[42:45]
	v_mfma_f32_16x16x32_bf16 v[42:45], v[152:155], v[184:187], v[42:45]
	v_mfma_f32_16x16x32_bf16 v[46:49], v[136:139], v[184:187], v[46:49]
	v_mfma_f32_16x16x32_bf16 v[46:49], v[132:135], v[180:183], v[46:49]
	v_mfma_f32_16x16x32_bf16 v[30:33], v[132:135], v[188:191], v[30:33]
	v_mfma_f32_16x16x32_bf16 v[30:33], v[136:139], v[192:195], v[30:33]
	v_mfma_f32_16x16x32_bf16 v[26:29], v[152:155], v[192:195], v[26:29]
	v_mfma_f32_16x16x32_bf16 v[26:29], v[148:151], v[188:191], v[26:29]
	v_mfma_f32_16x16x32_bf16 v[22:25], v[156:159], v[188:191], v[22:25]
	v_mfma_f32_16x16x32_bf16 v[22:25], v[160:163], v[192:195], v[22:25]
	v_mfma_f32_16x16x32_bf16 v[18:21], v[168:171], v[192:195], v[18:21]
	v_mfma_f32_16x16x32_bf16 v[18:21], v[164:167], v[188:191], v[18:21]
	v_mfma_f32_16x16x32_bf16 v[2:5], v[164:167], v[196:199], v[2:5]
	v_mfma_f32_16x16x32_bf16 v[2:5], v[168:171], v[200:203], v[2:5]
	v_mfma_f32_16x16x32_bf16 v[6:9], v[160:163], v[200:203], v[6:9]
	v_mfma_f32_16x16x32_bf16 v[6:9], v[156:159], v[196:199], v[6:9]
	v_mfma_f32_16x16x32_bf16 v[10:13], v[148:151], v[196:199], v[10:13]
	v_mfma_f32_16x16x32_bf16 v[10:13], v[152:155], v[200:203], v[10:13]
	v_mfma_f32_16x16x32_bf16 v[14:17], v[136:139], v[200:203], v[14:17]
	v_mfma_f32_16x16x32_bf16 v[14:17], v[132:135], v[196:199], v[14:17]
	s_setprio 0
	s_barrier
	s_add_i32 s62, s62, 2
	s_addk_i32 s61, 0x100
	s_cmp_ge_i32 s62, s3
	s_cbranch_scc0 .LBB0_1050

.LBB0_1181:
	v_add_u32_e32 v2, 0x10000, v232
	ds_read_b128 v[134:137], v2
	ds_read_b128 v[138:141], v2 offset:1024
	ds_read_b128 v[142:145], v2 offset:2048
	ds_read_b128 v[146:149], v2 offset:3072
	v_add_u32_e32 v2, 0x14000, v232
	ds_read_b128 v[150:153], v2
	ds_read_b128 v[154:157], v2 offset:1024
	ds_read_b128 v[158:161], v2 offset:2048
	ds_read_b128 v[162:165], v2 offset:3072
	s_add_i32 s50, s47, s90
	s_and_b64 s[18:19], exec, s[18:19]
	s_cselect_b32 s51, s88, s50
	s_add_i32 s50, s92, 0x80
	s_or_b32 s52, s51, 0x80
	s_add_i32 s18, s89, s93
	s_add_i32 s94, s94, 0x1bfffc80
	s_cmp_lt_u32 s91, 8
	s_cselect_b32 s18, s18, s94
	s_mov_b32 m0, s74
	s_add_i32 s19, s18, 0x80000
	ds_read_b128 v[166:169], v233
	ds_read_b128 v[170:173], v233 offset:1024
	ds_read_b128 v[174:177], v233 offset:2048
	ds_read_b128 v[178:181], v233 offset:3072
	ds_read_b128 v[182:185], v233 offset:4096
	ds_read_b128 v[186:189], v233 offset:5120
	ds_read_b128 v[190:193], v233 offset:6144
	ds_read_b128 v[194:197], v233 offset:7168
	buffer_load_dwordx4 v230, s[12:15], s19 offen lds
	s_add_i32 s18, s18, 0xc0000
	s_mov_b32 m0, s75
	s_nop 0
	buffer_load_dwordx4 v230, s[12:15], s18 offen lds
	s_waitcnt vmcnt(8)
	s_waitcnt lgkmcnt(0)
	s_setprio 1
	v_mfma_f32_16x16x32_bf16 v[130:133], v[134:137], v[166:169], v[130:133]
	s_barrier
	v_mfma_f32_16x16x32_bf16 v[130:133], v[138:141], v[170:173], v[130:133]
	v_mfma_f32_16x16x32_bf16 v[126:129], v[146:149], v[170:173], v[126:129]
	v_mfma_f32_16x16x32_bf16 v[126:129], v[142:145], v[166:169], v[126:129]
	v_mfma_f32_16x16x32_bf16 v[122:125], v[150:153], v[166:169], v[122:125]
	v_mfma_f32_16x16x32_bf16 v[122:125], v[154:157], v[170:173], v[122:125]
	v_mfma_f32_16x16x32_bf16 v[118:121], v[162:165], v[170:173], v[118:121]
	v_mfma_f32_16x16x32_bf16 v[118:121], v[158:161], v[166:169], v[118:121]
	v_mfma_f32_16x16x32_bf16 v[102:105], v[158:161], v[174:177], v[102:105]
	v_mfma_f32_16x16x32_bf16 v[102:105], v[162:165], v[178:181], v[102:105]
	v_mfma_f32_16x16x32_bf16 v[106:109], v[154:157], v[178:181], v[106:109]
	v_mfma_f32_16x16x32_bf16 v[106:109], v[150:153], v[174:177], v[106:109]
	v_mfma_f32_16x16x32_bf16 v[110:113], v[142:145], v[174:177], v[110:113]
	v_mfma_f32_16x16x32_bf16 v[110:113], v[146:149], v[178:181], v[110:113]
	v_mfma_f32_16x16x32_bf16 v[114:117], v[138:141], v[178:181], v[114:117]
	v_mfma_f32_16x16x32_bf16 v[114:117], v[134:137], v[174:177], v[114:117]
	v_mfma_f32_16x16x32_bf16 v[98:101], v[134:137], v[182:185], v[98:101]
	v_mfma_f32_16x16x32_bf16 v[98:101], v[138:141], v[186:189], v[98:101]
	v_mfma_f32_16x16x32_bf16 v[94:97], v[146:149], v[186:189], v[94:97]
	v_mfma_f32_16x16x32_bf16 v[94:97], v[142:145], v[182:185], v[94:97]
	v_mfma_f32_16x16x32_bf16 v[90:93], v[150:153], v[182:185], v[90:93]
	v_mfma_f32_16x16x32_bf16 v[90:93], v[154:157], v[186:189], v[90:93]
	v_mfma_f32_16x16x32_bf16 v[86:89], v[162:165], v[186:189], v[86:89]
	v_mfma_f32_16x16x32_bf16 v[86:89], v[158:161], v[182:185], v[86:89]
	v_mfma_f32_16x16x32_bf16 v[70:73], v[158:161], v[190:193], v[70:73]
	v_mfma_f32_16x16x32_bf16 v[70:73], v[162:165], v[194:197], v[70:73]
	v_mfma_f32_16x16x32_bf16 v[74:77], v[154:157], v[194:197], v[74:77]
	v_mfma_f32_16x16x32_bf16 v[74:77], v[150:153], v[190:193], v[74:77]
	v_mfma_f32_16x16x32_bf16 v[78:81], v[142:145], v[190:193], v[78:81]
	v_mfma_f32_16x16x32_bf16 v[78:81], v[146:149], v[194:197], v[78:81]
	v_mfma_f32_16x16x32_bf16 v[82:85], v[138:141], v[194:197], v[82:85]
	v_mfma_f32_16x16x32_bf16 v[82:85], v[134:137], v[190:193], v[82:85]
	s_setprio 0
	s_barrier
	s_mov_b32 m0, s27
	s_mov_b32 s18, s14
	s_mov_b32 s19, s15
	ds_read_b128 v[166:169], v233 offset:16384
	ds_read_b128 v[170:173], v233 offset:17408
	ds_read_b128 v[174:177], v233 offset:18432
	ds_read_b128 v[178:181], v233 offset:19456
	ds_read_b128 v[182:185], v233 offset:20480
	ds_read_b128 v[186:189], v233 offset:21504
	ds_read_b128 v[190:193], v233 offset:22528
	ds_read_b128 v[194:197], v233 offset:23552
	buffer_load_dwordx4 v231, s[16:19], s51 offen lds
	s_add_i32 s53, s51, 0x18000
	s_mov_b32 m0, s30
	s_nop 0
	buffer_load_dwordx4 v231, s[16:19], s53 offen lds
	s_add_i32 s53, s51, 0x30000
	s_mov_b32 m0, s31
	s_nop 0
	buffer_load_dwordx4 v231, s[16:19], s53 offen lds
	s_add_i32 s53, s51, 0x48000
	s_mov_b32 m0, s54
	s_nop 0
	buffer_load_dwordx4 v231, s[16:19], s53 offen lds
	s_mov_b32 m0, s25
	s_add_i32 s53, s92, 0x40000
	buffer_load_dwordx4 v230, s[12:15], s92 offen lds
	s_mov_b32 m0, s55
	s_nop 0
	buffer_load_dwordx4 v230, s[12:15], s53 offen lds
	s_waitcnt vmcnt(8)
	s_waitcnt lgkmcnt(0)
	s_setprio 1
	v_mfma_f32_16x16x32_bf16 v[66:69], v[134:137], v[166:169], v[66:69]
	s_barrier
	v_mfma_f32_16x16x32_bf16 v[62:65], v[142:145], v[166:169], v[62:65]
	v_mfma_f32_16x16x32_bf16 v[50:53], v[134:137], v[174:177], v[50:53]
	v_mfma_f32_16x16x32_bf16 v[46:49], v[142:145], v[174:177], v[46:49]
	v_mfma_f32_16x16x32_bf16 v[34:37], v[134:137], v[182:185], v[34:37]
	v_mfma_f32_16x16x32_bf16 v[30:33], v[142:145], v[182:185], v[30:33]
	v_mfma_f32_16x16x32_bf16 v[18:21], v[134:137], v[190:193], v[18:21]
	v_mfma_f32_16x16x32_bf16 v[14:17], v[142:145], v[190:193], v[14:17]
	v_mfma_f32_16x16x32_bf16 v[58:61], v[150:153], v[166:169], v[58:61]
	v_mfma_f32_16x16x32_bf16 v[54:57], v[158:161], v[166:169], v[54:57]
	v_mfma_f32_16x16x32_bf16 v[42:45], v[150:153], v[174:177], v[42:45]
	v_mfma_f32_16x16x32_bf16 v[38:41], v[158:161], v[174:177], v[38:41]
	v_mfma_f32_16x16x32_bf16 v[26:29], v[150:153], v[182:185], v[26:29]
	v_mfma_f32_16x16x32_bf16 v[22:25], v[158:161], v[182:185], v[22:25]
	v_mfma_f32_16x16x32_bf16 v[10:13], v[150:153], v[190:193], v[10:13]
	v_mfma_f32_16x16x32_bf16 v[4:7], v[158:161], v[190:193], v[6:9]
	v_mfma_f32_16x16x32_bf16 v[66:69], v[138:141], v[170:173], v[66:69]
	v_mfma_f32_16x16x32_bf16 v[62:65], v[146:149], v[170:173], v[62:65]
	v_mfma_f32_16x16x32_bf16 v[50:53], v[138:141], v[178:181], v[50:53]
	v_mfma_f32_16x16x32_bf16 v[46:49], v[146:149], v[178:181], v[46:49]
	v_mfma_f32_16x16x32_bf16 v[34:37], v[138:141], v[186:189], v[34:37]
	v_mfma_f32_16x16x32_bf16 v[30:33], v[146:149], v[186:189], v[30:33]
	v_mfma_f32_16x16x32_bf16 v[18:21], v[138:141], v[194:197], v[18:21]
	v_mfma_f32_16x16x32_bf16 v[14:17], v[146:149], v[194:197], v[14:17]
	v_mfma_f32_16x16x32_bf16 v[58:61], v[154:157], v[170:173], v[58:61]
	v_mfma_f32_16x16x32_bf16 v[54:57], v[162:165], v[170:173], v[54:57]
	v_mfma_f32_16x16x32_bf16 v[42:45], v[154:157], v[178:181], v[42:45]
	v_mfma_f32_16x16x32_bf16 v[38:41], v[162:165], v[178:181], v[38:41]
	v_mfma_f32_16x16x32_bf16 v[26:29], v[154:157], v[186:189], v[26:29]
	v_mfma_f32_16x16x32_bf16 v[22:25], v[162:165], v[186:189], v[22:25]
	v_mfma_f32_16x16x32_bf16 v[10:13], v[154:157], v[194:197], v[10:13]
	v_mfma_f32_16x16x32_bf16 v[4:7], v[162:165], v[194:197], v[4:7]
	s_setprio 0
	s_barrier
	v_add_u32_e32 v2, 0x18000, v232
	ds_read_b128 v[134:137], v2
	ds_read_b128 v[138:141], v2 offset:1024
	ds_read_b128 v[142:145], v2 offset:2048
	ds_read_b128 v[146:149], v2 offset:3072
	v_add_u32_e32 v2, 0x1c000, v232
	ds_read_b128 v[150:153], v2
	ds_read_b128 v[154:157], v2 offset:1024
	ds_read_b128 v[158:161], v2 offset:2048
	ds_read_b128 v[162:165], v2 offset:3072
	s_mov_b32 m0, s56
	s_add_i32 s53, s92, 0x80000
	ds_read_b128 v[166:169], v233 offset:32768
	ds_read_b128 v[170:173], v233 offset:33792
	ds_read_b128 v[174:177], v233 offset:34816
	ds_read_b128 v[178:181], v233 offset:35840
	ds_read_b128 v[182:185], v233 offset:36864
	ds_read_b128 v[186:189], v233 offset:37888
	ds_read_b128 v[190:193], v233 offset:38912
	ds_read_b128 v[194:197], v233 offset:39936
	buffer_load_dwordx4 v230, s[12:15], s53 offen lds
	s_add_i32 s53, s92, 0xc0000
	s_mov_b32 m0, s57
	s_nop 0
	buffer_load_dwordx4 v230, s[12:15], s53 offen lds
	s_waitcnt vmcnt(8)
	s_waitcnt lgkmcnt(0)
	s_setprio 1
	v_mfma_f32_16x16x32_bf16 v[130:133], v[134:137], v[166:169], v[130:133]
	s_barrier
	v_mfma_f32_16x16x32_bf16 v[130:133], v[138:141], v[170:173], v[130:133]
	v_mfma_f32_16x16x32_bf16 v[126:129], v[146:149], v[170:173], v[126:129]
	v_mfma_f32_16x16x32_bf16 v[126:129], v[142:145], v[166:169], v[126:129]
	v_mfma_f32_16x16x32_bf16 v[122:125], v[150:153], v[166:169], v[122:125]
	v_mfma_f32_16x16x32_bf16 v[122:125], v[154:157], v[170:173], v[122:125]
	v_mfma_f32_16x16x32_bf16 v[118:121], v[162:165], v[170:173], v[118:121]
	v_mfma_f32_16x16x32_bf16 v[118:121], v[158:161], v[166:169], v[118:121]
	v_mfma_f32_16x16x32_bf16 v[102:105], v[158:161], v[174:177], v[102:105]
	v_mfma_f32_16x16x32_bf16 v[102:105], v[162:165], v[178:181], v[102:105]
	v_mfma_f32_16x16x32_bf16 v[106:109], v[154:157], v[178:181], v[106:109]
	v_mfma_f32_16x16x32_bf16 v[106:109], v[150:153], v[174:177], v[106:109]
	v_mfma_f32_16x16x32_bf16 v[110:113], v[142:145], v[174:177], v[110:113]
	v_mfma_f32_16x16x32_bf16 v[110:113], v[146:149], v[178:181], v[110:113]
	v_mfma_f32_16x16x32_bf16 v[114:117], v[138:141], v[178:181], v[114:117]
	v_mfma_f32_16x16x32_bf16 v[114:117], v[134:137], v[174:177], v[114:117]
	v_mfma_f32_16x16x32_bf16 v[98:101], v[134:137], v[182:185], v[98:101]
	v_mfma_f32_16x16x32_bf16 v[98:101], v[138:141], v[186:189], v[98:101]
	v_mfma_f32_16x16x32_bf16 v[94:97], v[146:149], v[186:189], v[94:97]
	v_mfma_f32_16x16x32_bf16 v[94:97], v[142:145], v[182:185], v[94:97]
	v_mfma_f32_16x16x32_bf16 v[90:93], v[150:153], v[182:185], v[90:93]
	v_mfma_f32_16x16x32_bf16 v[90:93], v[154:157], v[186:189], v[90:93]
	v_mfma_f32_16x16x32_bf16 v[86:89], v[162:165], v[186:189], v[86:89]
	v_mfma_f32_16x16x32_bf16 v[86:89], v[158:161], v[182:185], v[86:89]
	v_mfma_f32_16x16x32_bf16 v[70:73], v[158:161], v[190:193], v[70:73]
	v_mfma_f32_16x16x32_bf16 v[70:73], v[162:165], v[194:197], v[70:73]
	v_mfma_f32_16x16x32_bf16 v[74:77], v[154:157], v[194:197], v[74:77]
	v_mfma_f32_16x16x32_bf16 v[74:77], v[150:153], v[190:193], v[74:77]
	v_mfma_f32_16x16x32_bf16 v[78:81], v[142:145], v[190:193], v[78:81]
	v_mfma_f32_16x16x32_bf16 v[78:81], v[146:149], v[194:197], v[78:81]
	v_mfma_f32_16x16x32_bf16 v[82:85], v[138:141], v[194:197], v[82:85]
	v_mfma_f32_16x16x32_bf16 v[82:85], v[134:137], v[190:193], v[82:85]
	s_setprio 0
	s_barrier
	s_mov_b32 m0, s64
	ds_read_b128 v[166:169], v233 offset:49152
	ds_read_b128 v[170:173], v233 offset:50176
	ds_read_b128 v[174:177], v233 offset:51200
	ds_read_b128 v[178:181], v233 offset:52224
	ds_read_b128 v[182:185], v233 offset:53248
	ds_read_b128 v[186:189], v233 offset:54272
	ds_read_b128 v[190:193], v233 offset:55296
	ds_read_b128 v[194:197], v233 offset:56320
	buffer_load_dwordx4 v231, s[16:19], s52 offen lds
	s_add_i32 s52, s51, 0x18080
	s_mov_b32 m0, s65
	s_nop 0
	buffer_load_dwordx4 v231, s[16:19], s52 offen lds
	s_add_i32 s52, s51, 0x30080
	s_mov_b32 m0, s68
	s_add_i32 s51, s51, 0x48080
	buffer_load_dwordx4 v231, s[16:19], s52 offen lds
	s_mov_b32 m0, s69
	s_nop 0
	buffer_load_dwordx4 v231, s[16:19], s51 offen lds
	s_mov_b32 m0, s66
	s_add_i32 s18, s92, 0x40080
	buffer_load_dwordx4 v230, s[12:15], s50 offen lds
	s_mov_b32 m0, s67
	s_nop 0
	buffer_load_dwordx4 v230, s[12:15], s18 offen lds
	s_waitcnt vmcnt(8)
	s_waitcnt lgkmcnt(0)
	s_setprio 1
	v_mfma_f32_16x16x32_bf16 v[66:69], v[134:137], v[166:169], v[66:69]
	s_barrier
	v_mfma_f32_16x16x32_bf16 v[62:65], v[142:145], v[166:169], v[62:65]
	v_mfma_f32_16x16x32_bf16 v[50:53], v[134:137], v[174:177], v[50:53]
	v_mfma_f32_16x16x32_bf16 v[46:49], v[142:145], v[174:177], v[46:49]
	v_mfma_f32_16x16x32_bf16 v[34:37], v[134:137], v[182:185], v[34:37]
	v_mfma_f32_16x16x32_bf16 v[30:33], v[142:145], v[182:185], v[30:33]
	v_mfma_f32_16x16x32_bf16 v[18:21], v[134:137], v[190:193], v[18:21]
	v_mfma_f32_16x16x32_bf16 v[14:17], v[142:145], v[190:193], v[14:17]
	v_mfma_f32_16x16x32_bf16 v[58:61], v[150:153], v[166:169], v[58:61]
	v_mfma_f32_16x16x32_bf16 v[54:57], v[158:161], v[166:169], v[54:57]
	v_mfma_f32_16x16x32_bf16 v[42:45], v[150:153], v[174:177], v[42:45]
	v_mfma_f32_16x16x32_bf16 v[38:41], v[158:161], v[174:177], v[38:41]
	v_mfma_f32_16x16x32_bf16 v[26:29], v[150:153], v[182:185], v[26:29]
	v_mfma_f32_16x16x32_bf16 v[22:25], v[158:161], v[182:185], v[22:25]
	v_mfma_f32_16x16x32_bf16 v[8:11], v[150:153], v[190:193], v[10:13]
	v_mfma_f32_16x16x32_bf16 v[4:7], v[158:161], v[190:193], v[4:7]
	v_mfma_f32_16x16x32_bf16 v[66:69], v[138:141], v[170:173], v[66:69]
	v_mfma_f32_16x16x32_bf16 v[62:65], v[146:149], v[170:173], v[62:65]
	v_mfma_f32_16x16x32_bf16 v[50:53], v[138:141], v[178:181], v[50:53]
	v_mfma_f32_16x16x32_bf16 v[46:49], v[146:149], v[178:181], v[46:49]
	v_mfma_f32_16x16x32_bf16 v[34:37], v[138:141], v[186:189], v[34:37]
	v_mfma_f32_16x16x32_bf16 v[30:33], v[146:149], v[186:189], v[30:33]
	v_mfma_f32_16x16x32_bf16 v[18:21], v[138:141], v[194:197], v[18:21]
	v_mfma_f32_16x16x32_bf16 v[14:17], v[146:149], v[194:197], v[14:17]
	v_mfma_f32_16x16x32_bf16 v[58:61], v[154:157], v[170:173], v[58:61]
	v_mfma_f32_16x16x32_bf16 v[54:57], v[162:165], v[170:173], v[54:57]
	v_mfma_f32_16x16x32_bf16 v[42:45], v[154:157], v[178:181], v[42:45]
	v_mfma_f32_16x16x32_bf16 v[38:41], v[162:165], v[178:181], v[38:41]
	v_mfma_f32_16x16x32_bf16 v[26:29], v[154:157], v[186:189], v[26:29]
	v_mfma_f32_16x16x32_bf16 v[22:25], v[162:165], v[186:189], v[22:25]
	v_mfma_f32_16x16x32_bf16 v[10:13], v[154:157], v[194:197], v[8:11]
	v_mfma_f32_16x16x32_bf16 v[6:9], v[162:165], v[194:197], v[4:7]
	s_setprio 0
	s_barrier
	s_add_i32 s91, s91, 2
	s_addk_i32 s90, 0x100
	s_cmp_ge_i32 s91, s3
	s_cbranch_scc1 .LBB0_1193

.LBB0_1290:
	ds_read_b128 v[106:109], v224
	ds_read_b128 v[118:121], v224 offset:1024
	ds_read_b128 v[130:133], v224 offset:2048
	ds_read_b128 v[138:141], v224 offset:3072
	ds_read_b128 v[146:149], v225
	ds_read_b128 v[150:153], v225 offset:1024
	ds_read_b128 v[154:157], v225 offset:2048
	ds_read_b128 v[158:161], v225 offset:3072
	s_add_i32 s18, s72, 0xffe80080
	s_cmp_eq_u32 s56, s74
	s_cselect_b32 s75, s6, s18
	s_cselect_b32 s77, s7, s73
	s_or_b32 s76, s75, 0x80
	s_add_i32 s18, s72, 0xfff80000
	s_mov_b32 m0, s57
	ds_read_b128 v[162:165], v226
	ds_read_b128 v[166:169], v226 offset:1024
	ds_read_b128 v[170:173], v226 offset:2048
	ds_read_b128 v[174:177], v226 offset:3072
	ds_read_b128 v[178:181], v226 offset:4096
	ds_read_b128 v[182:185], v226 offset:5120
	ds_read_b128 v[190:193], v226 offset:6144
	ds_read_b128 v[194:197], v226 offset:7168
	buffer_load_dwordx4 v222, s[12:15], s18 offen lds
	s_mov_b32 m0, s60
	s_nop 0
	buffer_load_dwordx4 v222, s[12:15], s72 offen lds
	s_waitcnt vmcnt(8)
	s_waitcnt lgkmcnt(0)
	s_setprio 1
	v_mfma_f32_16x16x32_bf16 v[142:145], v[106:109], v[162:165], v[142:145]
	s_barrier
	v_mfma_f32_16x16x32_bf16 v[142:145], v[118:121], v[166:169], v[142:145]
	v_mfma_f32_16x16x32_bf16 v[134:137], v[138:141], v[166:169], v[134:137]
	v_mfma_f32_16x16x32_bf16 v[134:137], v[130:133], v[162:165], v[134:137]
	v_mfma_f32_16x16x32_bf16 v[126:129], v[146:149], v[162:165], v[126:129]
	v_mfma_f32_16x16x32_bf16 v[126:129], v[150:153], v[166:169], v[126:129]
	v_mfma_f32_16x16x32_bf16 v[122:125], v[158:161], v[166:169], v[122:125]
	v_mfma_f32_16x16x32_bf16 v[122:125], v[154:157], v[162:165], v[122:125]
	v_mfma_f32_16x16x32_bf16 v[98:101], v[154:157], v[170:173], v[98:101]
	v_mfma_f32_16x16x32_bf16 v[98:101], v[158:161], v[174:177], v[98:101]
	v_mfma_f32_16x16x32_bf16 v[102:105], v[150:153], v[174:177], v[102:105]
	v_mfma_f32_16x16x32_bf16 v[102:105], v[146:149], v[170:173], v[102:105]
	v_mfma_f32_16x16x32_bf16 v[110:113], v[130:133], v[170:173], v[110:113]
	v_mfma_f32_16x16x32_bf16 v[110:113], v[138:141], v[174:177], v[110:113]
	v_mfma_f32_16x16x32_bf16 v[114:117], v[118:121], v[174:177], v[114:117]
	v_mfma_f32_16x16x32_bf16 v[114:117], v[106:109], v[170:173], v[114:117]
	v_mfma_f32_16x16x32_bf16 v[94:97], v[106:109], v[178:181], v[94:97]
	v_mfma_f32_16x16x32_bf16 v[94:97], v[118:121], v[182:185], v[94:97]
	v_mfma_f32_16x16x32_bf16 v[90:93], v[138:141], v[182:185], v[90:93]
	v_mfma_f32_16x16x32_bf16 v[90:93], v[130:133], v[178:181], v[90:93]
	v_mfma_f32_16x16x32_bf16 v[86:89], v[146:149], v[178:181], v[86:89]
	v_mfma_f32_16x16x32_bf16 v[86:89], v[150:153], v[182:185], v[86:89]
	v_mfma_f32_16x16x32_bf16 v[82:85], v[158:161], v[182:185], v[82:85]
	v_mfma_f32_16x16x32_bf16 v[82:85], v[154:157], v[178:181], v[82:85]
	v_mfma_f32_16x16x32_bf16 v[66:69], v[154:157], v[190:193], v[66:69]
	v_mfma_f32_16x16x32_bf16 v[66:69], v[158:161], v[194:197], v[66:69]
	v_mfma_f32_16x16x32_bf16 v[70:73], v[150:153], v[194:197], v[70:73]
	v_mfma_f32_16x16x32_bf16 v[70:73], v[146:149], v[190:193], v[70:73]
	v_mfma_f32_16x16x32_bf16 v[74:77], v[130:133], v[190:193], v[74:77]
	v_mfma_f32_16x16x32_bf16 v[74:77], v[138:141], v[194:197], v[74:77]
	v_mfma_f32_16x16x32_bf16 v[78:81], v[118:121], v[194:197], v[78:81]
	v_mfma_f32_16x16x32_bf16 v[78:81], v[106:109], v[190:193], v[78:81]
	s_setprio 0
	s_barrier
	s_mov_b32 m0, s27
	s_mov_b32 s18, s14
	s_mov_b32 s19, s15
	ds_read_b128 v[162:165], v226 offset:16384
	ds_read_b128 v[166:169], v226 offset:17408
	ds_read_b128 v[170:173], v226 offset:18432
	ds_read_b128 v[174:177], v226 offset:19456
	ds_read_b128 v[178:181], v226 offset:20480
	ds_read_b128 v[182:185], v226 offset:21504
	ds_read_b128 v[190:193], v226 offset:22528
	ds_read_b128 v[194:197], v226 offset:23552
	buffer_load_dwordx4 v223, s[16:19], s77 offen lds
	s_add_i32 s78, s77, 0x80000
	s_mov_b32 m0, s30
	s_nop 0
	buffer_load_dwordx4 v223, s[16:19], s78 offen lds
	s_add_i32 s78, s77, 0x100000
	s_mov_b32 m0, s31
	s_nop 0
	buffer_load_dwordx4 v223, s[16:19], s78 offen lds
	s_add_i32 s78, s77, 0x180000
	s_mov_b32 m0, s41
	s_nop 0
	buffer_load_dwordx4 v223, s[16:19], s78 offen lds
	s_mov_b32 m0, s25
	s_add_i32 s78, s75, 0x80000
	buffer_load_dwordx4 v222, s[12:15], s75 offen lds
	s_mov_b32 m0, s42
	s_nop 0
	buffer_load_dwordx4 v222, s[12:15], s78 offen lds
	s_waitcnt vmcnt(8)
	s_waitcnt lgkmcnt(0)
	s_setprio 1
	v_mfma_f32_16x16x32_bf16 v[62:65], v[106:109], v[162:165], v[62:65]
	s_barrier
	v_mfma_f32_16x16x32_bf16 v[62:65], v[118:121], v[166:169], v[62:65]
	v_mfma_f32_16x16x32_bf16 v[58:61], v[138:141], v[166:169], v[58:61]
	v_mfma_f32_16x16x32_bf16 v[58:61], v[130:133], v[162:165], v[58:61]
	v_mfma_f32_16x16x32_bf16 v[54:57], v[146:149], v[162:165], v[54:57]
	v_mfma_f32_16x16x32_bf16 v[54:57], v[150:153], v[166:169], v[54:57]
	v_mfma_f32_16x16x32_bf16 v[50:53], v[158:161], v[166:169], v[50:53]
	v_mfma_f32_16x16x32_bf16 v[50:53], v[154:157], v[162:165], v[50:53]
	v_mfma_f32_16x16x32_bf16 v[34:37], v[154:157], v[170:173], v[34:37]
	v_mfma_f32_16x16x32_bf16 v[34:37], v[158:161], v[174:177], v[34:37]
	v_mfma_f32_16x16x32_bf16 v[38:41], v[150:153], v[174:177], v[38:41]
	v_mfma_f32_16x16x32_bf16 v[38:41], v[146:149], v[170:173], v[38:41]
	v_mfma_f32_16x16x32_bf16 v[42:45], v[130:133], v[170:173], v[42:45]
	v_mfma_f32_16x16x32_bf16 v[42:45], v[138:141], v[174:177], v[42:45]
	v_mfma_f32_16x16x32_bf16 v[46:49], v[118:121], v[174:177], v[46:49]
	v_mfma_f32_16x16x32_bf16 v[46:49], v[106:109], v[170:173], v[46:49]
	v_mfma_f32_16x16x32_bf16 v[30:33], v[106:109], v[178:181], v[30:33]
	v_mfma_f32_16x16x32_bf16 v[30:33], v[118:121], v[182:185], v[30:33]
	v_mfma_f32_16x16x32_bf16 v[26:29], v[138:141], v[182:185], v[26:29]
	v_mfma_f32_16x16x32_bf16 v[26:29], v[130:133], v[178:181], v[26:29]
	v_mfma_f32_16x16x32_bf16 v[22:25], v[146:149], v[178:181], v[22:25]
	v_mfma_f32_16x16x32_bf16 v[22:25], v[150:153], v[182:185], v[22:25]
	v_mfma_f32_16x16x32_bf16 v[18:21], v[158:161], v[182:185], v[18:21]
	v_mfma_f32_16x16x32_bf16 v[18:21], v[154:157], v[178:181], v[18:21]
	v_mfma_f32_16x16x32_bf16 v[2:5], v[154:157], v[190:193], v[2:5]
	v_mfma_f32_16x16x32_bf16 v[2:5], v[158:161], v[194:197], v[2:5]
	v_mfma_f32_16x16x32_bf16 v[6:9], v[150:153], v[194:197], v[6:9]
	v_mfma_f32_16x16x32_bf16 v[6:9], v[146:149], v[190:193], v[6:9]
	v_mfma_f32_16x16x32_bf16 v[10:13], v[130:133], v[190:193], v[10:13]
	v_mfma_f32_16x16x32_bf16 v[10:13], v[138:141], v[194:197], v[10:13]
	v_mfma_f32_16x16x32_bf16 v[14:17], v[118:121], v[194:197], v[14:17]
	v_mfma_f32_16x16x32_bf16 v[14:17], v[106:109], v[190:193], v[14:17]
	s_setprio 0
	s_barrier
	ds_read_b128 v[106:109], v227
	ds_read_b128 v[118:121], v227 offset:1024
	ds_read_b128 v[130:133], v227 offset:2048
	ds_read_b128 v[138:141], v227 offset:3072
	ds_read_b128 v[146:149], v228
	ds_read_b128 v[150:153], v228 offset:1024
	ds_read_b128 v[154:157], v228 offset:2048
	ds_read_b128 v[158:161], v228 offset:3072
	s_mov_b32 m0, s43
	s_add_i32 s78, s75, 0x100000
	ds_read_b128 v[162:165], v226 offset:32768
	ds_read_b128 v[166:169], v226 offset:33792
	ds_read_b128 v[170:173], v226 offset:34816
	ds_read_b128 v[174:177], v226 offset:35840
	ds_read_b128 v[178:181], v226 offset:36864
	ds_read_b128 v[182:185], v226 offset:37888
	ds_read_b128 v[190:193], v226 offset:38912
	ds_read_b128 v[194:197], v226 offset:39936
	buffer_load_dwordx4 v222, s[12:15], s78 offen lds
	s_add_i32 s78, s75, 0x180000
	s_mov_b32 m0, s44
	s_nop 0
	buffer_load_dwordx4 v222, s[12:15], s78 offen lds
	s_waitcnt vmcnt(8)
	s_waitcnt lgkmcnt(0)
	s_setprio 1
	v_mfma_f32_16x16x32_bf16 v[142:145], v[106:109], v[162:165], v[142:145]
	s_barrier
	v_mfma_f32_16x16x32_bf16 v[142:145], v[118:121], v[166:169], v[142:145]
	v_mfma_f32_16x16x32_bf16 v[134:137], v[138:141], v[166:169], v[134:137]
	v_mfma_f32_16x16x32_bf16 v[134:137], v[130:133], v[162:165], v[134:137]
	v_mfma_f32_16x16x32_bf16 v[126:129], v[146:149], v[162:165], v[126:129]
	v_mfma_f32_16x16x32_bf16 v[126:129], v[150:153], v[166:169], v[126:129]
	v_mfma_f32_16x16x32_bf16 v[122:125], v[158:161], v[166:169], v[122:125]
	v_mfma_f32_16x16x32_bf16 v[122:125], v[154:157], v[162:165], v[122:125]
	v_mfma_f32_16x16x32_bf16 v[98:101], v[154:157], v[170:173], v[98:101]
	v_mfma_f32_16x16x32_bf16 v[98:101], v[158:161], v[174:177], v[98:101]
	v_mfma_f32_16x16x32_bf16 v[102:105], v[150:153], v[174:177], v[102:105]
	v_mfma_f32_16x16x32_bf16 v[102:105], v[146:149], v[170:173], v[102:105]
	v_mfma_f32_16x16x32_bf16 v[110:113], v[130:133], v[170:173], v[110:113]
	v_mfma_f32_16x16x32_bf16 v[110:113], v[138:141], v[174:177], v[110:113]
	v_mfma_f32_16x16x32_bf16 v[114:117], v[118:121], v[174:177], v[114:117]
	v_mfma_f32_16x16x32_bf16 v[114:117], v[106:109], v[170:173], v[114:117]
	v_mfma_f32_16x16x32_bf16 v[94:97], v[106:109], v[178:181], v[94:97]
	v_mfma_f32_16x16x32_bf16 v[94:97], v[118:121], v[182:185], v[94:97]
	v_mfma_f32_16x16x32_bf16 v[90:93], v[138:141], v[182:185], v[90:93]
	v_mfma_f32_16x16x32_bf16 v[90:93], v[130:133], v[178:181], v[90:93]
	v_mfma_f32_16x16x32_bf16 v[86:89], v[146:149], v[178:181], v[86:89]
	v_mfma_f32_16x16x32_bf16 v[86:89], v[150:153], v[182:185], v[86:89]
	v_mfma_f32_16x16x32_bf16 v[82:85], v[158:161], v[182:185], v[82:85]
	v_mfma_f32_16x16x32_bf16 v[82:85], v[154:157], v[178:181], v[82:85]
	v_mfma_f32_16x16x32_bf16 v[66:69], v[154:157], v[190:193], v[66:69]
	v_mfma_f32_16x16x32_bf16 v[66:69], v[158:161], v[194:197], v[66:69]
	v_mfma_f32_16x16x32_bf16 v[70:73], v[150:153], v[194:197], v[70:73]
	v_mfma_f32_16x16x32_bf16 v[70:73], v[146:149], v[190:193], v[70:73]
	v_mfma_f32_16x16x32_bf16 v[74:77], v[130:133], v[190:193], v[74:77]
	v_mfma_f32_16x16x32_bf16 v[74:77], v[138:141], v[194:197], v[74:77]
	v_mfma_f32_16x16x32_bf16 v[78:81], v[118:121], v[194:197], v[78:81]
	v_mfma_f32_16x16x32_bf16 v[78:81], v[106:109], v[190:193], v[78:81]
	s_setprio 0
	s_barrier
	s_mov_b32 m0, s48
	s_or_b32 s78, s77, 0x80
	ds_read_b128 v[162:165], v226 offset:49152
	ds_read_b128 v[166:169], v226 offset:50176
	ds_read_b128 v[170:173], v226 offset:51200
	ds_read_b128 v[174:177], v226 offset:52224
	ds_read_b128 v[178:181], v226 offset:53248
	ds_read_b128 v[182:185], v226 offset:54272
	ds_read_b128 v[190:193], v226 offset:55296
	ds_read_b128 v[194:197], v226 offset:56320
	buffer_load_dwordx4 v223, s[16:19], s78 offen lds
	s_add_i32 s78, s77, 0x80080
	s_mov_b32 m0, s49
	s_add_i32 s75, s75, 0x80080
	buffer_load_dwordx4 v223, s[16:19], s78 offen lds
	s_add_i32 s78, s77, 0x100080
	s_mov_b32 m0, s52
	s_add_i32 s77, s77, 0x180080
	buffer_load_dwordx4 v223, s[16:19], s78 offen lds
	s_mov_b32 m0, s53
	s_nop 0
	buffer_load_dwordx4 v223, s[16:19], s77 offen lds
	s_mov_b32 m0, s50
	s_nop 0
	buffer_load_dwordx4 v222, s[12:15], s76 offen lds
	s_mov_b32 m0, s51
	s_nop 0
	buffer_load_dwordx4 v222, s[12:15], s75 offen lds
	s_waitcnt vmcnt(8)
	s_waitcnt lgkmcnt(0)
	s_setprio 1
	v_mfma_f32_16x16x32_bf16 v[62:65], v[106:109], v[162:165], v[62:65]
	s_barrier
	v_mfma_f32_16x16x32_bf16 v[62:65], v[118:121], v[166:169], v[62:65]
	v_mfma_f32_16x16x32_bf16 v[58:61], v[138:141], v[166:169], v[58:61]
	v_mfma_f32_16x16x32_bf16 v[58:61], v[130:133], v[162:165], v[58:61]
	v_mfma_f32_16x16x32_bf16 v[54:57], v[146:149], v[162:165], v[54:57]
	v_mfma_f32_16x16x32_bf16 v[54:57], v[150:153], v[166:169], v[54:57]
	v_mfma_f32_16x16x32_bf16 v[50:53], v[158:161], v[166:169], v[50:53]
	v_mfma_f32_16x16x32_bf16 v[50:53], v[154:157], v[162:165], v[50:53]
	v_mfma_f32_16x16x32_bf16 v[34:37], v[154:157], v[170:173], v[34:37]
	v_mfma_f32_16x16x32_bf16 v[34:37], v[158:161], v[174:177], v[34:37]
	v_mfma_f32_16x16x32_bf16 v[38:41], v[150:153], v[174:177], v[38:41]
	v_mfma_f32_16x16x32_bf16 v[38:41], v[146:149], v[170:173], v[38:41]
	v_mfma_f32_16x16x32_bf16 v[42:45], v[130:133], v[170:173], v[42:45]
	v_mfma_f32_16x16x32_bf16 v[42:45], v[138:141], v[174:177], v[42:45]
	v_mfma_f32_16x16x32_bf16 v[46:49], v[118:121], v[174:177], v[46:49]
	v_mfma_f32_16x16x32_bf16 v[46:49], v[106:109], v[170:173], v[46:49]
	v_mfma_f32_16x16x32_bf16 v[30:33], v[106:109], v[178:181], v[30:33]
	v_mfma_f32_16x16x32_bf16 v[30:33], v[118:121], v[182:185], v[30:33]
	v_mfma_f32_16x16x32_bf16 v[26:29], v[138:141], v[182:185], v[26:29]
	v_mfma_f32_16x16x32_bf16 v[26:29], v[130:133], v[178:181], v[26:29]
	v_mfma_f32_16x16x32_bf16 v[22:25], v[146:149], v[178:181], v[22:25]
	v_mfma_f32_16x16x32_bf16 v[22:25], v[150:153], v[182:185], v[22:25]
	v_mfma_f32_16x16x32_bf16 v[18:21], v[158:161], v[182:185], v[18:21]
	v_mfma_f32_16x16x32_bf16 v[18:21], v[154:157], v[178:181], v[18:21]
	v_mfma_f32_16x16x32_bf16 v[2:5], v[154:157], v[190:193], v[2:5]
	v_mfma_f32_16x16x32_bf16 v[2:5], v[158:161], v[194:197], v[2:5]
	v_mfma_f32_16x16x32_bf16 v[6:9], v[150:153], v[194:197], v[6:9]
	v_mfma_f32_16x16x32_bf16 v[6:9], v[146:149], v[190:193], v[6:9]
	v_mfma_f32_16x16x32_bf16 v[10:13], v[130:133], v[190:193], v[10:13]
	v_mfma_f32_16x16x32_bf16 v[10:13], v[138:141], v[194:197], v[10:13]
	v_mfma_f32_16x16x32_bf16 v[14:17], v[118:121], v[194:197], v[14:17]
	v_mfma_f32_16x16x32_bf16 v[14:17], v[106:109], v[190:193], v[14:17]
	s_setprio 0
	s_barrier
	s_add_i32 s74, s74, 2
	s_addk_i32 s72, 0x100
	s_addk_i32 s73, 0x100
	s_cmp_ge_i32 s74, s3
	s_cbranch_scc0 .LBB0_1290
	s_and_b64 vcc, exec, s[38:39]
	s_cbranch_vccz .LBB0_1293

.LBB0_1382:
	ds_read_b128 v[144:147], v138
	ds_read_b128 v[148:151], v138 offset:1024
	ds_read_b128 v[152:155], v138 offset:2048
	ds_read_b128 v[156:159], v138 offset:3072
	ds_read_b128 v[160:163], v139
	ds_read_b128 v[164:167], v139 offset:1024
	ds_read_b128 v[168:171], v139 offset:2048
	ds_read_b128 v[172:175], v139 offset:3072
	s_add_i32 s14, s74, 0xffe80080
	s_cmp_eq_u32 s61, s76
	s_cselect_b32 s77, s72, s14
	s_cselect_b32 s79, s73, s75
	s_or_b32 s78, s77, 0x80
	s_add_i32 s14, s74, 0xfff80000
	s_mov_b32 m0, s62
	ds_read_b128 v[176:179], v140
	ds_read_b128 v[180:183], v140 offset:1024
	ds_read_b128 v[184:187], v140 offset:2048
	ds_read_b128 v[188:191], v140 offset:3072
	ds_read_b128 v[192:195], v140 offset:4096
	ds_read_b128 v[196:199], v140 offset:5120
	ds_read_b128 v[200:203], v140 offset:6144
	ds_read_b128 v[204:207], v140 offset:7168
	buffer_load_dwordx4 v136, s[16:19], s14 offen lds
	s_mov_b32 m0, s63
	s_nop 0
	buffer_load_dwordx4 v136, s[16:19], s74 offen lds
	s_waitcnt vmcnt(8)
	s_waitcnt lgkmcnt(0)
	s_setprio 1
	v_mfma_f32_16x16x32_bf16 v[118:121], v[144:147], v[176:179], v[118:121]
	s_barrier
	v_mfma_f32_16x16x32_bf16 v[118:121], v[148:151], v[180:183], v[118:121]
	v_mfma_f32_16x16x32_bf16 v[114:117], v[156:159], v[180:183], v[114:117]
	v_mfma_f32_16x16x32_bf16 v[114:117], v[152:155], v[176:179], v[114:117]
	v_mfma_f32_16x16x32_bf16 v[126:129], v[160:163], v[176:179], v[126:129]
	v_mfma_f32_16x16x32_bf16 v[126:129], v[164:167], v[180:183], v[126:129]
	v_mfma_f32_16x16x32_bf16 v[122:125], v[172:175], v[180:183], v[122:125]
	v_mfma_f32_16x16x32_bf16 v[122:125], v[168:171], v[176:179], v[122:125]
	v_mfma_f32_16x16x32_bf16 v[98:101], v[168:171], v[184:187], v[98:101]
	v_mfma_f32_16x16x32_bf16 v[98:101], v[172:175], v[188:191], v[98:101]
	v_mfma_f32_16x16x32_bf16 v[106:109], v[164:167], v[188:191], v[106:109]
	v_mfma_f32_16x16x32_bf16 v[106:109], v[160:163], v[184:187], v[106:109]
	v_mfma_f32_16x16x32_bf16 v[102:105], v[152:155], v[184:187], v[102:105]
	v_mfma_f32_16x16x32_bf16 v[102:105], v[156:159], v[188:191], v[102:105]
	v_mfma_f32_16x16x32_bf16 v[110:113], v[148:151], v[188:191], v[110:113]
	v_mfma_f32_16x16x32_bf16 v[110:113], v[144:147], v[184:187], v[110:113]
	v_mfma_f32_16x16x32_bf16 v[94:97], v[144:147], v[192:195], v[94:97]
	v_mfma_f32_16x16x32_bf16 v[94:97], v[148:151], v[196:199], v[94:97]
	v_mfma_f32_16x16x32_bf16 v[86:89], v[156:159], v[196:199], v[86:89]
	v_mfma_f32_16x16x32_bf16 v[86:89], v[152:155], v[192:195], v[86:89]
	v_mfma_f32_16x16x32_bf16 v[90:93], v[160:163], v[192:195], v[90:93]
	v_mfma_f32_16x16x32_bf16 v[90:93], v[164:167], v[196:199], v[90:93]
	v_mfma_f32_16x16x32_bf16 v[82:85], v[172:175], v[196:199], v[82:85]
	v_mfma_f32_16x16x32_bf16 v[82:85], v[168:171], v[192:195], v[82:85]
	v_mfma_f32_16x16x32_bf16 v[70:73], v[168:171], v[200:203], v[70:73]
	v_mfma_f32_16x16x32_bf16 v[70:73], v[172:175], v[204:207], v[70:73]
	v_mfma_f32_16x16x32_bf16 v[74:77], v[164:167], v[204:207], v[74:77]
	v_mfma_f32_16x16x32_bf16 v[74:77], v[160:163], v[200:203], v[74:77]
	v_mfma_f32_16x16x32_bf16 v[66:69], v[152:155], v[200:203], v[66:69]
	v_mfma_f32_16x16x32_bf16 v[66:69], v[156:159], v[204:207], v[66:69]
	v_mfma_f32_16x16x32_bf16 v[78:81], v[148:151], v[204:207], v[78:81]
	v_mfma_f32_16x16x32_bf16 v[78:81], v[144:147], v[200:203], v[78:81]
	s_setprio 0
	s_barrier
	s_mov_b32 m0, s45
	s_mov_b32 s14, s18
	s_mov_b32 s15, s19
	ds_read_b128 v[176:179], v140 offset:16384
	ds_read_b128 v[180:183], v140 offset:17408
	ds_read_b128 v[184:187], v140 offset:18432
	ds_read_b128 v[188:191], v140 offset:19456
	ds_read_b128 v[192:195], v140 offset:20480
	ds_read_b128 v[196:199], v140 offset:21504
	ds_read_b128 v[200:203], v140 offset:22528
	ds_read_b128 v[204:207], v140 offset:23552
	buffer_load_dwordx4 v137, s[12:15], s79 offen lds
	s_add_i32 s80, s79, 0x80000
	s_mov_b32 m0, s46
	s_nop 0
	buffer_load_dwordx4 v137, s[12:15], s80 offen lds
	s_add_i32 s80, s79, 0x100000
	s_mov_b32 m0, s47
	s_nop 0
	buffer_load_dwordx4 v137, s[12:15], s80 offen lds
	s_add_i32 s80, s79, 0x180000
	s_mov_b32 m0, s48
	s_nop 0
	buffer_load_dwordx4 v137, s[12:15], s80 offen lds
	s_mov_b32 m0, s44
	s_add_i32 s80, s77, 0x80000
	buffer_load_dwordx4 v136, s[16:19], s77 offen lds
	s_mov_b32 m0, s49
	s_nop 0
	buffer_load_dwordx4 v136, s[16:19], s80 offen lds
	s_waitcnt vmcnt(8)
	s_waitcnt lgkmcnt(0)
	s_setprio 1
	v_mfma_f32_16x16x32_bf16 v[62:65], v[144:147], v[176:179], v[62:65]
	s_barrier
	v_mfma_f32_16x16x32_bf16 v[62:65], v[148:151], v[180:183], v[62:65]
	v_mfma_f32_16x16x32_bf16 v[54:57], v[156:159], v[180:183], v[54:57]
	v_mfma_f32_16x16x32_bf16 v[54:57], v[152:155], v[176:179], v[54:57]
	v_mfma_f32_16x16x32_bf16 v[58:61], v[160:163], v[176:179], v[58:61]
	v_mfma_f32_16x16x32_bf16 v[58:61], v[164:167], v[180:183], v[58:61]
	v_mfma_f32_16x16x32_bf16 v[50:53], v[172:175], v[180:183], v[50:53]
	v_mfma_f32_16x16x32_bf16 v[50:53], v[168:171], v[176:179], v[50:53]
	v_mfma_f32_16x16x32_bf16 v[34:37], v[168:171], v[184:187], v[34:37]
	v_mfma_f32_16x16x32_bf16 v[34:37], v[172:175], v[188:191], v[34:37]
	v_mfma_f32_16x16x32_bf16 v[42:45], v[164:167], v[188:191], v[42:45]
	v_mfma_f32_16x16x32_bf16 v[42:45], v[160:163], v[184:187], v[42:45]
	v_mfma_f32_16x16x32_bf16 v[38:41], v[152:155], v[184:187], v[38:41]
	v_mfma_f32_16x16x32_bf16 v[38:41], v[156:159], v[188:191], v[38:41]
	v_mfma_f32_16x16x32_bf16 v[46:49], v[148:151], v[188:191], v[46:49]
	v_mfma_f32_16x16x32_bf16 v[46:49], v[144:147], v[184:187], v[46:49]
	v_mfma_f32_16x16x32_bf16 v[30:33], v[144:147], v[192:195], v[30:33]
	v_mfma_f32_16x16x32_bf16 v[30:33], v[148:151], v[196:199], v[30:33]
	v_mfma_f32_16x16x32_bf16 v[22:25], v[156:159], v[196:199], v[22:25]
	v_mfma_f32_16x16x32_bf16 v[22:25], v[152:155], v[192:195], v[22:25]
	v_mfma_f32_16x16x32_bf16 v[26:29], v[160:163], v[192:195], v[26:29]
	v_mfma_f32_16x16x32_bf16 v[26:29], v[164:167], v[196:199], v[26:29]
	v_mfma_f32_16x16x32_bf16 v[18:21], v[172:175], v[196:199], v[18:21]
	v_mfma_f32_16x16x32_bf16 v[18:21], v[168:171], v[192:195], v[18:21]
	v_mfma_f32_16x16x32_bf16 v[2:5], v[168:171], v[200:203], v[2:5]
	v_mfma_f32_16x16x32_bf16 v[2:5], v[172:175], v[204:207], v[2:5]
	v_mfma_f32_16x16x32_bf16 v[10:13], v[164:167], v[204:207], v[10:13]
	v_mfma_f32_16x16x32_bf16 v[10:13], v[160:163], v[200:203], v[10:13]
	v_mfma_f32_16x16x32_bf16 v[6:9], v[152:155], v[200:203], v[6:9]
	v_mfma_f32_16x16x32_bf16 v[6:9], v[156:159], v[204:207], v[6:9]
	v_mfma_f32_16x16x32_bf16 v[14:17], v[148:151], v[204:207], v[14:17]
	v_mfma_f32_16x16x32_bf16 v[14:17], v[144:147], v[200:203], v[14:17]
	s_setprio 0
	s_barrier
	ds_read_b128 v[144:147], v141
	ds_read_b128 v[148:151], v141 offset:1024
	ds_read_b128 v[152:155], v141 offset:2048
	ds_read_b128 v[156:159], v141 offset:3072
	ds_read_b128 v[160:163], v142
	ds_read_b128 v[164:167], v142 offset:1024
	ds_read_b128 v[168:171], v142 offset:2048
	ds_read_b128 v[172:175], v142 offset:3072
	s_mov_b32 m0, s50
	s_add_i32 s80, s77, 0x100000
	ds_read_b128 v[176:179], v140 offset:32768
	ds_read_b128 v[180:183], v140 offset:33792
	ds_read_b128 v[184:187], v140 offset:34816
	ds_read_b128 v[188:191], v140 offset:35840
	ds_read_b128 v[192:195], v140 offset:36864
	ds_read_b128 v[196:199], v140 offset:37888
	ds_read_b128 v[200:203], v140 offset:38912
	ds_read_b128 v[204:207], v140 offset:39936
	buffer_load_dwordx4 v136, s[16:19], s80 offen lds
	s_add_i32 s80, s77, 0x180000
	s_mov_b32 m0, s51
	s_nop 0
	buffer_load_dwordx4 v136, s[16:19], s80 offen lds
	s_waitcnt vmcnt(8)
	s_waitcnt lgkmcnt(0)
	s_setprio 1
	v_mfma_f32_16x16x32_bf16 v[118:121], v[144:147], v[176:179], v[118:121]
	s_barrier
	v_mfma_f32_16x16x32_bf16 v[118:121], v[148:151], v[180:183], v[118:121]
	v_mfma_f32_16x16x32_bf16 v[114:117], v[156:159], v[180:183], v[114:117]
	v_mfma_f32_16x16x32_bf16 v[114:117], v[152:155], v[176:179], v[114:117]
	v_mfma_f32_16x16x32_bf16 v[126:129], v[160:163], v[176:179], v[126:129]
	v_mfma_f32_16x16x32_bf16 v[126:129], v[164:167], v[180:183], v[126:129]
	v_mfma_f32_16x16x32_bf16 v[122:125], v[172:175], v[180:183], v[122:125]
	v_mfma_f32_16x16x32_bf16 v[122:125], v[168:171], v[176:179], v[122:125]
	v_mfma_f32_16x16x32_bf16 v[98:101], v[168:171], v[184:187], v[98:101]
	v_mfma_f32_16x16x32_bf16 v[98:101], v[172:175], v[188:191], v[98:101]
	v_mfma_f32_16x16x32_bf16 v[106:109], v[164:167], v[188:191], v[106:109]
	v_mfma_f32_16x16x32_bf16 v[106:109], v[160:163], v[184:187], v[106:109]
	v_mfma_f32_16x16x32_bf16 v[102:105], v[152:155], v[184:187], v[102:105]
	v_mfma_f32_16x16x32_bf16 v[102:105], v[156:159], v[188:191], v[102:105]
	v_mfma_f32_16x16x32_bf16 v[110:113], v[148:151], v[188:191], v[110:113]
	v_mfma_f32_16x16x32_bf16 v[110:113], v[144:147], v[184:187], v[110:113]
	v_mfma_f32_16x16x32_bf16 v[94:97], v[144:147], v[192:195], v[94:97]
	v_mfma_f32_16x16x32_bf16 v[94:97], v[148:151], v[196:199], v[94:97]
	v_mfma_f32_16x16x32_bf16 v[86:89], v[156:159], v[196:199], v[86:89]
	v_mfma_f32_16x16x32_bf16 v[86:89], v[152:155], v[192:195], v[86:89]
	v_mfma_f32_16x16x32_bf16 v[90:93], v[160:163], v[192:195], v[90:93]
	v_mfma_f32_16x16x32_bf16 v[90:93], v[164:167], v[196:199], v[90:93]
	v_mfma_f32_16x16x32_bf16 v[82:85], v[172:175], v[196:199], v[82:85]
	v_mfma_f32_16x16x32_bf16 v[82:85], v[168:171], v[192:195], v[82:85]
	v_mfma_f32_16x16x32_bf16 v[70:73], v[168:171], v[200:203], v[70:73]
	v_mfma_f32_16x16x32_bf16 v[70:73], v[172:175], v[204:207], v[70:73]
	v_mfma_f32_16x16x32_bf16 v[74:77], v[164:167], v[204:207], v[74:77]
	v_mfma_f32_16x16x32_bf16 v[74:77], v[160:163], v[200:203], v[74:77]
	v_mfma_f32_16x16x32_bf16 v[66:69], v[152:155], v[200:203], v[66:69]
	v_mfma_f32_16x16x32_bf16 v[66:69], v[156:159], v[204:207], v[66:69]
	v_mfma_f32_16x16x32_bf16 v[78:81], v[148:151], v[204:207], v[78:81]
	v_mfma_f32_16x16x32_bf16 v[78:81], v[144:147], v[200:203], v[78:81]
	s_setprio 0
	s_barrier
	s_mov_b32 m0, s53
	s_or_b32 s80, s79, 0x80
	ds_read_b128 v[176:179], v140 offset:49152
	ds_read_b128 v[180:183], v140 offset:50176
	ds_read_b128 v[184:187], v140 offset:51200
	ds_read_b128 v[188:191], v140 offset:52224
	ds_read_b128 v[192:195], v140 offset:53248
	ds_read_b128 v[196:199], v140 offset:54272
	ds_read_b128 v[200:203], v140 offset:55296
	ds_read_b128 v[204:207], v140 offset:56320
	buffer_load_dwordx4 v137, s[12:15], s80 offen lds
	s_add_i32 s80, s79, 0x80080
	s_mov_b32 m0, s54
	s_add_i32 s77, s77, 0x80080
	buffer_load_dwordx4 v137, s[12:15], s80 offen lds
	s_add_i32 s80, s79, 0x100080
	s_mov_b32 m0, s57
	s_add_i32 s79, s79, 0x180080
	buffer_load_dwordx4 v137, s[12:15], s80 offen lds
	s_mov_b32 m0, s58
	s_nop 0
	buffer_load_dwordx4 v137, s[12:15], s79 offen lds
	s_mov_b32 m0, s55
	s_nop 0
	buffer_load_dwordx4 v136, s[16:19], s78 offen lds
	s_mov_b32 m0, s56
	s_nop 0
	buffer_load_dwordx4 v136, s[16:19], s77 offen lds
	s_waitcnt vmcnt(8)
	s_waitcnt lgkmcnt(0)
	s_setprio 1
	v_mfma_f32_16x16x32_bf16 v[62:65], v[144:147], v[176:179], v[62:65]
	s_barrier
	v_mfma_f32_16x16x32_bf16 v[62:65], v[148:151], v[180:183], v[62:65]
	v_mfma_f32_16x16x32_bf16 v[54:57], v[156:159], v[180:183], v[54:57]
	v_mfma_f32_16x16x32_bf16 v[54:57], v[152:155], v[176:179], v[54:57]
	v_mfma_f32_16x16x32_bf16 v[58:61], v[160:163], v[176:179], v[58:61]
	v_mfma_f32_16x16x32_bf16 v[58:61], v[164:167], v[180:183], v[58:61]
	v_mfma_f32_16x16x32_bf16 v[50:53], v[172:175], v[180:183], v[50:53]
	v_mfma_f32_16x16x32_bf16 v[50:53], v[168:171], v[176:179], v[50:53]
	v_mfma_f32_16x16x32_bf16 v[34:37], v[168:171], v[184:187], v[34:37]
	v_mfma_f32_16x16x32_bf16 v[34:37], v[172:175], v[188:191], v[34:37]
	v_mfma_f32_16x16x32_bf16 v[42:45], v[164:167], v[188:191], v[42:45]
	v_mfma_f32_16x16x32_bf16 v[42:45], v[160:163], v[184:187], v[42:45]
	v_mfma_f32_16x16x32_bf16 v[38:41], v[152:155], v[184:187], v[38:41]
	v_mfma_f32_16x16x32_bf16 v[38:41], v[156:159], v[188:191], v[38:41]
	v_mfma_f32_16x16x32_bf16 v[46:49], v[148:151], v[188:191], v[46:49]
	v_mfma_f32_16x16x32_bf16 v[46:49], v[144:147], v[184:187], v[46:49]
	v_mfma_f32_16x16x32_bf16 v[30:33], v[144:147], v[192:195], v[30:33]
	v_mfma_f32_16x16x32_bf16 v[30:33], v[148:151], v[196:199], v[30:33]
	v_mfma_f32_16x16x32_bf16 v[22:25], v[156:159], v[196:199], v[22:25]
	v_mfma_f32_16x16x32_bf16 v[22:25], v[152:155], v[192:195], v[22:25]
	v_mfma_f32_16x16x32_bf16 v[26:29], v[160:163], v[192:195], v[26:29]
	v_mfma_f32_16x16x32_bf16 v[26:29], v[164:167], v[196:199], v[26:29]
	v_mfma_f32_16x16x32_bf16 v[18:21], v[172:175], v[196:199], v[18:21]
	v_mfma_f32_16x16x32_bf16 v[18:21], v[168:171], v[192:195], v[18:21]
	v_mfma_f32_16x16x32_bf16 v[2:5], v[168:171], v[200:203], v[2:5]
	v_mfma_f32_16x16x32_bf16 v[2:5], v[172:175], v[204:207], v[2:5]
	v_mfma_f32_16x16x32_bf16 v[10:13], v[164:167], v[204:207], v[10:13]
	v_mfma_f32_16x16x32_bf16 v[10:13], v[160:163], v[200:203], v[10:13]
	v_mfma_f32_16x16x32_bf16 v[6:9], v[152:155], v[200:203], v[6:9]
	v_mfma_f32_16x16x32_bf16 v[6:9], v[156:159], v[204:207], v[6:9]
	v_mfma_f32_16x16x32_bf16 v[14:17], v[148:151], v[204:207], v[14:17]
	v_mfma_f32_16x16x32_bf16 v[14:17], v[144:147], v[200:203], v[14:17]
	s_setprio 0
	s_barrier
	s_add_i32 s76, s76, 2
	s_addk_i32 s74, 0x100
	s_addk_i32 s75, 0x100
	s_cmp_ge_i32 s76, s27
	s_cbranch_scc0 .LBB0_1382
	s_and_b64 vcc, exec, s[42:43]
	s_cbranch_vccz .LBB0_1385

.LBB0_1402:
	ds_read_b128 v[146:149], v138
	ds_read_b128 v[150:153], v138 offset:1024
	ds_read_b128 v[154:157], v138 offset:2048
	ds_read_b128 v[158:161], v138 offset:3072
	ds_read_b128 v[162:165], v139
	ds_read_b128 v[166:169], v139 offset:1024
	ds_read_b128 v[170:173], v139 offset:2048
	ds_read_b128 v[174:177], v139 offset:3072
	s_add_i32 s22, s75, 0xffe80080
	s_cmp_eq_u32 s62, s77
	s_cselect_b32 s78, s73, s22
	s_cselect_b32 s80, s74, s76
	s_or_b32 s79, s78, 0x80
	s_add_i32 s22, s75, 0xfff80000
	s_mov_b32 m0, s63
	ds_read_b128 v[178:181], v140
	ds_read_b128 v[182:185], v140 offset:1024
	ds_read_b128 v[186:189], v140 offset:2048
	ds_read_b128 v[190:193], v140 offset:3072
	ds_read_b128 v[194:197], v140 offset:4096
	ds_read_b128 v[198:201], v140 offset:5120
	ds_read_b128 v[202:205], v140 offset:6144
	ds_read_b128 v[206:209], v140 offset:7168
	buffer_load_dwordx4 v136, s[16:19], s22 offen lds
	s_mov_b32 m0, s64
	s_nop 0
	buffer_load_dwordx4 v136, s[16:19], s75 offen lds
	s_waitcnt vmcnt(8)
	s_waitcnt lgkmcnt(0)
	s_setprio 1
	v_mfma_f32_16x16x32_bf16 v[118:121], v[146:149], v[178:181], v[118:121]
	s_barrier
	v_mfma_f32_16x16x32_bf16 v[118:121], v[150:153], v[182:185], v[118:121]
	v_mfma_f32_16x16x32_bf16 v[114:117], v[158:161], v[182:185], v[114:117]
	v_mfma_f32_16x16x32_bf16 v[114:117], v[154:157], v[178:181], v[114:117]
	v_mfma_f32_16x16x32_bf16 v[126:129], v[162:165], v[178:181], v[126:129]
	v_mfma_f32_16x16x32_bf16 v[126:129], v[166:169], v[182:185], v[126:129]
	v_mfma_f32_16x16x32_bf16 v[122:125], v[174:177], v[182:185], v[122:125]
	v_mfma_f32_16x16x32_bf16 v[122:125], v[170:173], v[178:181], v[122:125]
	v_mfma_f32_16x16x32_bf16 v[98:101], v[170:173], v[186:189], v[98:101]
	v_mfma_f32_16x16x32_bf16 v[98:101], v[174:177], v[190:193], v[98:101]
	v_mfma_f32_16x16x32_bf16 v[106:109], v[166:169], v[190:193], v[106:109]
	v_mfma_f32_16x16x32_bf16 v[106:109], v[162:165], v[186:189], v[106:109]
	v_mfma_f32_16x16x32_bf16 v[102:105], v[154:157], v[186:189], v[102:105]
	v_mfma_f32_16x16x32_bf16 v[102:105], v[158:161], v[190:193], v[102:105]
	v_mfma_f32_16x16x32_bf16 v[110:113], v[150:153], v[190:193], v[110:113]
	v_mfma_f32_16x16x32_bf16 v[110:113], v[146:149], v[186:189], v[110:113]
	v_mfma_f32_16x16x32_bf16 v[94:97], v[146:149], v[194:197], v[94:97]
	v_mfma_f32_16x16x32_bf16 v[94:97], v[150:153], v[198:201], v[94:97]
	v_mfma_f32_16x16x32_bf16 v[86:89], v[158:161], v[198:201], v[86:89]
	v_mfma_f32_16x16x32_bf16 v[86:89], v[154:157], v[194:197], v[86:89]
	v_mfma_f32_16x16x32_bf16 v[90:93], v[162:165], v[194:197], v[90:93]
	v_mfma_f32_16x16x32_bf16 v[90:93], v[166:169], v[198:201], v[90:93]
	v_mfma_f32_16x16x32_bf16 v[82:85], v[174:177], v[198:201], v[82:85]
	v_mfma_f32_16x16x32_bf16 v[82:85], v[170:173], v[194:197], v[82:85]
	v_mfma_f32_16x16x32_bf16 v[70:73], v[170:173], v[202:205], v[70:73]
	v_mfma_f32_16x16x32_bf16 v[70:73], v[174:177], v[206:209], v[70:73]
	v_mfma_f32_16x16x32_bf16 v[74:77], v[166:169], v[206:209], v[74:77]
	v_mfma_f32_16x16x32_bf16 v[74:77], v[162:165], v[202:205], v[74:77]
	v_mfma_f32_16x16x32_bf16 v[66:69], v[154:157], v[202:205], v[66:69]
	v_mfma_f32_16x16x32_bf16 v[66:69], v[158:161], v[206:209], v[66:69]
	v_mfma_f32_16x16x32_bf16 v[78:81], v[150:153], v[206:209], v[78:81]
	v_mfma_f32_16x16x32_bf16 v[78:81], v[146:149], v[202:205], v[78:81]
	s_setprio 0
	s_barrier
	s_mov_b32 m0, s31
	s_mov_b32 s22, s18
	s_mov_b32 s23, s19
	ds_read_b128 v[178:181], v140 offset:16384
	ds_read_b128 v[182:185], v140 offset:17408
	ds_read_b128 v[186:189], v140 offset:18432
	ds_read_b128 v[190:193], v140 offset:19456
	ds_read_b128 v[194:197], v140 offset:20480
	ds_read_b128 v[198:201], v140 offset:21504
	ds_read_b128 v[202:205], v140 offset:22528
	ds_read_b128 v[206:209], v140 offset:23552
	buffer_load_dwordx4 v137, s[20:23], s80 offen lds
	s_add_i32 s81, s80, 0x80000
	s_mov_b32 m0, s48
	s_nop 0
	buffer_load_dwordx4 v137, s[20:23], s81 offen lds
	s_add_i32 s81, s80, 0x100000
	s_mov_b32 m0, s49
	s_nop 0
	buffer_load_dwordx4 v137, s[20:23], s81 offen lds
	s_add_i32 s81, s80, 0x180000
	s_mov_b32 m0, s50
	s_nop 0
	buffer_load_dwordx4 v137, s[20:23], s81 offen lds
	s_mov_b32 m0, s30
	s_add_i32 s81, s78, 0x80000
	buffer_load_dwordx4 v136, s[16:19], s78 offen lds
	s_mov_b32 m0, s51
	s_nop 0
	buffer_load_dwordx4 v136, s[16:19], s81 offen lds
	s_waitcnt vmcnt(8)
	s_waitcnt lgkmcnt(0)
	s_setprio 1
	v_mfma_f32_16x16x32_bf16 v[62:65], v[146:149], v[178:181], v[62:65]
	s_barrier
	v_mfma_f32_16x16x32_bf16 v[62:65], v[150:153], v[182:185], v[62:65]
	v_mfma_f32_16x16x32_bf16 v[54:57], v[158:161], v[182:185], v[54:57]
	v_mfma_f32_16x16x32_bf16 v[54:57], v[154:157], v[178:181], v[54:57]
	v_mfma_f32_16x16x32_bf16 v[58:61], v[162:165], v[178:181], v[58:61]
	v_mfma_f32_16x16x32_bf16 v[58:61], v[166:169], v[182:185], v[58:61]
	v_mfma_f32_16x16x32_bf16 v[50:53], v[174:177], v[182:185], v[50:53]
	v_mfma_f32_16x16x32_bf16 v[50:53], v[170:173], v[178:181], v[50:53]
	v_mfma_f32_16x16x32_bf16 v[34:37], v[170:173], v[186:189], v[34:37]
	v_mfma_f32_16x16x32_bf16 v[34:37], v[174:177], v[190:193], v[34:37]
	v_mfma_f32_16x16x32_bf16 v[42:45], v[166:169], v[190:193], v[42:45]
	v_mfma_f32_16x16x32_bf16 v[42:45], v[162:165], v[186:189], v[42:45]
	v_mfma_f32_16x16x32_bf16 v[38:41], v[154:157], v[186:189], v[38:41]
	v_mfma_f32_16x16x32_bf16 v[38:41], v[158:161], v[190:193], v[38:41]
	v_mfma_f32_16x16x32_bf16 v[46:49], v[150:153], v[190:193], v[46:49]
	v_mfma_f32_16x16x32_bf16 v[46:49], v[146:149], v[186:189], v[46:49]
	v_mfma_f32_16x16x32_bf16 v[30:33], v[146:149], v[194:197], v[30:33]
	v_mfma_f32_16x16x32_bf16 v[30:33], v[150:153], v[198:201], v[30:33]
	v_mfma_f32_16x16x32_bf16 v[22:25], v[158:161], v[198:201], v[22:25]
	v_mfma_f32_16x16x32_bf16 v[22:25], v[154:157], v[194:197], v[22:25]
	v_mfma_f32_16x16x32_bf16 v[26:29], v[162:165], v[194:197], v[26:29]
	v_mfma_f32_16x16x32_bf16 v[26:29], v[166:169], v[198:201], v[26:29]
	v_mfma_f32_16x16x32_bf16 v[18:21], v[174:177], v[198:201], v[18:21]
	v_mfma_f32_16x16x32_bf16 v[18:21], v[170:173], v[194:197], v[18:21]
	v_mfma_f32_16x16x32_bf16 v[2:5], v[170:173], v[202:205], v[2:5]
	v_mfma_f32_16x16x32_bf16 v[2:5], v[174:177], v[206:209], v[2:5]
	v_mfma_f32_16x16x32_bf16 v[10:13], v[166:169], v[206:209], v[10:13]
	v_mfma_f32_16x16x32_bf16 v[10:13], v[162:165], v[202:205], v[10:13]
	v_mfma_f32_16x16x32_bf16 v[6:9], v[154:157], v[202:205], v[6:9]
	v_mfma_f32_16x16x32_bf16 v[6:9], v[158:161], v[206:209], v[6:9]
	v_mfma_f32_16x16x32_bf16 v[14:17], v[150:153], v[206:209], v[14:17]
	v_mfma_f32_16x16x32_bf16 v[14:17], v[146:149], v[202:205], v[14:17]
	s_setprio 0
	s_barrier
	ds_read_b128 v[146:149], v141
	ds_read_b128 v[150:153], v141 offset:1024
	ds_read_b128 v[154:157], v141 offset:2048
	ds_read_b128 v[158:161], v141 offset:3072
	ds_read_b128 v[162:165], v142
	ds_read_b128 v[166:169], v142 offset:1024
	ds_read_b128 v[170:173], v142 offset:2048
	ds_read_b128 v[174:177], v142 offset:3072
	s_mov_b32 m0, s52
	s_add_i32 s81, s78, 0x100000
	ds_read_b128 v[178:181], v140 offset:32768
	ds_read_b128 v[182:185], v140 offset:33792
	ds_read_b128 v[186:189], v140 offset:34816
	ds_read_b128 v[190:193], v140 offset:35840
	ds_read_b128 v[194:197], v140 offset:36864
	ds_read_b128 v[198:201], v140 offset:37888
	ds_read_b128 v[202:205], v140 offset:38912
	ds_read_b128 v[206:209], v140 offset:39936
	buffer_load_dwordx4 v136, s[16:19], s81 offen lds
	s_add_i32 s81, s78, 0x180000
	s_mov_b32 m0, s53
	s_nop 0
	buffer_load_dwordx4 v136, s[16:19], s81 offen lds
	s_waitcnt vmcnt(8)
	s_waitcnt lgkmcnt(0)
	s_setprio 1
	v_mfma_f32_16x16x32_bf16 v[118:121], v[146:149], v[178:181], v[118:121]
	s_barrier
	v_mfma_f32_16x16x32_bf16 v[118:121], v[150:153], v[182:185], v[118:121]
	v_mfma_f32_16x16x32_bf16 v[114:117], v[158:161], v[182:185], v[114:117]
	v_mfma_f32_16x16x32_bf16 v[114:117], v[154:157], v[178:181], v[114:117]
	v_mfma_f32_16x16x32_bf16 v[126:129], v[162:165], v[178:181], v[126:129]
	v_mfma_f32_16x16x32_bf16 v[126:129], v[166:169], v[182:185], v[126:129]
	v_mfma_f32_16x16x32_bf16 v[122:125], v[174:177], v[182:185], v[122:125]
	v_mfma_f32_16x16x32_bf16 v[122:125], v[170:173], v[178:181], v[122:125]
	v_mfma_f32_16x16x32_bf16 v[98:101], v[170:173], v[186:189], v[98:101]
	v_mfma_f32_16x16x32_bf16 v[98:101], v[174:177], v[190:193], v[98:101]
	v_mfma_f32_16x16x32_bf16 v[106:109], v[166:169], v[190:193], v[106:109]
	v_mfma_f32_16x16x32_bf16 v[106:109], v[162:165], v[186:189], v[106:109]
	v_mfma_f32_16x16x32_bf16 v[102:105], v[154:157], v[186:189], v[102:105]
	v_mfma_f32_16x16x32_bf16 v[102:105], v[158:161], v[190:193], v[102:105]
	v_mfma_f32_16x16x32_bf16 v[110:113], v[150:153], v[190:193], v[110:113]
	v_mfma_f32_16x16x32_bf16 v[110:113], v[146:149], v[186:189], v[110:113]
	v_mfma_f32_16x16x32_bf16 v[94:97], v[146:149], v[194:197], v[94:97]
	v_mfma_f32_16x16x32_bf16 v[94:97], v[150:153], v[198:201], v[94:97]
	v_mfma_f32_16x16x32_bf16 v[86:89], v[158:161], v[198:201], v[86:89]
	v_mfma_f32_16x16x32_bf16 v[86:89], v[154:157], v[194:197], v[86:89]
	v_mfma_f32_16x16x32_bf16 v[90:93], v[162:165], v[194:197], v[90:93]
	v_mfma_f32_16x16x32_bf16 v[90:93], v[166:169], v[198:201], v[90:93]
	v_mfma_f32_16x16x32_bf16 v[82:85], v[174:177], v[198:201], v[82:85]
	v_mfma_f32_16x16x32_bf16 v[82:85], v[170:173], v[194:197], v[82:85]
	v_mfma_f32_16x16x32_bf16 v[70:73], v[170:173], v[202:205], v[70:73]
	v_mfma_f32_16x16x32_bf16 v[70:73], v[174:177], v[206:209], v[70:73]
	v_mfma_f32_16x16x32_bf16 v[74:77], v[166:169], v[206:209], v[74:77]
	v_mfma_f32_16x16x32_bf16 v[74:77], v[162:165], v[202:205], v[74:77]
	v_mfma_f32_16x16x32_bf16 v[66:69], v[154:157], v[202:205], v[66:69]
	v_mfma_f32_16x16x32_bf16 v[66:69], v[158:161], v[206:209], v[66:69]
	v_mfma_f32_16x16x32_bf16 v[78:81], v[150:153], v[206:209], v[78:81]
	v_mfma_f32_16x16x32_bf16 v[78:81], v[146:149], v[202:205], v[78:81]
	s_setprio 0
	s_barrier
	s_mov_b32 m0, s54
	s_or_b32 s81, s80, 0x80
	ds_read_b128 v[178:181], v140 offset:49152
	ds_read_b128 v[182:185], v140 offset:50176
	ds_read_b128 v[186:189], v140 offset:51200
	ds_read_b128 v[190:193], v140 offset:52224
	ds_read_b128 v[194:197], v140 offset:53248
	ds_read_b128 v[198:201], v140 offset:54272
	ds_read_b128 v[202:205], v140 offset:55296
	ds_read_b128 v[206:209], v140 offset:56320
	buffer_load_dwordx4 v137, s[20:23], s81 offen lds
	s_add_i32 s81, s80, 0x80080
	s_mov_b32 m0, s55
	s_add_i32 s78, s78, 0x80080
	buffer_load_dwordx4 v137, s[20:23], s81 offen lds
	s_add_i32 s81, s80, 0x100080
	s_mov_b32 m0, s58
	s_add_i32 s80, s80, 0x180080
	buffer_load_dwordx4 v137, s[20:23], s81 offen lds
	s_mov_b32 m0, s59
	s_nop 0
	buffer_load_dwordx4 v137, s[20:23], s80 offen lds
	s_mov_b32 m0, s56
	s_nop 0
	buffer_load_dwordx4 v136, s[16:19], s79 offen lds
	s_mov_b32 m0, s57
	s_nop 0
	buffer_load_dwordx4 v136, s[16:19], s78 offen lds
	s_waitcnt vmcnt(8)
	s_waitcnt lgkmcnt(0)
	s_setprio 1
	v_mfma_f32_16x16x32_bf16 v[62:65], v[146:149], v[178:181], v[62:65]
	s_barrier
	v_mfma_f32_16x16x32_bf16 v[62:65], v[150:153], v[182:185], v[62:65]
	v_mfma_f32_16x16x32_bf16 v[54:57], v[158:161], v[182:185], v[54:57]
	v_mfma_f32_16x16x32_bf16 v[54:57], v[154:157], v[178:181], v[54:57]
	v_mfma_f32_16x16x32_bf16 v[58:61], v[162:165], v[178:181], v[58:61]
	v_mfma_f32_16x16x32_bf16 v[58:61], v[166:169], v[182:185], v[58:61]
	v_mfma_f32_16x16x32_bf16 v[50:53], v[174:177], v[182:185], v[50:53]
	v_mfma_f32_16x16x32_bf16 v[50:53], v[170:173], v[178:181], v[50:53]
	v_mfma_f32_16x16x32_bf16 v[34:37], v[170:173], v[186:189], v[34:37]
	v_mfma_f32_16x16x32_bf16 v[34:37], v[174:177], v[190:193], v[34:37]
	v_mfma_f32_16x16x32_bf16 v[42:45], v[166:169], v[190:193], v[42:45]
	v_mfma_f32_16x16x32_bf16 v[42:45], v[162:165], v[186:189], v[42:45]
	v_mfma_f32_16x16x32_bf16 v[38:41], v[154:157], v[186:189], v[38:41]
	v_mfma_f32_16x16x32_bf16 v[38:41], v[158:161], v[190:193], v[38:41]
	v_mfma_f32_16x16x32_bf16 v[46:49], v[150:153], v[190:193], v[46:49]
	v_mfma_f32_16x16x32_bf16 v[46:49], v[146:149], v[186:189], v[46:49]
	v_mfma_f32_16x16x32_bf16 v[30:33], v[146:149], v[194:197], v[30:33]
	v_mfma_f32_16x16x32_bf16 v[30:33], v[150:153], v[198:201], v[30:33]
	v_mfma_f32_16x16x32_bf16 v[22:25], v[158:161], v[198:201], v[22:25]
	v_mfma_f32_16x16x32_bf16 v[22:25], v[154:157], v[194:197], v[22:25]
	v_mfma_f32_16x16x32_bf16 v[26:29], v[162:165], v[194:197], v[26:29]
	v_mfma_f32_16x16x32_bf16 v[26:29], v[166:169], v[198:201], v[26:29]
	v_mfma_f32_16x16x32_bf16 v[18:21], v[174:177], v[198:201], v[18:21]
	v_mfma_f32_16x16x32_bf16 v[18:21], v[170:173], v[194:197], v[18:21]
	v_mfma_f32_16x16x32_bf16 v[2:5], v[170:173], v[202:205], v[2:5]
	v_mfma_f32_16x16x32_bf16 v[2:5], v[174:177], v[206:209], v[2:5]
	v_mfma_f32_16x16x32_bf16 v[10:13], v[166:169], v[206:209], v[10:13]
	v_mfma_f32_16x16x32_bf16 v[10:13], v[162:165], v[202:205], v[10:13]
	v_mfma_f32_16x16x32_bf16 v[6:9], v[154:157], v[202:205], v[6:9]
	v_mfma_f32_16x16x32_bf16 v[6:9], v[158:161], v[206:209], v[6:9]
	v_mfma_f32_16x16x32_bf16 v[14:17], v[150:153], v[206:209], v[14:17]
	v_mfma_f32_16x16x32_bf16 v[14:17], v[146:149], v[202:205], v[14:17]
	s_setprio 0
	s_barrier
	s_add_i32 s77, s77, 2
	s_addk_i32 s75, 0x100
	s_addk_i32 s76, 0x100
	s_cmp_ge_i32 s77, s13
	s_cbranch_scc0 .LBB0_1402
	s_and_b64 vcc, exec, s[46:47]
	s_cbranch_vccz .LBB0_1405

.LBB0_1519:
	ds_read_b128 v[134:137], v208
	ds_read_b128 v[138:141], v208 offset:1024
	ds_read_b128 v[142:145], v208 offset:2048
	ds_read_b128 v[146:149], v208 offset:3072
	ds_read_b128 v[150:153], v209
	ds_read_b128 v[154:157], v209 offset:1024
	ds_read_b128 v[158:161], v209 offset:2048
	ds_read_b128 v[162:165], v209 offset:3072
	s_add_i32 s18, s80, 0xffbf8080
	s_cmp_eq_u32 s65, s82
	s_cselect_b32 s83, s6, s18
	s_cselect_b32 s85, s7, s81
	s_or_b32 s84, s83, 0x80
	s_add_i32 s18, s80, 0xffea8000
	s_mov_b32 m0, s66
	ds_read_b128 v[166:169], v210
	ds_read_b128 v[170:173], v210 offset:1024
	ds_read_b128 v[174:177], v210 offset:2048
	ds_read_b128 v[178:181], v210 offset:3072
	ds_read_b128 v[182:185], v210 offset:4096
	ds_read_b128 v[186:189], v210 offset:5120
	ds_read_b128 v[190:193], v210 offset:6144
	ds_read_b128 v[194:197], v210 offset:7168
	buffer_load_dwordx4 v206, s[12:15], s18 offen lds
	s_mov_b32 m0, s69
	s_nop 0
	buffer_load_dwordx4 v206, s[12:15], s80 offen lds
	s_waitcnt vmcnt(8)
	s_waitcnt lgkmcnt(0)
	s_setprio 1
	v_mfma_f32_16x16x32_bf16 v[126:129], v[134:137], v[166:169], v[126:129]
	s_barrier
	v_mfma_f32_16x16x32_bf16 v[126:129], v[138:141], v[170:173], v[126:129]
	v_mfma_f32_16x16x32_bf16 v[122:125], v[146:149], v[170:173], v[122:125]
	v_mfma_f32_16x16x32_bf16 v[122:125], v[142:145], v[166:169], v[122:125]
	v_mfma_f32_16x16x32_bf16 v[110:113], v[150:153], v[166:169], v[110:113]
	v_mfma_f32_16x16x32_bf16 v[110:113], v[154:157], v[170:173], v[110:113]
	v_mfma_f32_16x16x32_bf16 v[102:105], v[162:165], v[170:173], v[102:105]
	v_mfma_f32_16x16x32_bf16 v[102:105], v[158:161], v[166:169], v[102:105]
	v_mfma_f32_16x16x32_bf16 v[86:89], v[158:161], v[174:177], v[86:89]
	v_mfma_f32_16x16x32_bf16 v[86:89], v[162:165], v[178:181], v[86:89]
	v_mfma_f32_16x16x32_bf16 v[94:97], v[154:157], v[178:181], v[94:97]
	v_mfma_f32_16x16x32_bf16 v[94:97], v[150:153], v[174:177], v[94:97]
	v_mfma_f32_16x16x32_bf16 v[114:117], v[142:145], v[174:177], v[114:117]
	v_mfma_f32_16x16x32_bf16 v[114:117], v[146:149], v[178:181], v[114:117]
	v_mfma_f32_16x16x32_bf16 v[118:121], v[138:141], v[178:181], v[118:121]
	v_mfma_f32_16x16x32_bf16 v[118:121], v[134:137], v[174:177], v[118:121]
	v_mfma_f32_16x16x32_bf16 v[106:109], v[134:137], v[182:185], v[106:109]
	v_mfma_f32_16x16x32_bf16 v[106:109], v[138:141], v[186:189], v[106:109]
	v_mfma_f32_16x16x32_bf16 v[98:101], v[146:149], v[186:189], v[98:101]
	v_mfma_f32_16x16x32_bf16 v[98:101], v[142:145], v[182:185], v[98:101]
	v_mfma_f32_16x16x32_bf16 v[78:81], v[150:153], v[182:185], v[78:81]
	v_mfma_f32_16x16x32_bf16 v[78:81], v[154:157], v[186:189], v[78:81]
	v_mfma_f32_16x16x32_bf16 v[74:77], v[162:165], v[186:189], v[74:77]
	v_mfma_f32_16x16x32_bf16 v[74:77], v[158:161], v[182:185], v[74:77]
	v_mfma_f32_16x16x32_bf16 v[66:69], v[158:161], v[190:193], v[66:69]
	v_mfma_f32_16x16x32_bf16 v[66:69], v[162:165], v[194:197], v[66:69]
	v_mfma_f32_16x16x32_bf16 v[70:73], v[154:157], v[194:197], v[70:73]
	v_mfma_f32_16x16x32_bf16 v[70:73], v[150:153], v[190:193], v[70:73]
	v_mfma_f32_16x16x32_bf16 v[82:85], v[142:145], v[190:193], v[82:85]
	v_mfma_f32_16x16x32_bf16 v[82:85], v[146:149], v[194:197], v[82:85]
	v_mfma_f32_16x16x32_bf16 v[90:93], v[138:141], v[194:197], v[90:93]
	v_mfma_f32_16x16x32_bf16 v[90:93], v[134:137], v[190:193], v[90:93]
	s_setprio 0
	s_barrier
	s_mov_b32 m0, s27
	s_mov_b32 s18, s14
	s_mov_b32 s19, s15
	ds_read_b128 v[166:169], v210 offset:16384
	ds_read_b128 v[170:173], v210 offset:17408
	ds_read_b128 v[174:177], v210 offset:18432
	ds_read_b128 v[178:181], v210 offset:19456
	ds_read_b128 v[182:185], v210 offset:20480
	ds_read_b128 v[186:189], v210 offset:21504
	ds_read_b128 v[190:193], v210 offset:22528
	ds_read_b128 v[194:197], v210 offset:23552
	buffer_load_dwordx4 v207, s[16:19], s85 offen lds
	s_add_i32 s86, s85, 0x158000
	s_mov_b32 m0, s30
	s_nop 0
	buffer_load_dwordx4 v207, s[16:19], s86 offen lds
	s_add_i32 s86, s85, 0x2b0000
	s_mov_b32 m0, s31
	s_nop 0
	buffer_load_dwordx4 v207, s[16:19], s86 offen lds
	s_add_i32 s86, s85, 0x408000
	s_mov_b32 m0, s50
	s_nop 0
	buffer_load_dwordx4 v207, s[16:19], s86 offen lds
	s_mov_b32 m0, s25
	s_add_i32 s86, s83, 0x158000
	buffer_load_dwordx4 v206, s[12:15], s83 offen lds
	s_mov_b32 m0, s51
	s_nop 0
	buffer_load_dwordx4 v206, s[12:15], s86 offen lds
	s_waitcnt vmcnt(8)
	s_waitcnt lgkmcnt(0)
	s_setprio 1
	v_mfma_f32_16x16x32_bf16 v[62:65], v[134:137], v[166:169], v[62:65]
	s_barrier
	v_mfma_f32_16x16x32_bf16 v[62:65], v[138:141], v[170:173], v[62:65]
	v_mfma_f32_16x16x32_bf16 v[58:61], v[146:149], v[170:173], v[58:61]
	v_mfma_f32_16x16x32_bf16 v[58:61], v[142:145], v[166:169], v[58:61]
	v_mfma_f32_16x16x32_bf16 v[46:49], v[150:153], v[166:169], v[46:49]
	v_mfma_f32_16x16x32_bf16 v[46:49], v[154:157], v[170:173], v[46:49]
	v_mfma_f32_16x16x32_bf16 v[38:41], v[162:165], v[170:173], v[38:41]
	v_mfma_f32_16x16x32_bf16 v[38:41], v[158:161], v[166:169], v[38:41]
	v_mfma_f32_16x16x32_bf16 v[22:25], v[158:161], v[174:177], v[22:25]
	v_mfma_f32_16x16x32_bf16 v[22:25], v[162:165], v[178:181], v[22:25]
	v_mfma_f32_16x16x32_bf16 v[30:33], v[154:157], v[178:181], v[30:33]
	v_mfma_f32_16x16x32_bf16 v[30:33], v[150:153], v[174:177], v[30:33]
	v_mfma_f32_16x16x32_bf16 v[50:53], v[142:145], v[174:177], v[50:53]
	v_mfma_f32_16x16x32_bf16 v[50:53], v[146:149], v[178:181], v[50:53]
	v_mfma_f32_16x16x32_bf16 v[54:57], v[138:141], v[178:181], v[54:57]
	v_mfma_f32_16x16x32_bf16 v[54:57], v[134:137], v[174:177], v[54:57]
	v_mfma_f32_16x16x32_bf16 v[42:45], v[134:137], v[182:185], v[42:45]
	v_mfma_f32_16x16x32_bf16 v[42:45], v[138:141], v[186:189], v[42:45]
	v_mfma_f32_16x16x32_bf16 v[34:37], v[146:149], v[186:189], v[34:37]
	v_mfma_f32_16x16x32_bf16 v[34:37], v[142:145], v[182:185], v[34:37]
	v_mfma_f32_16x16x32_bf16 v[14:17], v[150:153], v[182:185], v[14:17]
	v_mfma_f32_16x16x32_bf16 v[14:17], v[154:157], v[186:189], v[14:17]
	v_mfma_f32_16x16x32_bf16 v[10:13], v[162:165], v[186:189], v[10:13]
	v_mfma_f32_16x16x32_bf16 v[10:13], v[158:161], v[182:185], v[10:13]
	v_mfma_f32_16x16x32_bf16 v[2:5], v[158:161], v[190:193], v[2:5]
	v_mfma_f32_16x16x32_bf16 v[2:5], v[162:165], v[194:197], v[2:5]
	v_mfma_f32_16x16x32_bf16 v[6:9], v[154:157], v[194:197], v[6:9]
	v_mfma_f32_16x16x32_bf16 v[6:9], v[150:153], v[190:193], v[6:9]
	v_mfma_f32_16x16x32_bf16 v[18:21], v[142:145], v[190:193], v[18:21]
	v_mfma_f32_16x16x32_bf16 v[18:21], v[146:149], v[194:197], v[18:21]
	v_mfma_f32_16x16x32_bf16 v[26:29], v[138:141], v[194:197], v[26:29]
	v_mfma_f32_16x16x32_bf16 v[26:29], v[134:137], v[190:193], v[26:29]
	s_setprio 0
	s_barrier
	ds_read_b128 v[134:137], v211
	ds_read_b128 v[138:141], v211 offset:1024
	ds_read_b128 v[142:145], v211 offset:2048
	ds_read_b128 v[146:149], v211 offset:3072
	ds_read_b128 v[150:153], v212
	ds_read_b128 v[154:157], v212 offset:1024
	ds_read_b128 v[158:161], v212 offset:2048
	ds_read_b128 v[162:165], v212 offset:3072
	s_mov_b32 m0, s52
	s_add_i32 s86, s83, 0x2b0000
	ds_read_b128 v[166:169], v210 offset:32768
	ds_read_b128 v[170:173], v210 offset:33792
	ds_read_b128 v[174:177], v210 offset:34816
	ds_read_b128 v[178:181], v210 offset:35840
	ds_read_b128 v[182:185], v210 offset:36864
	ds_read_b128 v[186:189], v210 offset:37888
	ds_read_b128 v[190:193], v210 offset:38912
	ds_read_b128 v[194:197], v210 offset:39936
	buffer_load_dwordx4 v206, s[12:15], s86 offen lds
	s_add_i32 s86, s83, 0x408000
	s_mov_b32 m0, s53
	s_nop 0
	buffer_load_dwordx4 v206, s[12:15], s86 offen lds
	s_waitcnt vmcnt(8)
	s_waitcnt lgkmcnt(0)
	s_setprio 1
	v_mfma_f32_16x16x32_bf16 v[126:129], v[134:137], v[166:169], v[126:129]
	s_barrier
	v_mfma_f32_16x16x32_bf16 v[126:129], v[138:141], v[170:173], v[126:129]
	v_mfma_f32_16x16x32_bf16 v[122:125], v[146:149], v[170:173], v[122:125]
	v_mfma_f32_16x16x32_bf16 v[122:125], v[142:145], v[166:169], v[122:125]
	v_mfma_f32_16x16x32_bf16 v[110:113], v[150:153], v[166:169], v[110:113]
	v_mfma_f32_16x16x32_bf16 v[110:113], v[154:157], v[170:173], v[110:113]
	v_mfma_f32_16x16x32_bf16 v[102:105], v[162:165], v[170:173], v[102:105]
	v_mfma_f32_16x16x32_bf16 v[102:105], v[158:161], v[166:169], v[102:105]
	v_mfma_f32_16x16x32_bf16 v[86:89], v[158:161], v[174:177], v[86:89]
	v_mfma_f32_16x16x32_bf16 v[86:89], v[162:165], v[178:181], v[86:89]
	v_mfma_f32_16x16x32_bf16 v[94:97], v[154:157], v[178:181], v[94:97]
	v_mfma_f32_16x16x32_bf16 v[94:97], v[150:153], v[174:177], v[94:97]
	v_mfma_f32_16x16x32_bf16 v[114:117], v[142:145], v[174:177], v[114:117]
	v_mfma_f32_16x16x32_bf16 v[114:117], v[146:149], v[178:181], v[114:117]
	v_mfma_f32_16x16x32_bf16 v[118:121], v[138:141], v[178:181], v[118:121]
	v_mfma_f32_16x16x32_bf16 v[118:121], v[134:137], v[174:177], v[118:121]
	v_mfma_f32_16x16x32_bf16 v[106:109], v[134:137], v[182:185], v[106:109]
	v_mfma_f32_16x16x32_bf16 v[106:109], v[138:141], v[186:189], v[106:109]
	v_mfma_f32_16x16x32_bf16 v[98:101], v[146:149], v[186:189], v[98:101]
	v_mfma_f32_16x16x32_bf16 v[98:101], v[142:145], v[182:185], v[98:101]
	v_mfma_f32_16x16x32_bf16 v[78:81], v[150:153], v[182:185], v[78:81]
	v_mfma_f32_16x16x32_bf16 v[78:81], v[154:157], v[186:189], v[78:81]
	v_mfma_f32_16x16x32_bf16 v[74:77], v[162:165], v[186:189], v[74:77]
	v_mfma_f32_16x16x32_bf16 v[74:77], v[158:161], v[182:185], v[74:77]
	v_mfma_f32_16x16x32_bf16 v[66:69], v[158:161], v[190:193], v[66:69]
	v_mfma_f32_16x16x32_bf16 v[66:69], v[162:165], v[194:197], v[66:69]
	v_mfma_f32_16x16x32_bf16 v[70:73], v[154:157], v[194:197], v[70:73]
	v_mfma_f32_16x16x32_bf16 v[70:73], v[150:153], v[190:193], v[70:73]
	v_mfma_f32_16x16x32_bf16 v[82:85], v[142:145], v[190:193], v[82:85]
	v_mfma_f32_16x16x32_bf16 v[82:85], v[146:149], v[194:197], v[82:85]
	v_mfma_f32_16x16x32_bf16 v[90:93], v[138:141], v[194:197], v[90:93]
	v_mfma_f32_16x16x32_bf16 v[90:93], v[134:137], v[190:193], v[90:93]
	s_setprio 0
	s_barrier
	s_mov_b32 m0, s57
	s_or_b32 s86, s85, 0x80
	ds_read_b128 v[166:169], v210 offset:49152
	ds_read_b128 v[170:173], v210 offset:50176
	ds_read_b128 v[174:177], v210 offset:51200
	ds_read_b128 v[178:181], v210 offset:52224
	ds_read_b128 v[182:185], v210 offset:53248
	ds_read_b128 v[186:189], v210 offset:54272
	ds_read_b128 v[190:193], v210 offset:55296
	ds_read_b128 v[194:197], v210 offset:56320
	buffer_load_dwordx4 v207, s[16:19], s86 offen lds
	s_add_i32 s86, s85, 0x158080
	s_mov_b32 m0, s58
	s_add_i32 s83, s83, 0x158080
	buffer_load_dwordx4 v207, s[16:19], s86 offen lds
	s_add_i32 s86, s85, 0x2b0080
	s_mov_b32 m0, s61
	s_add_i32 s85, s85, 0x408080
	buffer_load_dwordx4 v207, s[16:19], s86 offen lds
	s_mov_b32 m0, s62
	s_nop 0
	buffer_load_dwordx4 v207, s[16:19], s85 offen lds
	s_mov_b32 m0, s59
	s_nop 0
	buffer_load_dwordx4 v206, s[12:15], s84 offen lds
	s_mov_b32 m0, s60
	s_nop 0
	buffer_load_dwordx4 v206, s[12:15], s83 offen lds
	s_waitcnt vmcnt(8)
	s_waitcnt lgkmcnt(0)
	s_setprio 1
	v_mfma_f32_16x16x32_bf16 v[62:65], v[134:137], v[166:169], v[62:65]
	s_barrier
	v_mfma_f32_16x16x32_bf16 v[62:65], v[138:141], v[170:173], v[62:65]
	v_mfma_f32_16x16x32_bf16 v[58:61], v[146:149], v[170:173], v[58:61]
	v_mfma_f32_16x16x32_bf16 v[58:61], v[142:145], v[166:169], v[58:61]
	v_mfma_f32_16x16x32_bf16 v[46:49], v[150:153], v[166:169], v[46:49]
	v_mfma_f32_16x16x32_bf16 v[46:49], v[154:157], v[170:173], v[46:49]
	v_mfma_f32_16x16x32_bf16 v[38:41], v[162:165], v[170:173], v[38:41]
	v_mfma_f32_16x16x32_bf16 v[38:41], v[158:161], v[166:169], v[38:41]
	v_mfma_f32_16x16x32_bf16 v[22:25], v[158:161], v[174:177], v[22:25]
	v_mfma_f32_16x16x32_bf16 v[22:25], v[162:165], v[178:181], v[22:25]
	v_mfma_f32_16x16x32_bf16 v[30:33], v[154:157], v[178:181], v[30:33]
	v_mfma_f32_16x16x32_bf16 v[30:33], v[150:153], v[174:177], v[30:33]
	v_mfma_f32_16x16x32_bf16 v[50:53], v[142:145], v[174:177], v[50:53]
	v_mfma_f32_16x16x32_bf16 v[50:53], v[146:149], v[178:181], v[50:53]
	v_mfma_f32_16x16x32_bf16 v[54:57], v[138:141], v[178:181], v[54:57]
	v_mfma_f32_16x16x32_bf16 v[54:57], v[134:137], v[174:177], v[54:57]
	v_mfma_f32_16x16x32_bf16 v[42:45], v[134:137], v[182:185], v[42:45]
	v_mfma_f32_16x16x32_bf16 v[42:45], v[138:141], v[186:189], v[42:45]
	v_mfma_f32_16x16x32_bf16 v[34:37], v[146:149], v[186:189], v[34:37]
	v_mfma_f32_16x16x32_bf16 v[34:37], v[142:145], v[182:185], v[34:37]
	v_mfma_f32_16x16x32_bf16 v[14:17], v[150:153], v[182:185], v[14:17]
	v_mfma_f32_16x16x32_bf16 v[14:17], v[154:157], v[186:189], v[14:17]
	v_mfma_f32_16x16x32_bf16 v[10:13], v[162:165], v[186:189], v[10:13]
	v_mfma_f32_16x16x32_bf16 v[10:13], v[158:161], v[182:185], v[10:13]
	v_mfma_f32_16x16x32_bf16 v[2:5], v[158:161], v[190:193], v[2:5]
	v_mfma_f32_16x16x32_bf16 v[2:5], v[162:165], v[194:197], v[2:5]
	v_mfma_f32_16x16x32_bf16 v[6:9], v[154:157], v[194:197], v[6:9]
	v_mfma_f32_16x16x32_bf16 v[6:9], v[150:153], v[190:193], v[6:9]
	v_mfma_f32_16x16x32_bf16 v[18:21], v[142:145], v[190:193], v[18:21]
	v_mfma_f32_16x16x32_bf16 v[18:21], v[146:149], v[194:197], v[18:21]
	v_mfma_f32_16x16x32_bf16 v[26:29], v[138:141], v[194:197], v[26:29]
	v_mfma_f32_16x16x32_bf16 v[26:29], v[134:137], v[190:193], v[26:29]
	s_setprio 0
	s_barrier
	s_add_i32 s82, s82, 2
	s_addk_i32 s80, 0x100
	s_addk_i32 s81, 0x100
	s_cmp_ge_i32 s82, s3
	s_cbranch_scc0 .LBB0_1519
	v_pk_mul_f32 v[182:183], v[128:129], 0.5 op_sel_hi:[1,0]
	v_pk_mul_f32 v[184:185], v[126:127], 0.5 op_sel_hi:[1,0]
	v_pk_mul_f32 v[186:187], v[124:125], 0.5 op_sel_hi:[1,0]
	v_pk_mul_f32 v[188:189], v[122:123], 0.5 op_sel_hi:[1,0]
	v_pk_mul_f32 v[196:197], v[112:113], 0.5 op_sel_hi:[1,0]
	v_pk_mul_f32 v[194:195], v[110:111], 0.5 op_sel_hi:[1,0]
	v_pk_mul_f32 v[192:193], v[104:105], 0.5 op_sel_hi:[1,0]
	v_pk_mul_f32 v[190:191], v[102:103], 0.5 op_sel_hi:[1,0]
	v_pk_mul_f32 v[180:181], v[120:121], 0.5 op_sel_hi:[1,0]
	v_pk_mul_f32 v[178:179], v[118:119], 0.5 op_sel_hi:[1,0]
	v_pk_mul_f32 v[176:177], v[116:117], 0.5 op_sel_hi:[1,0]
	v_pk_mul_f32 v[174:175], v[114:115], 0.5 op_sel_hi:[1,0]
	v_pk_mul_f32 v[170:171], v[96:97], 0.5 op_sel_hi:[1,0]
	v_pk_mul_f32 v[168:169], v[94:95], 0.5 op_sel_hi:[1,0]
	v_pk_mul_f32 v[166:167], v[88:89], 0.5 op_sel_hi:[1,0]
	v_pk_mul_f32 v[164:165], v[86:87], 0.5 op_sel_hi:[1,0]
	v_pk_mul_f32 v[162:163], v[108:109], 0.5 op_sel_hi:[1,0]
	v_pk_mul_f32 v[160:161], v[106:107], 0.5 op_sel_hi:[1,0]
	v_pk_mul_f32 v[158:159], v[100:101], 0.5 op_sel_hi:[1,0]
	v_pk_mul_f32 v[156:157], v[98:99], 0.5 op_sel_hi:[1,0]
	v_pk_mul_f32 v[154:155], v[80:81], 0.5 op_sel_hi:[1,0]
	v_pk_mul_f32 v[152:153], v[78:79], 0.5 op_sel_hi:[1,0]
	v_pk_mul_f32 v[150:151], v[76:77], 0.5 op_sel_hi:[1,0]
	v_pk_mul_f32 v[148:149], v[74:75], 0.5 op_sel_hi:[1,0]
	v_pk_mul_f32 v[144:145], v[92:93], 0.5 op_sel_hi:[1,0]
	v_pk_mul_f32 v[142:143], v[90:91], 0.5 op_sel_hi:[1,0]
	v_pk_mul_f32 v[140:141], v[84:85], 0.5 op_sel_hi:[1,0]
	v_pk_mul_f32 v[138:139], v[82:83], 0.5 op_sel_hi:[1,0]
	v_pk_mul_f32 v[136:137], v[72:73], 0.5 op_sel_hi:[1,0]
	v_pk_mul_f32 v[134:135], v[70:71], 0.5 op_sel_hi:[1,0]
	v_pk_mul_f32 v[128:129], v[68:69], 0.5 op_sel_hi:[1,0]
	v_pk_mul_f32 v[126:127], v[66:67], 0.5 op_sel_hi:[1,0]
	v_pk_mul_f32 v[122:123], v[64:65], 0.5 op_sel_hi:[1,0]
	v_pk_mul_f32 v[120:121], v[62:63], 0.5 op_sel_hi:[1,0]
	v_pk_mul_f32 v[118:119], v[60:61], 0.5 op_sel_hi:[1,0]
	v_pk_mul_f32 v[116:117], v[58:59], 0.5 op_sel_hi:[1,0]
	v_pk_mul_f32 v[112:113], v[48:49], 0.5 op_sel_hi:[1,0]
	v_pk_mul_f32 v[110:111], v[46:47], 0.5 op_sel_hi:[1,0]
	v_pk_mul_f32 v[108:109], v[40:41], 0.5 op_sel_hi:[1,0]
	v_pk_mul_f32 v[106:107], v[38:39], 0.5 op_sel_hi:[1,0]
	v_pk_mul_f32 v[104:105], v[56:57], 0.5 op_sel_hi:[1,0]
	v_pk_mul_f32 v[102:103], v[54:55], 0.5 op_sel_hi:[1,0]
	v_pk_mul_f32 v[100:101], v[52:53], 0.5 op_sel_hi:[1,0]
	v_pk_mul_f32 v[98:99], v[50:51], 0.5 op_sel_hi:[1,0]
	v_pk_mul_f32 v[96:97], v[32:33], 0.5 op_sel_hi:[1,0]
	v_pk_mul_f32 v[94:95], v[30:31], 0.5 op_sel_hi:[1,0]
	v_pk_mul_f32 v[92:93], v[24:25], 0.5 op_sel_hi:[1,0]
	v_pk_mul_f32 v[90:91], v[22:23], 0.5 op_sel_hi:[1,0]
	v_pk_mul_f32 v[88:89], v[44:45], 0.5 op_sel_hi:[1,0]
	v_pk_mul_f32 v[86:87], v[42:43], 0.5 op_sel_hi:[1,0]
	v_pk_mul_f32 v[84:85], v[36:37], 0.5 op_sel_hi:[1,0]
	v_pk_mul_f32 v[82:83], v[34:35], 0.5 op_sel_hi:[1,0]
	v_pk_mul_f32 v[80:81], v[16:17], 0.5 op_sel_hi:[1,0]
	v_pk_mul_f32 v[78:79], v[14:15], 0.5 op_sel_hi:[1,0]
	v_pk_mul_f32 v[76:77], v[12:13], 0.5 op_sel_hi:[1,0]
	v_pk_mul_f32 v[74:75], v[10:11], 0.5 op_sel_hi:[1,0]
	v_pk_mul_f32 v[72:73], v[28:29], 0.5 op_sel_hi:[1,0]
	v_pk_mul_f32 v[70:71], v[26:27], 0.5 op_sel_hi:[1,0]
	v_pk_mul_f32 v[68:69], v[20:21], 0.5 op_sel_hi:[1,0]
	v_pk_mul_f32 v[66:67], v[18:19], 0.5 op_sel_hi:[1,0]
	v_pk_mul_f32 v[64:65], v[8:9], 0.5 op_sel_hi:[1,0]
	v_pk_mul_f32 v[62:63], v[6:7], 0.5 op_sel_hi:[1,0]
	v_pk_mul_f32 v[60:61], v[4:5], 0.5 op_sel_hi:[1,0]
	v_pk_mul_f32 v[58:59], v[2:3], 0.5 op_sel_hi:[1,0]
	s_and_b64 vcc, exec, s[40:41]
	s_cbranch_vccz .LBB0_1522
